# 256x128 GEMM k-loops: row-group pointers folded into SALU adds, freed VGPRs double-buffer LDS fragments (reads of kk+1 under MFMAs of kk)
# speedup vs baseline: 1.0012x; 1.0012x over previous
.LBB0_944:
	s_add_i32 s3, s1, 1
	s_cmp_lt_u32 s1, 15
	s_cselect_b32 s1, s3, s1
	s_lshl_b32 s12, s1, 6
	s_lshl_b64 s[10:11], s[12:13], 1
	s_barrier
	s_waitcnt vmcnt(0)
	ds_write_b128 v204, v[174:177]
	ds_write_b128 v204, v[170:173] offset:4608
	ds_write_b128 v204, v[166:169] offset:9216
	ds_write_b128 v204, v[162:165] offset:13824
	ds_write_b128 v204, v[158:161] offset:18432
	ds_write_b128 v204, v[154:157] offset:23040
	ds_write_b128 v204, v[150:153] offset:27648
	ds_write_b128 v204, v[146:149] offset:32256
	ds_write_b128 v204, v[142:145] offset:36864
	ds_write_b128 v204, v[134:137] offset:41472
	ds_write_b128 v204, v[130:133] offset:46080
	ds_write_b128 v204, v[138:141] offset:50688
	v_lshl_add_u64 v[130:131], v[178:179], 0, s[10:11]
	s_add_u32 s100, s10, 0x10000
	s_addc_u32 s101, s11, 0
	v_lshl_add_u64 v[132:133], v[178:179], 0, s[100:101]
	s_add_u32 s100, s100, 0x10000
	s_addc_u32 s101, s101, 0
	v_lshl_add_u64 v[134:135], v[178:179], 0, s[100:101]
	s_add_u32 s100, s100, 0x10000
	s_addc_u32 s101, s101, 0
	v_lshl_add_u64 v[136:137], v[178:179], 0, s[100:101]
	s_add_u32 s100, s100, 0x10000
	s_addc_u32 s101, s101, 0
	v_lshl_add_u64 v[138:139], v[178:179], 0, s[100:101]
	s_add_u32 s100, s100, 0x10000
	s_addc_u32 s101, s101, 0
	v_lshl_add_u64 v[140:141], v[178:179], 0, s[100:101]
	s_add_u32 s100, s100, 0x10000
	s_addc_u32 s101, s101, 0
	v_lshl_add_u64 v[142:143], v[178:179], 0, s[100:101]
	s_add_u32 s100, s100, 0x10000
	s_addc_u32 s101, s101, 0
	v_lshl_add_u64 v[144:145], v[178:179], 0, s[100:101]
	s_waitcnt lgkmcnt(0)
	s_barrier
	v_lshl_add_u64 v[224:225], v[180:181], 0, s[10:11]
	s_add_u32 s100, s10, 0x10000
	s_addc_u32 s101, s11, 0
	v_lshl_add_u64 v[226:227], v[180:181], 0, s[100:101]
	s_add_u32 s100, s100, 0x10000
	s_addc_u32 s101, s101, 0
	v_lshl_add_u64 v[228:229], v[180:181], 0, s[100:101]
	s_add_u32 s100, s100, 0x10000
	s_addc_u32 s101, s101, 0
	v_lshl_add_u64 v[230:231], v[180:181], 0, s[100:101]
	global_load_dwordx4 v[174:177], v[130:131], off
	global_load_dwordx4 v[170:173], v[132:133], off
	global_load_dwordx4 v[166:169], v[134:135], off
	global_load_dwordx4 v[162:165], v[136:137], off
	global_load_dwordx4 v[158:161], v[138:139], off
	global_load_dwordx4 v[154:157], v[140:141], off
	global_load_dwordx4 v[150:153], v[142:143], off
	global_load_dwordx4 v[146:149], v[144:145], off
	global_load_dwordx4 v[142:145], v[224:225], off
	global_load_dwordx4 v[134:137], v[226:227], off
	global_load_dwordx4 v[130:133], v[228:229], off
	global_load_dwordx4 v[138:141], v[230:231], off
	ds_read_b128 v[224:227], v182
	ds_read_b128 v[228:231], v183 offset:36864
	ds_read_b128 v[232:235], v183 offset:41472
	ds_read_b128 v[184:187], v182 offset:4608
	ds_read_b128 v[236:239], v183 offset:46080
	ds_read_b128 v[240:243], v183 offset:50688
	s_waitcnt lgkmcnt(4)
	v_mfma_f32_32x32x16_bf16 v[114:129], v[224:227], v[228:231], v[114:129]
	ds_read_b128 v[188:191], v183 offset:36896
	ds_read_b128 v[192:195], v183 offset:41504
	s_waitcnt lgkmcnt(5)
	v_mfma_f32_32x32x16_bf16 v[82:97], v[224:227], v[232:235], v[82:97]
	ds_read_b128 v[196:199], v183 offset:46112
	ds_read_b128 v[200:203], v183 offset:50720
	s_waitcnt lgkmcnt(5)
	v_mfma_f32_32x32x16_bf16 v[98:113], v[224:227], v[236:239], v[98:113]
	s_waitcnt lgkmcnt(4)
	v_mfma_f32_32x32x16_bf16 v[66:81], v[224:227], v[240:243], v[66:81]
	ds_read_b128 v[224:227], v182 offset:32
	v_mfma_f32_32x32x16_bf16 v[50:65], v[184:187], v[228:231], v[50:65]
	v_mfma_f32_32x32x16_bf16 v[16:31], v[184:187], v[232:235], v[16:31]
	v_mfma_f32_32x32x16_bf16 v[34:49], v[184:187], v[236:239], v[34:49]
	v_mfma_f32_32x32x16_bf16 v[0:15], v[184:187], v[240:243], v[0:15]
	ds_read_b128 v[184:187], v182 offset:4640
	s_waitcnt lgkmcnt(1)
	v_mfma_f32_32x32x16_bf16 v[114:129], v[224:227], v[188:191], v[114:129]
	ds_read_b128 v[228:231], v183 offset:36928
	ds_read_b128 v[232:235], v183 offset:41536
	v_mfma_f32_32x32x16_bf16 v[82:97], v[224:227], v[192:195], v[82:97]
	ds_read_b128 v[236:239], v183 offset:46144
	ds_read_b128 v[240:243], v183 offset:50752
	v_mfma_f32_32x32x16_bf16 v[98:113], v[224:227], v[196:199], v[98:113]
	v_mfma_f32_32x32x16_bf16 v[66:81], v[224:227], v[200:203], v[66:81]
	ds_read_b128 v[224:227], v182 offset:64
	s_waitcnt lgkmcnt(5)
	v_mfma_f32_32x32x16_bf16 v[50:65], v[184:187], v[188:191], v[50:65]
	v_mfma_f32_32x32x16_bf16 v[16:31], v[184:187], v[192:195], v[16:31]
	v_mfma_f32_32x32x16_bf16 v[34:49], v[184:187], v[196:199], v[34:49]
	v_mfma_f32_32x32x16_bf16 v[0:15], v[184:187], v[200:203], v[0:15]
	ds_read_b128 v[184:187], v182 offset:4672
	s_waitcnt lgkmcnt(1)
	v_mfma_f32_32x32x16_bf16 v[114:129], v[224:227], v[228:231], v[114:129]
	ds_read_b128 v[188:191], v183 offset:36960
	ds_read_b128 v[192:195], v183 offset:41568
	v_mfma_f32_32x32x16_bf16 v[82:97], v[224:227], v[232:235], v[82:97]
	ds_read_b128 v[196:199], v183 offset:46176
	ds_read_b128 v[200:203], v183 offset:50784
	v_mfma_f32_32x32x16_bf16 v[98:113], v[224:227], v[236:239], v[98:113]
	v_mfma_f32_32x32x16_bf16 v[66:81], v[224:227], v[240:243], v[66:81]
	ds_read_b128 v[224:227], v182 offset:96
	s_waitcnt lgkmcnt(5)
	v_mfma_f32_32x32x16_bf16 v[50:65], v[184:187], v[228:231], v[50:65]
	v_mfma_f32_32x32x16_bf16 v[16:31], v[184:187], v[232:235], v[16:31]
	v_mfma_f32_32x32x16_bf16 v[34:49], v[184:187], v[236:239], v[34:49]
	v_mfma_f32_32x32x16_bf16 v[0:15], v[184:187], v[240:243], v[0:15]
	ds_read_b128 v[184:187], v182 offset:4704
	s_waitcnt lgkmcnt(1)
	v_mfma_f32_32x32x16_bf16 v[114:129], v[224:227], v[188:191], v[114:129]
	v_mfma_f32_32x32x16_bf16 v[82:97], v[224:227], v[192:195], v[82:97]
	v_mfma_f32_32x32x16_bf16 v[98:113], v[224:227], v[196:199], v[98:113]
	v_mfma_f32_32x32x16_bf16 v[66:81], v[224:227], v[200:203], v[66:81]
	s_waitcnt lgkmcnt(0)
	v_mfma_f32_32x32x16_bf16 v[50:65], v[184:187], v[188:191], v[50:65]
	v_mfma_f32_32x32x16_bf16 v[16:31], v[184:187], v[192:195], v[16:31]
	v_mfma_f32_32x32x16_bf16 v[34:49], v[184:187], v[196:199], v[34:49]
	v_mfma_f32_32x32x16_bf16 v[0:15], v[184:187], v[200:203], v[0:15]
	s_mov_b32 s1, s3
	s_cmp_lg_u32 s3, 16
	s_cbranch_scc1 .LBB0_944
	s_lshl_b32 s1, s2, 7
	s_lshr_b32 s2, s9, 24
	s_add_i32 s2, s8, s2
	s_lshr_b32 s2, s2, 8
	s_add_i32 s2, s2, s6
	s_mulk_i32 s2, 0x1800
	v_mov_b32_e32 v32, v206
	s_barrier
	s_ashr_i32 s3, s2, 31
	v_readlane_b32 s36, v248, 46
	s_lshl_b64 s[2:3], s[2:3], 2
	s_waitcnt vmcnt(1)
	v_and_b32_e32 v130, 0xffffffc0, v32
	v_lshrrev_b32_e32 v131, 3, v32
	v_readlane_b32 s40, v248, 50
	v_and_or_b32 v148, v32, 31, s1
	v_and_or_b32 v32, v131, 4, v130
	v_readlane_b32 s41, v248, 51
	s_add_u32 s2, s40, s2
	v_lshl_add_u32 v132, s0, 8, v32
	s_addc_u32 s3, s41, s3
	v_ashrrev_i32_e32 v133, 31, v132
	v_readlane_b32 s48, v248, 58
	v_readlane_b32 s49, v248, 59
	s_add_u32 s2, s2, 0x2000
	v_ashrrev_i32_e32 v149, 31, v148
	v_lshlrev_b64 v[136:137], 12, v[132:133]
	s_addc_u32 s3, s3, 0
	v_lshlrev_b64 v[130:131], 2, v[148:149]
	v_lshl_add_u64 v[136:137], s[48:49], 0, v[136:137]
	v_lshl_add_u64 v[134:135], s[2:3], 0, v[130:131]
	v_lshl_add_u64 v[150:151], v[136:137], 0, v[130:131]
	global_load_dword v32, v[134:135], off
	global_load_dword v138, v[134:135], off offset:256
	global_load_dword v133, v[150:151], off
	v_or_b32_e32 v136, 1, v132
	v_ashrrev_i32_e32 v137, 31, v136
	v_lshlrev_b64 v[136:137], 12, v[136:137]
	v_lshl_add_u64 v[136:137], s[48:49], 0, v[136:137]
	s_waitcnt vmcnt(3)
	v_lshl_add_u64 v[140:141], v[136:137], 0, v[130:131]
	v_writelane_b32 v251, s12, 29
	v_readlane_b32 s37, v248, 47
	v_readlane_b32 s38, v248, 48
	v_writelane_b32 v251, s13, 30
	v_readlane_b32 s39, v248, 49
	v_readlane_b32 s0, v251, 24
	s_add_i32 s7, s7, s0
	s_cmpk_lt_i32 s7, 0x200
	v_readlane_b32 s42, v248, 52
	v_readlane_b32 s43, v248, 53
	v_readlane_b32 s44, v248, 54
	v_readlane_b32 s45, v248, 55
	v_readlane_b32 s46, v248, 56
	v_readlane_b32 s47, v248, 57
	v_readlane_b32 s50, v248, 60
	v_readlane_b32 s51, v248, 61
	v_readlane_b32 s1, v251, 25
	s_waitcnt vmcnt(0)
	v_mul_f32_e32 v133, 0x3fd744fd, v133
	v_fmac_f32_e32 v133, v114, v32
	global_load_dword v114, v[150:151], off offset:256
	s_waitcnt vmcnt(0)
	v_mul_f32_e32 v114, 0x3fd744fd, v114
	v_fmac_f32_e32 v114, v98, v138
	global_load_dword v98, v[140:141], off
	s_waitcnt vmcnt(0)
	v_mul_f32_e32 v98, 0x3fd744fd, v98
	v_fmac_f32_e32 v98, v115, v32
	global_store_dword v[140:141], v98, off
	global_load_dword v98, v[140:141], off offset:256
	s_waitcnt vmcnt(0)
	v_mul_f32_e32 v98, 0x3fd744fd, v98
	v_fmac_f32_e32 v98, v99, v138
	global_store_dword v[140:141], v98, off offset:256
	v_or_b32_e32 v98, 2, v132
	v_ashrrev_i32_e32 v99, 31, v98
	v_lshlrev_b64 v[98:99], 12, v[98:99]
	v_lshl_add_u64 v[98:99], s[48:49], 0, v[98:99]
	v_lshl_add_u64 v[144:145], v[98:99], 0, v[130:131]
	global_load_dword v98, v[144:145], off
	s_waitcnt vmcnt(0)
	v_mul_f32_e32 v98, 0x3fd744fd, v98
	v_fmac_f32_e32 v98, v116, v32
	global_store_dword v[144:145], v98, off
	global_load_dword v98, v[144:145], off offset:256
	s_waitcnt vmcnt(0)
	v_mul_f32_e32 v98, 0x3fd744fd, v98
	v_fmac_f32_e32 v98, v100, v138
	global_store_dword v[144:145], v98, off offset:256
	v_or_b32_e32 v98, 3, v132
	v_ashrrev_i32_e32 v99, 31, v98
	v_lshlrev_b64 v[98:99], 12, v[98:99]
	v_lshl_add_u64 v[98:99], s[48:49], 0, v[98:99]
	v_lshl_add_u64 v[142:143], v[98:99], 0, v[130:131]
	global_load_dword v98, v[142:143], off
	s_waitcnt vmcnt(0)
	v_mul_f32_e32 v98, 0x3fd744fd, v98
	v_fmac_f32_e32 v98, v117, v32
	global_load_dword v32, v[142:143], off offset:256
	s_waitcnt vmcnt(0)
	v_mul_f32_e32 v32, 0x3fd744fd, v32
	global_store_dword v[142:143], v98, off
	v_or_b32_e32 v98, 8, v132
	v_ashrrev_i32_e32 v99, 31, v98
	v_lshlrev_b64 v[98:99], 12, v[98:99]
	v_fmac_f32_e32 v32, v101, v138
	v_lshl_add_u64 v[98:99], s[48:49], 0, v[98:99]
	global_store_dword v[150:151], v133, off
	global_store_dword v[150:151], v114, off offset:256
	global_store_dword v[142:143], v32, off offset:256
	v_lshl_add_u64 v[146:147], v[98:99], 0, v[130:131]
	global_load_dword v32, v[134:135], off
	global_load_dword v100, v[134:135], off offset:256
	global_load_dword v98, v[146:147], off
	s_waitcnt vmcnt(0)
	v_mul_f32_e32 v98, 0x3fd744fd, v98
	v_fmac_f32_e32 v98, v118, v32
	global_store_dword v[146:147], v98, off
	global_load_dword v98, v[146:147], off offset:256
	s_waitcnt vmcnt(0)
	v_mul_f32_e32 v98, 0x3fd744fd, v98
	v_fmac_f32_e32 v98, v102, v100
	global_store_dword v[146:147], v98, off offset:256
	v_or_b32_e32 v98, 9, v132
	v_ashrrev_i32_e32 v99, 31, v98
	v_lshlrev_b64 v[98:99], 12, v[98:99]
	v_lshl_add_u64 v[98:99], s[48:49], 0, v[98:99]
	v_lshl_add_u64 v[136:137], v[98:99], 0, v[130:131]
	global_load_dword v98, v[136:137], off
	s_waitcnt vmcnt(0)
	v_mul_f32_e32 v98, 0x3fd744fd, v98
	v_fmac_f32_e32 v98, v119, v32
	global_store_dword v[136:137], v98, off
	global_load_dword v98, v[136:137], off offset:256
	s_waitcnt vmcnt(0)
	v_mul_f32_e32 v98, 0x3fd744fd, v98
	v_fmac_f32_e32 v98, v103, v100
	global_store_dword v[136:137], v98, off offset:256
	v_or_b32_e32 v98, 10, v132
	v_ashrrev_i32_e32 v99, 31, v98
	v_lshlrev_b64 v[98:99], 12, v[98:99]
	v_lshl_add_u64 v[98:99], s[48:49], 0, v[98:99]
	v_lshl_add_u64 v[138:139], v[98:99], 0, v[130:131]
	global_load_dword v98, v[138:139], off
	s_waitcnt vmcnt(0)
	v_mul_f32_e32 v98, 0x3fd744fd, v98
	v_fmac_f32_e32 v98, v120, v32
	global_store_dword v[138:139], v98, off
	global_load_dword v98, v[138:139], off offset:256
	s_waitcnt vmcnt(0)
	v_mul_f32_e32 v98, 0x3fd744fd, v98
	v_fmac_f32_e32 v98, v104, v100
	global_store_dword v[138:139], v98, off offset:256
	v_or_b32_e32 v98, 11, v132
	v_ashrrev_i32_e32 v99, 31, v98
	v_lshlrev_b64 v[98:99], 12, v[98:99]
	v_lshl_add_u64 v[98:99], s[48:49], 0, v[98:99]
	v_lshl_add_u64 v[118:119], v[98:99], 0, v[130:131]
	global_load_dword v98, v[118:119], off
	s_waitcnt vmcnt(0)
	v_mul_f32_e32 v98, 0x3fd744fd, v98
	v_fmac_f32_e32 v98, v121, v32
	global_load_dword v32, v[118:119], off offset:256
	s_waitcnt vmcnt(0)
	v_mul_f32_e32 v32, 0x3fd744fd, v32
	global_store_dword v[118:119], v98, off
	v_or_b32_e32 v98, 16, v132
	v_ashrrev_i32_e32 v99, 31, v98
	v_lshlrev_b64 v[98:99], 12, v[98:99]
	v_fmac_f32_e32 v32, v105, v100
	v_lshl_add_u64 v[98:99], s[48:49], 0, v[98:99]
	global_store_dword v[118:119], v32, off offset:256
	v_lshl_add_u64 v[120:121], v[98:99], 0, v[130:131]
	global_load_dword v32, v[134:135], off
	global_load_dword v100, v[134:135], off offset:256
	global_load_dword v98, v[120:121], off
	s_waitcnt vmcnt(0)
	v_mul_f32_e32 v98, 0x3fd744fd, v98
	v_fmac_f32_e32 v98, v122, v32
	global_store_dword v[120:121], v98, off
	global_load_dword v98, v[120:121], off offset:256
	s_waitcnt vmcnt(0)
	v_mul_f32_e32 v98, 0x3fd744fd, v98
	v_fmac_f32_e32 v98, v106, v100
	global_store_dword v[120:121], v98, off offset:256
	v_or_b32_e32 v98, 17, v132
	v_ashrrev_i32_e32 v99, 31, v98
	v_lshlrev_b64 v[98:99], 12, v[98:99]
	v_lshl_add_u64 v[98:99], s[48:49], 0, v[98:99]
	v_lshl_add_u64 v[114:115], v[98:99], 0, v[130:131]
	global_load_dword v98, v[114:115], off
	s_waitcnt vmcnt(0)
	v_mul_f32_e32 v98, 0x3fd744fd, v98
	v_fmac_f32_e32 v98, v123, v32
	global_store_dword v[114:115], v98, off
	global_load_dword v98, v[114:115], off offset:256
	s_waitcnt vmcnt(0)
	v_mul_f32_e32 v98, 0x3fd744fd, v98
	v_fmac_f32_e32 v98, v107, v100
	global_store_dword v[114:115], v98, off offset:256
	v_or_b32_e32 v98, 18, v132
	v_ashrrev_i32_e32 v99, 31, v98
	v_lshlrev_b64 v[98:99], 12, v[98:99]
	v_lshl_add_u64 v[98:99], s[48:49], 0, v[98:99]
	v_lshl_add_u64 v[116:117], v[98:99], 0, v[130:131]
	global_load_dword v98, v[116:117], off
	s_waitcnt vmcnt(0)
	v_mul_f32_e32 v98, 0x3fd744fd, v98
	v_fmac_f32_e32 v98, v124, v32
	global_store_dword v[116:117], v98, off
	global_load_dword v98, v[116:117], off offset:256
	s_waitcnt vmcnt(0)
	v_mul_f32_e32 v98, 0x3fd744fd, v98
	v_fmac_f32_e32 v98, v108, v100
	global_store_dword v[116:117], v98, off offset:256
	v_or_b32_e32 v98, 19, v132
	v_ashrrev_i32_e32 v99, 31, v98
	v_lshlrev_b64 v[98:99], 12, v[98:99]
	v_lshl_add_u64 v[98:99], s[48:49], 0, v[98:99]
	v_lshl_add_u64 v[106:107], v[98:99], 0, v[130:131]
	global_load_dword v98, v[106:107], off
	s_waitcnt vmcnt(0)
	v_mul_f32_e32 v98, 0x3fd744fd, v98
	v_fmac_f32_e32 v98, v125, v32
	global_load_dword v32, v[106:107], off offset:256
	s_waitcnt vmcnt(0)
	v_mul_f32_e32 v32, 0x3fd744fd, v32
	global_store_dword v[106:107], v98, off
	v_or_b32_e32 v98, 24, v132
	v_ashrrev_i32_e32 v99, 31, v98
	v_lshlrev_b64 v[98:99], 12, v[98:99]
	v_fmac_f32_e32 v32, v109, v100
	v_lshl_add_u64 v[98:99], s[48:49], 0, v[98:99]
	global_store_dword v[106:107], v32, off offset:256
	v_lshl_add_u64 v[108:109], v[98:99], 0, v[130:131]
	global_load_dword v32, v[134:135], off
	global_load_dword v122, v[134:135], off offset:256
	global_load_dword v98, v[108:109], off
	s_waitcnt vmcnt(0)
	v_mul_f32_e32 v98, 0x3fd744fd, v98
	v_fmac_f32_e32 v98, v126, v32
	global_store_dword v[108:109], v98, off
	global_load_dword v98, v[108:109], off offset:256
	s_waitcnt vmcnt(0)
	v_mul_f32_e32 v98, 0x3fd744fd, v98
	v_fmac_f32_e32 v98, v110, v122
	global_store_dword v[108:109], v98, off offset:256
	v_or_b32_e32 v98, 25, v132
	v_ashrrev_i32_e32 v99, 31, v98
	v_lshlrev_b64 v[98:99], 12, v[98:99]
	v_lshl_add_u64 v[98:99], s[48:49], 0, v[98:99]
	v_lshl_add_u64 v[102:103], v[98:99], 0, v[130:131]
	global_load_dword v98, v[102:103], off
	s_waitcnt vmcnt(0)
	v_mul_f32_e32 v98, 0x3fd744fd, v98
	v_fmac_f32_e32 v98, v127, v32
	global_store_dword v[102:103], v98, off
	global_load_dword v98, v[102:103], off offset:256
	s_waitcnt vmcnt(0)
	v_mul_f32_e32 v98, 0x3fd744fd, v98
	v_fmac_f32_e32 v98, v111, v122
	global_store_dword v[102:103], v98, off offset:256
	v_or_b32_e32 v98, 26, v132
	v_ashrrev_i32_e32 v99, 31, v98
	v_lshlrev_b64 v[98:99], 12, v[98:99]
	v_lshl_add_u64 v[98:99], s[48:49], 0, v[98:99]
	v_lshl_add_u64 v[104:105], v[98:99], 0, v[130:131]
	global_load_dword v98, v[104:105], off
	s_waitcnt vmcnt(0)
	v_mul_f32_e32 v98, 0x3fd744fd, v98
	v_fmac_f32_e32 v98, v128, v32
	global_store_dword v[104:105], v98, off
	global_load_dword v98, v[104:105], off offset:256
	s_waitcnt vmcnt(0)
	v_mul_f32_e32 v98, 0x3fd744fd, v98
	v_fmac_f32_e32 v98, v112, v122
	global_store_dword v[104:105], v98, off offset:256
	v_or_b32_e32 v98, 27, v132
	v_ashrrev_i32_e32 v99, 31, v98
	v_lshlrev_b64 v[98:99], 12, v[98:99]
	v_lshl_add_u64 v[98:99], s[48:49], 0, v[98:99]
	v_lshl_add_u64 v[100:101], v[98:99], 0, v[130:131]
	global_load_dword v98, v[100:101], off
	s_waitcnt vmcnt(0)
	v_mul_f32_e32 v98, 0x3fd744fd, v98
	v_fmac_f32_e32 v98, v129, v32
	global_load_dword v32, v[100:101], off offset:256
	s_waitcnt vmcnt(0)
	v_mul_f32_e32 v32, 0x3fd744fd, v32
	global_store_dword v[100:101], v98, off
	v_or_b32_e32 v98, 32, v148
	v_fmac_f32_e32 v32, v113, v122
	v_ashrrev_i32_e32 v99, 31, v98
	global_store_dword v[100:101], v32, off offset:256
	v_lshl_add_u64 v[98:99], v[98:99], 2, s[2:3]
	global_load_dword v110, v[98:99], off
	global_load_dword v32, v[98:99], off offset:256
	global_load_dword v111, v[150:151], off offset:128
	s_waitcnt vmcnt(0)
	v_mul_f32_e32 v111, 0x3fd744fd, v111
	v_fmac_f32_e32 v111, v82, v110
	global_load_dword v82, v[150:151], off offset:384
	s_waitcnt vmcnt(0)
	v_mul_f32_e32 v82, 0x3fd744fd, v82
	v_fmac_f32_e32 v82, v66, v32
	global_load_dword v66, v[140:141], off offset:128
	s_waitcnt vmcnt(0)
	v_mul_f32_e32 v66, 0x3fd744fd, v66
	v_fmac_f32_e32 v66, v83, v110
	global_store_dword v[140:141], v66, off offset:128
	global_load_dword v66, v[140:141], off offset:384
	s_waitcnt vmcnt(0)
	v_mul_f32_e32 v66, 0x3fd744fd, v66
	v_fmac_f32_e32 v66, v67, v32
	global_store_dword v[140:141], v66, off offset:384
	global_load_dword v66, v[144:145], off offset:128
	s_waitcnt vmcnt(0)
	v_mul_f32_e32 v66, 0x3fd744fd, v66
	v_fmac_f32_e32 v66, v84, v110
	global_store_dword v[144:145], v66, off offset:128
	global_load_dword v66, v[144:145], off offset:384
	s_waitcnt vmcnt(0)
	v_mul_f32_e32 v66, 0x3fd744fd, v66
	v_fmac_f32_e32 v66, v68, v32
	global_store_dword v[144:145], v66, off offset:384
	global_load_dword v66, v[142:143], off offset:128
	s_waitcnt vmcnt(0)
	v_mul_f32_e32 v66, 0x3fd744fd, v66
	v_fmac_f32_e32 v66, v85, v110
	global_store_dword v[142:143], v66, off offset:128
	global_load_dword v66, v[142:143], off offset:384
	s_waitcnt vmcnt(0)
	v_mul_f32_e32 v66, 0x3fd744fd, v66
	v_fmac_f32_e32 v66, v69, v32
	global_store_dword v[150:151], v111, off offset:128
	global_store_dword v[150:151], v82, off offset:384
	global_store_dword v[142:143], v66, off offset:384
	global_load_dword v32, v[98:99], off
	s_nop 0
	global_load_dword v66, v[98:99], off offset:256
	global_load_dword v67, v[146:147], off offset:128
	s_waitcnt vmcnt(0)
	v_mul_f32_e32 v67, 0x3fd744fd, v67
	v_fmac_f32_e32 v67, v86, v32
	global_store_dword v[146:147], v67, off offset:128
	global_load_dword v67, v[146:147], off offset:384
	s_waitcnt vmcnt(0)
	v_mul_f32_e32 v67, 0x3fd744fd, v67
	v_fmac_f32_e32 v67, v70, v66
	global_store_dword v[146:147], v67, off offset:384
	global_load_dword v67, v[136:137], off offset:128
	s_waitcnt vmcnt(0)
	v_mul_f32_e32 v67, 0x3fd744fd, v67
	v_fmac_f32_e32 v67, v87, v32
	global_store_dword v[136:137], v67, off offset:128
	global_load_dword v67, v[136:137], off offset:384
	s_waitcnt vmcnt(0)
	v_mul_f32_e32 v67, 0x3fd744fd, v67
	v_fmac_f32_e32 v67, v71, v66
	global_store_dword v[136:137], v67, off offset:384
	global_load_dword v67, v[138:139], off offset:128
	s_waitcnt vmcnt(0)
	v_mul_f32_e32 v67, 0x3fd744fd, v67
	v_fmac_f32_e32 v67, v88, v32
	global_store_dword v[138:139], v67, off offset:128
	global_load_dword v67, v[138:139], off offset:384
	s_waitcnt vmcnt(0)
	v_mul_f32_e32 v67, 0x3fd744fd, v67
	v_fmac_f32_e32 v67, v72, v66
	global_store_dword v[138:139], v67, off offset:384
	global_load_dword v67, v[118:119], off offset:128
	s_waitcnt vmcnt(0)
	v_mul_f32_e32 v67, 0x3fd744fd, v67
	v_fmac_f32_e32 v67, v89, v32
	global_load_dword v32, v[118:119], off offset:384
	s_waitcnt vmcnt(0)
	v_mul_f32_e32 v32, 0x3fd744fd, v32
	v_fmac_f32_e32 v32, v73, v66
	global_store_dword v[118:119], v67, off offset:128
	global_store_dword v[118:119], v32, off offset:384
	global_load_dword v32, v[98:99], off
	s_nop 0
	global_load_dword v66, v[98:99], off offset:256
	global_load_dword v67, v[120:121], off offset:128
	s_waitcnt vmcnt(0)
	v_mul_f32_e32 v67, 0x3fd744fd, v67
	v_fmac_f32_e32 v67, v90, v32
	global_store_dword v[120:121], v67, off offset:128
	global_load_dword v67, v[120:121], off offset:384
	s_waitcnt vmcnt(0)
	v_mul_f32_e32 v67, 0x3fd744fd, v67
	v_fmac_f32_e32 v67, v74, v66
	global_store_dword v[120:121], v67, off offset:384
	global_load_dword v67, v[114:115], off offset:128
	s_waitcnt vmcnt(0)
	v_mul_f32_e32 v67, 0x3fd744fd, v67
	v_fmac_f32_e32 v67, v91, v32
	global_store_dword v[114:115], v67, off offset:128
	global_load_dword v67, v[114:115], off offset:384
	s_waitcnt vmcnt(0)
	v_mul_f32_e32 v67, 0x3fd744fd, v67
	v_fmac_f32_e32 v67, v75, v66
	global_store_dword v[114:115], v67, off offset:384
	global_load_dword v67, v[116:117], off offset:128
	s_waitcnt vmcnt(0)
	v_mul_f32_e32 v67, 0x3fd744fd, v67
	v_fmac_f32_e32 v67, v92, v32
	global_store_dword v[116:117], v67, off offset:128
	global_load_dword v67, v[116:117], off offset:384
	s_waitcnt vmcnt(0)
	v_mul_f32_e32 v67, 0x3fd744fd, v67
	v_fmac_f32_e32 v67, v76, v66
	global_store_dword v[116:117], v67, off offset:384
	global_load_dword v67, v[106:107], off offset:128
	s_waitcnt vmcnt(0)
	v_mul_f32_e32 v67, 0x3fd744fd, v67
	v_fmac_f32_e32 v67, v93, v32
	global_load_dword v32, v[106:107], off offset:384
	s_waitcnt vmcnt(0)
	v_mul_f32_e32 v32, 0x3fd744fd, v32
	v_fmac_f32_e32 v32, v77, v66
	global_store_dword v[106:107], v67, off offset:128
	global_store_dword v[106:107], v32, off offset:384
	global_load_dword v32, v[98:99], off
	s_nop 0
	global_load_dword v66, v[98:99], off offset:256
	global_load_dword v67, v[108:109], off offset:128
	s_waitcnt vmcnt(0)
	v_mul_f32_e32 v67, 0x3fd744fd, v67
	v_fmac_f32_e32 v67, v94, v32
	global_store_dword v[108:109], v67, off offset:128
	global_load_dword v67, v[108:109], off offset:384
	s_waitcnt vmcnt(0)
	v_mul_f32_e32 v67, 0x3fd744fd, v67
	v_fmac_f32_e32 v67, v78, v66
	global_store_dword v[108:109], v67, off offset:384
	global_load_dword v67, v[102:103], off offset:128
	s_waitcnt vmcnt(0)
	v_mul_f32_e32 v67, 0x3fd744fd, v67
	v_fmac_f32_e32 v67, v95, v32
	global_store_dword v[102:103], v67, off offset:128
	global_load_dword v67, v[102:103], off offset:384
	s_waitcnt vmcnt(0)
	v_mul_f32_e32 v67, 0x3fd744fd, v67
	v_fmac_f32_e32 v67, v79, v66
	global_store_dword v[102:103], v67, off offset:384
	global_load_dword v67, v[104:105], off offset:128
	s_waitcnt vmcnt(0)
	v_mul_f32_e32 v67, 0x3fd744fd, v67
	v_fmac_f32_e32 v67, v96, v32
	global_store_dword v[104:105], v67, off offset:128
	global_load_dword v67, v[104:105], off offset:384
	s_waitcnt vmcnt(0)
	v_mul_f32_e32 v67, 0x3fd744fd, v67
	v_fmac_f32_e32 v67, v80, v66
	global_store_dword v[104:105], v67, off offset:384
	global_load_dword v67, v[100:101], off offset:128
	s_waitcnt vmcnt(0)
	v_mul_f32_e32 v67, 0x3fd744fd, v67
	v_fmac_f32_e32 v67, v97, v32
	global_load_dword v32, v[100:101], off offset:384
	s_waitcnt vmcnt(0)
	v_mul_f32_e32 v32, 0x3fd744fd, v32
	v_fmac_f32_e32 v32, v81, v66
	v_or_b32_e32 v66, 32, v132
	global_store_dword v[100:101], v67, off offset:128
	v_ashrrev_i32_e32 v67, 31, v66
	v_lshlrev_b64 v[66:67], 12, v[66:67]
	v_lshl_add_u64 v[66:67], s[48:49], 0, v[66:67]
	global_store_dword v[100:101], v32, off offset:384
	v_lshl_add_u64 v[78:79], v[66:67], 0, v[130:131]
	global_load_dword v32, v[134:135], off
	global_load_dword v70, v[134:135], off offset:256
	global_load_dword v66, v[78:79], off
	s_waitcnt vmcnt(0)
	v_mul_f32_e32 v66, 0x3fd744fd, v66
	v_fmac_f32_e32 v66, v50, v32
	global_load_dword v50, v[78:79], off offset:256
	s_waitcnt vmcnt(0)
	v_mul_f32_e32 v50, 0x3fd744fd, v50
	global_store_dword v[78:79], v66, off
	v_or_b32_e32 v66, 33, v132
	v_ashrrev_i32_e32 v67, 31, v66
	v_lshlrev_b64 v[66:67], 12, v[66:67]
	v_lshl_add_u64 v[66:67], s[48:49], 0, v[66:67]
	v_lshl_add_u64 v[66:67], v[66:67], 0, v[130:131]
	v_fmac_f32_e32 v50, v34, v70
	global_load_dword v34, v[66:67], off
	s_waitcnt vmcnt(0)
	v_mul_f32_e32 v34, 0x3fd744fd, v34
	v_fmac_f32_e32 v34, v51, v32
	global_store_dword v[66:67], v34, off
	global_load_dword v34, v[66:67], off offset:256
	s_waitcnt vmcnt(0)
	v_mul_f32_e32 v34, 0x3fd744fd, v34
	v_fmac_f32_e32 v34, v35, v70
	global_store_dword v[66:67], v34, off offset:256
	v_or_b32_e32 v34, 34, v132
	v_ashrrev_i32_e32 v35, 31, v34
	v_lshlrev_b64 v[34:35], 12, v[34:35]
	v_lshl_add_u64 v[34:35], s[48:49], 0, v[34:35]
	v_lshl_add_u64 v[68:69], v[34:35], 0, v[130:131]
	global_load_dword v34, v[68:69], off
	s_waitcnt vmcnt(0)
	v_mul_f32_e32 v34, 0x3fd744fd, v34
	v_fmac_f32_e32 v34, v52, v32
	global_store_dword v[68:69], v34, off
	global_load_dword v34, v[68:69], off offset:256
	s_waitcnt vmcnt(0)
	v_mul_f32_e32 v34, 0x3fd744fd, v34
	v_fmac_f32_e32 v34, v36, v70
	global_store_dword v[68:69], v34, off offset:256
	v_or_b32_e32 v34, 35, v132
	v_ashrrev_i32_e32 v35, 31, v34
	v_lshlrev_b64 v[34:35], 12, v[34:35]
	v_lshl_add_u64 v[34:35], s[48:49], 0, v[34:35]
	v_lshl_add_u64 v[72:73], v[34:35], 0, v[130:131]
	global_load_dword v34, v[72:73], off
	s_waitcnt vmcnt(0)
	v_mul_f32_e32 v34, 0x3fd744fd, v34
	v_fmac_f32_e32 v34, v53, v32
	global_load_dword v32, v[72:73], off offset:256
	s_waitcnt vmcnt(0)
	v_mul_f32_e32 v32, 0x3fd744fd, v32
	global_store_dword v[72:73], v34, off
	v_or_b32_e32 v34, 40, v132
	v_ashrrev_i32_e32 v35, 31, v34
	v_lshlrev_b64 v[34:35], 12, v[34:35]
	v_fmac_f32_e32 v32, v37, v70
	v_lshl_add_u64 v[34:35], s[48:49], 0, v[34:35]
	global_store_dword v[78:79], v50, off offset:256
	global_store_dword v[72:73], v32, off offset:256
	v_lshl_add_u64 v[76:77], v[34:35], 0, v[130:131]
	global_load_dword v32, v[134:135], off
	global_load_dword v36, v[134:135], off offset:256
	global_load_dword v34, v[76:77], off
	s_waitcnt vmcnt(0)
	v_mul_f32_e32 v34, 0x3fd744fd, v34
	v_fmac_f32_e32 v34, v54, v32
	global_store_dword v[76:77], v34, off
	global_load_dword v34, v[76:77], off offset:256
	s_waitcnt vmcnt(0)
	v_mul_f32_e32 v34, 0x3fd744fd, v34
	v_fmac_f32_e32 v34, v38, v36
	global_store_dword v[76:77], v34, off offset:256
	v_or_b32_e32 v34, 41, v132
	v_ashrrev_i32_e32 v35, 31, v34
	v_lshlrev_b64 v[34:35], 12, v[34:35]
	v_lshl_add_u64 v[34:35], s[48:49], 0, v[34:35]
	v_lshl_add_u64 v[70:71], v[34:35], 0, v[130:131]
	global_load_dword v34, v[70:71], off
	s_waitcnt vmcnt(0)
	v_mul_f32_e32 v34, 0x3fd744fd, v34
	v_fmac_f32_e32 v34, v55, v32
	global_store_dword v[70:71], v34, off
	global_load_dword v34, v[70:71], off offset:256
	s_waitcnt vmcnt(0)
	v_mul_f32_e32 v34, 0x3fd744fd, v34
	v_fmac_f32_e32 v34, v39, v36
	global_store_dword v[70:71], v34, off offset:256
	v_or_b32_e32 v34, 42, v132
	v_ashrrev_i32_e32 v35, 31, v34
	v_lshlrev_b64 v[34:35], 12, v[34:35]
	v_lshl_add_u64 v[34:35], s[48:49], 0, v[34:35]
	v_lshl_add_u64 v[54:55], v[34:35], 0, v[130:131]
	global_load_dword v34, v[54:55], off
	s_waitcnt vmcnt(0)
	v_mul_f32_e32 v34, 0x3fd744fd, v34
	v_fmac_f32_e32 v34, v56, v32
	global_store_dword v[54:55], v34, off
	global_load_dword v34, v[54:55], off offset:256
	s_waitcnt vmcnt(0)
	v_mul_f32_e32 v34, 0x3fd744fd, v34
	v_fmac_f32_e32 v34, v40, v36
	global_store_dword v[54:55], v34, off offset:256
	v_or_b32_e32 v34, 43, v132
	v_ashrrev_i32_e32 v35, 31, v34
	v_lshlrev_b64 v[34:35], 12, v[34:35]
	v_lshl_add_u64 v[34:35], s[48:49], 0, v[34:35]
	v_lshl_add_u64 v[74:75], v[34:35], 0, v[130:131]
	global_load_dword v34, v[74:75], off
	s_waitcnt vmcnt(0)
	v_mul_f32_e32 v34, 0x3fd744fd, v34
	v_fmac_f32_e32 v34, v57, v32
	global_load_dword v32, v[74:75], off offset:256
	s_waitcnt vmcnt(0)
	v_mul_f32_e32 v32, 0x3fd744fd, v32
	global_store_dword v[74:75], v34, off
	v_or_b32_e32 v34, 48, v132
	v_ashrrev_i32_e32 v35, 31, v34
	v_lshlrev_b64 v[34:35], 12, v[34:35]
	v_fmac_f32_e32 v32, v41, v36
	v_lshl_add_u64 v[34:35], s[48:49], 0, v[34:35]
	global_store_dword v[74:75], v32, off offset:256
	v_lshl_add_u64 v[56:57], v[34:35], 0, v[130:131]
	global_load_dword v32, v[134:135], off
	global_load_dword v36, v[134:135], off offset:256
	global_load_dword v34, v[56:57], off
	s_waitcnt vmcnt(0)
	v_mul_f32_e32 v34, 0x3fd744fd, v34
	v_fmac_f32_e32 v34, v58, v32
	global_store_dword v[56:57], v34, off
	global_load_dword v34, v[56:57], off offset:256
	s_waitcnt vmcnt(0)
	v_mul_f32_e32 v34, 0x3fd744fd, v34
	v_fmac_f32_e32 v34, v42, v36
	global_store_dword v[56:57], v34, off offset:256
	v_or_b32_e32 v34, 49, v132
	v_ashrrev_i32_e32 v35, 31, v34
	v_lshlrev_b64 v[34:35], 12, v[34:35]
	v_lshl_add_u64 v[34:35], s[48:49], 0, v[34:35]
	v_lshl_add_u64 v[50:51], v[34:35], 0, v[130:131]
	global_load_dword v34, v[50:51], off
	s_waitcnt vmcnt(0)
	v_mul_f32_e32 v34, 0x3fd744fd, v34
	v_fmac_f32_e32 v34, v59, v32
	global_store_dword v[50:51], v34, off
	global_load_dword v34, v[50:51], off offset:256
	s_waitcnt vmcnt(0)
	v_mul_f32_e32 v34, 0x3fd744fd, v34
	v_fmac_f32_e32 v34, v43, v36
	global_store_dword v[50:51], v34, off offset:256
	v_or_b32_e32 v34, 50, v132
	v_ashrrev_i32_e32 v35, 31, v34
	v_lshlrev_b64 v[34:35], 12, v[34:35]
	v_lshl_add_u64 v[34:35], s[48:49], 0, v[34:35]
	v_lshl_add_u64 v[52:53], v[34:35], 0, v[130:131]
	global_load_dword v34, v[52:53], off
	s_waitcnt vmcnt(0)
	v_mul_f32_e32 v34, 0x3fd744fd, v34
	v_fmac_f32_e32 v34, v60, v32
	global_store_dword v[52:53], v34, off
	global_load_dword v34, v[52:53], off offset:256
	s_waitcnt vmcnt(0)
	v_mul_f32_e32 v34, 0x3fd744fd, v34
	v_fmac_f32_e32 v34, v44, v36
	global_store_dword v[52:53], v34, off offset:256
	v_or_b32_e32 v34, 51, v132
	v_ashrrev_i32_e32 v35, 31, v34
	v_lshlrev_b64 v[34:35], 12, v[34:35]
	v_lshl_add_u64 v[34:35], s[48:49], 0, v[34:35]
	v_lshl_add_u64 v[40:41], v[34:35], 0, v[130:131]
	global_load_dword v34, v[40:41], off
	s_waitcnt vmcnt(0)
	v_mul_f32_e32 v34, 0x3fd744fd, v34
	v_fmac_f32_e32 v34, v61, v32
	global_load_dword v32, v[40:41], off offset:256
	s_waitcnt vmcnt(0)
	v_mul_f32_e32 v32, 0x3fd744fd, v32
	global_store_dword v[40:41], v34, off
	v_or_b32_e32 v34, 56, v132
	v_ashrrev_i32_e32 v35, 31, v34
	v_lshlrev_b64 v[34:35], 12, v[34:35]
	v_fmac_f32_e32 v32, v45, v36
	v_lshl_add_u64 v[34:35], s[48:49], 0, v[34:35]
	global_store_dword v[40:41], v32, off offset:256
	v_lshl_add_u64 v[42:43], v[34:35], 0, v[130:131]
	global_load_dword v32, v[134:135], off
	global_load_dword v44, v[134:135], off offset:256
	global_load_dword v34, v[42:43], off
	s_waitcnt vmcnt(0)
	v_mul_f32_e32 v34, 0x3fd744fd, v34
	v_fmac_f32_e32 v34, v62, v32
	global_store_dword v[42:43], v34, off
	global_load_dword v34, v[42:43], off offset:256
	s_waitcnt vmcnt(0)
	v_mul_f32_e32 v34, 0x3fd744fd, v34
	v_fmac_f32_e32 v34, v46, v44
	global_store_dword v[42:43], v34, off offset:256
	v_or_b32_e32 v34, 57, v132
	v_ashrrev_i32_e32 v35, 31, v34
	v_lshlrev_b64 v[34:35], 12, v[34:35]
	v_lshl_add_u64 v[34:35], s[48:49], 0, v[34:35]
	v_lshl_add_u64 v[36:37], v[34:35], 0, v[130:131]
	global_load_dword v34, v[36:37], off
	s_waitcnt vmcnt(0)
	v_mul_f32_e32 v34, 0x3fd744fd, v34
	v_fmac_f32_e32 v34, v63, v32
	global_store_dword v[36:37], v34, off
	global_load_dword v34, v[36:37], off offset:256
	s_waitcnt vmcnt(0)
	v_mul_f32_e32 v34, 0x3fd744fd, v34
	v_fmac_f32_e32 v34, v47, v44
	global_store_dword v[36:37], v34, off offset:256
	v_or_b32_e32 v34, 58, v132
	v_ashrrev_i32_e32 v35, 31, v34
	v_lshlrev_b64 v[34:35], 12, v[34:35]
	v_lshl_add_u64 v[34:35], s[48:49], 0, v[34:35]
	v_lshl_add_u64 v[38:39], v[34:35], 0, v[130:131]
	global_load_dword v34, v[38:39], off
	s_waitcnt vmcnt(0)
	v_mul_f32_e32 v34, 0x3fd744fd, v34
	v_fmac_f32_e32 v34, v64, v32
	global_store_dword v[38:39], v34, off
	global_load_dword v34, v[38:39], off offset:256
	s_waitcnt vmcnt(0)
	v_mul_f32_e32 v34, 0x3fd744fd, v34
	v_fmac_f32_e32 v34, v48, v44
	global_store_dword v[38:39], v34, off offset:256
	v_or_b32_e32 v34, 59, v132
	v_ashrrev_i32_e32 v35, 31, v34
	v_lshlrev_b64 v[34:35], 12, v[34:35]
	v_lshl_add_u64 v[34:35], s[48:49], 0, v[34:35]
	v_lshl_add_u64 v[34:35], v[34:35], 0, v[130:131]
	global_load_dword v45, v[34:35], off
	s_waitcnt vmcnt(0)
	v_mul_f32_e32 v45, 0x3fd744fd, v45
	v_fmac_f32_e32 v45, v65, v32
	global_load_dword v32, v[34:35], off offset:256
	s_waitcnt vmcnt(0)
	v_mul_f32_e32 v32, 0x3fd744fd, v32
	v_fmac_f32_e32 v32, v49, v44
	global_store_dword v[34:35], v45, off
	global_store_dword v[34:35], v32, off offset:256
	global_load_dword v44, v[98:99], off
	s_nop 0
	global_load_dword v32, v[98:99], off offset:256
	global_load_dword v45, v[78:79], off offset:128
	s_waitcnt vmcnt(0)
	v_mul_f32_e32 v45, 0x3fd744fd, v45
	v_fmac_f32_e32 v45, v16, v44
	global_load_dword v16, v[78:79], off offset:384
	s_waitcnt vmcnt(0)
	v_mul_f32_e32 v16, 0x3fd744fd, v16
	v_fmac_f32_e32 v16, v0, v32
	global_load_dword v0, v[66:67], off offset:128
	s_waitcnt vmcnt(0)
	v_mul_f32_e32 v0, 0x3fd744fd, v0
	v_fmac_f32_e32 v0, v17, v44
	global_store_dword v[66:67], v0, off offset:128
	global_load_dword v0, v[66:67], off offset:384
	s_waitcnt vmcnt(0)
	v_mul_f32_e32 v0, 0x3fd744fd, v0
	v_fmac_f32_e32 v0, v1, v32
	global_store_dword v[66:67], v0, off offset:384
	global_load_dword v0, v[68:69], off offset:128
	s_waitcnt vmcnt(0)
	v_mul_f32_e32 v0, 0x3fd744fd, v0
	v_fmac_f32_e32 v0, v18, v44
	global_store_dword v[68:69], v0, off offset:128
	global_load_dword v0, v[68:69], off offset:384
	s_waitcnt vmcnt(0)
	v_mul_f32_e32 v0, 0x3fd744fd, v0
	v_fmac_f32_e32 v0, v2, v32
	global_store_dword v[68:69], v0, off offset:384
	global_load_dword v0, v[72:73], off offset:128
	s_waitcnt vmcnt(0)
	v_mul_f32_e32 v0, 0x3fd744fd, v0
	v_fmac_f32_e32 v0, v19, v44
	global_store_dword v[72:73], v0, off offset:128
	global_load_dword v0, v[72:73], off offset:384
	s_waitcnt vmcnt(0)
	v_mul_f32_e32 v0, 0x3fd744fd, v0
	v_fmac_f32_e32 v0, v3, v32
	global_store_dword v[78:79], v45, off offset:128
	global_store_dword v[78:79], v16, off offset:384
	global_store_dword v[72:73], v0, off offset:384
	global_load_dword v0, v[98:99], off
	s_nop 0
	global_load_dword v1, v[98:99], off offset:256
	global_load_dword v2, v[76:77], off offset:128
	s_waitcnt vmcnt(0)
	v_mul_f32_e32 v2, 0x3fd744fd, v2
	v_fmac_f32_e32 v2, v20, v0
	global_store_dword v[76:77], v2, off offset:128
	global_load_dword v2, v[76:77], off offset:384
	s_waitcnt vmcnt(0)
	v_mul_f32_e32 v2, 0x3fd744fd, v2
	v_fmac_f32_e32 v2, v4, v1
	global_store_dword v[76:77], v2, off offset:384
	global_load_dword v2, v[70:71], off offset:128
	s_waitcnt vmcnt(0)
	v_mul_f32_e32 v2, 0x3fd744fd, v2
	v_fmac_f32_e32 v2, v21, v0
	global_store_dword v[70:71], v2, off offset:128
	global_load_dword v2, v[70:71], off offset:384
	s_waitcnt vmcnt(0)
	v_mul_f32_e32 v2, 0x3fd744fd, v2
	v_fmac_f32_e32 v2, v5, v1
	global_store_dword v[70:71], v2, off offset:384
	global_load_dword v2, v[54:55], off offset:128
	s_waitcnt vmcnt(0)
	v_mul_f32_e32 v2, 0x3fd744fd, v2
	v_fmac_f32_e32 v2, v22, v0
	global_store_dword v[54:55], v2, off offset:128
	global_load_dword v2, v[54:55], off offset:384
	s_waitcnt vmcnt(0)
	v_mul_f32_e32 v2, 0x3fd744fd, v2
	v_fmac_f32_e32 v2, v6, v1
	global_store_dword v[54:55], v2, off offset:384
	global_load_dword v2, v[74:75], off offset:128
	s_waitcnt vmcnt(0)
	v_mul_f32_e32 v2, 0x3fd744fd, v2
	v_fmac_f32_e32 v2, v23, v0
	global_load_dword v0, v[74:75], off offset:384
	s_waitcnt vmcnt(0)
	v_mul_f32_e32 v0, 0x3fd744fd, v0
	v_fmac_f32_e32 v0, v7, v1
	global_store_dword v[74:75], v2, off offset:128
	global_store_dword v[74:75], v0, off offset:384
	global_load_dword v0, v[98:99], off
	s_nop 0
	global_load_dword v1, v[98:99], off offset:256
	global_load_dword v2, v[56:57], off offset:128
	s_waitcnt vmcnt(0)
	v_mul_f32_e32 v2, 0x3fd744fd, v2
	v_fmac_f32_e32 v2, v24, v0
	global_store_dword v[56:57], v2, off offset:128
	global_load_dword v2, v[56:57], off offset:384
	s_waitcnt vmcnt(0)
	v_mul_f32_e32 v2, 0x3fd744fd, v2
	v_fmac_f32_e32 v2, v8, v1
	global_store_dword v[56:57], v2, off offset:384
	global_load_dword v2, v[50:51], off offset:128
	s_waitcnt vmcnt(0)
	v_mul_f32_e32 v2, 0x3fd744fd, v2
	v_fmac_f32_e32 v2, v25, v0
	global_store_dword v[50:51], v2, off offset:128
	global_load_dword v2, v[50:51], off offset:384
	s_waitcnt vmcnt(0)
	v_mul_f32_e32 v2, 0x3fd744fd, v2
	v_fmac_f32_e32 v2, v9, v1
	global_store_dword v[50:51], v2, off offset:384
	global_load_dword v2, v[52:53], off offset:128
	s_waitcnt vmcnt(0)
	v_mul_f32_e32 v2, 0x3fd744fd, v2
	v_fmac_f32_e32 v2, v26, v0
	global_store_dword v[52:53], v2, off offset:128
	global_load_dword v2, v[52:53], off offset:384
	s_waitcnt vmcnt(0)
	v_mul_f32_e32 v2, 0x3fd744fd, v2
	v_fmac_f32_e32 v2, v10, v1
	global_store_dword v[52:53], v2, off offset:384
	global_load_dword v2, v[40:41], off offset:128
	s_waitcnt vmcnt(0)
	v_mul_f32_e32 v2, 0x3fd744fd, v2
	v_fmac_f32_e32 v2, v27, v0
	global_load_dword v0, v[40:41], off offset:384
	s_waitcnt vmcnt(0)
	v_mul_f32_e32 v0, 0x3fd744fd, v0
	v_fmac_f32_e32 v0, v11, v1
	global_store_dword v[40:41], v2, off offset:128
	global_store_dword v[40:41], v0, off offset:384
	global_load_dword v0, v[98:99], off
	s_nop 0
	global_load_dword v1, v[98:99], off offset:256
	global_load_dword v2, v[42:43], off offset:128
	s_waitcnt vmcnt(0)
	v_mul_f32_e32 v2, 0x3fd744fd, v2
	v_fmac_f32_e32 v2, v28, v0
	global_store_dword v[42:43], v2, off offset:128
	global_load_dword v2, v[42:43], off offset:384
	s_waitcnt vmcnt(0)
	v_mul_f32_e32 v2, 0x3fd744fd, v2
	v_fmac_f32_e32 v2, v12, v1
	global_store_dword v[42:43], v2, off offset:384
	global_load_dword v2, v[36:37], off offset:128
	s_waitcnt vmcnt(0)
	v_mul_f32_e32 v2, 0x3fd744fd, v2
	v_fmac_f32_e32 v2, v29, v0
	global_store_dword v[36:37], v2, off offset:128
	global_load_dword v2, v[36:37], off offset:384
	s_waitcnt vmcnt(0)
	v_mul_f32_e32 v2, 0x3fd744fd, v2
	v_fmac_f32_e32 v2, v13, v1
	global_store_dword v[36:37], v2, off offset:384
	global_load_dword v2, v[38:39], off offset:128
	s_waitcnt vmcnt(0)
	v_mul_f32_e32 v2, 0x3fd744fd, v2
	v_fmac_f32_e32 v2, v30, v0
	global_store_dword v[38:39], v2, off offset:128
	global_load_dword v2, v[38:39], off offset:384
	s_waitcnt vmcnt(0)
	v_mul_f32_e32 v2, 0x3fd744fd, v2
	v_fmac_f32_e32 v2, v14, v1
	global_store_dword v[38:39], v2, off offset:384
	global_load_dword v2, v[34:35], off offset:128
	s_waitcnt vmcnt(0)
	v_mul_f32_e32 v2, 0x3fd744fd, v2
	v_fmac_f32_e32 v2, v31, v0
	global_load_dword v0, v[34:35], off offset:384
	s_waitcnt vmcnt(0)
	v_mul_f32_e32 v0, 0x3fd744fd, v0
	v_fmac_f32_e32 v0, v15, v1
	global_store_dword v[34:35], v2, off offset:128
	global_store_dword v[34:35], v0, off offset:384
	s_cbranch_scc1 .LBB0_940

.LBB0_1018:
	s_add_i32 s3, s1, 1
	s_cmp_lt_u32 s1, 15
	s_cselect_b32 s1, s3, s1
	s_lshl_b32 s12, s1, 6
	s_lshl_b64 s[10:11], s[12:13], 1
	s_barrier
	s_waitcnt vmcnt(0)
	ds_write_b128 v204, v[174:177]
	ds_write_b128 v204, v[170:173] offset:4608
	ds_write_b128 v204, v[166:169] offset:9216
	ds_write_b128 v204, v[162:165] offset:13824
	ds_write_b128 v204, v[158:161] offset:18432
	ds_write_b128 v204, v[154:157] offset:23040
	ds_write_b128 v204, v[150:153] offset:27648
	ds_write_b128 v204, v[146:149] offset:32256
	ds_write_b128 v204, v[142:145] offset:36864
	ds_write_b128 v204, v[134:137] offset:41472
	ds_write_b128 v204, v[130:133] offset:46080
	ds_write_b128 v204, v[138:141] offset:50688
	v_lshl_add_u64 v[130:131], v[178:179], 0, s[10:11]
	s_add_u32 s100, s10, 0x10000
	s_addc_u32 s101, s11, 0
	v_lshl_add_u64 v[132:133], v[178:179], 0, s[100:101]
	s_add_u32 s100, s100, 0x10000
	s_addc_u32 s101, s101, 0
	v_lshl_add_u64 v[134:135], v[178:179], 0, s[100:101]
	s_add_u32 s100, s100, 0x10000
	s_addc_u32 s101, s101, 0
	v_lshl_add_u64 v[136:137], v[178:179], 0, s[100:101]
	s_add_u32 s100, s100, 0x10000
	s_addc_u32 s101, s101, 0
	v_lshl_add_u64 v[138:139], v[178:179], 0, s[100:101]
	s_add_u32 s100, s100, 0x10000
	s_addc_u32 s101, s101, 0
	v_lshl_add_u64 v[140:141], v[178:179], 0, s[100:101]
	s_add_u32 s100, s100, 0x10000
	s_addc_u32 s101, s101, 0
	v_lshl_add_u64 v[142:143], v[178:179], 0, s[100:101]
	s_add_u32 s100, s100, 0x10000
	s_addc_u32 s101, s101, 0
	v_lshl_add_u64 v[144:145], v[178:179], 0, s[100:101]
	s_waitcnt lgkmcnt(0)
	s_barrier
	v_lshl_add_u64 v[224:225], v[180:181], 0, s[10:11]
	s_add_u32 s100, s10, 0x10000
	s_addc_u32 s101, s11, 0
	v_lshl_add_u64 v[226:227], v[180:181], 0, s[100:101]
	s_add_u32 s100, s100, 0x10000
	s_addc_u32 s101, s101, 0
	v_lshl_add_u64 v[228:229], v[180:181], 0, s[100:101]
	s_add_u32 s100, s100, 0x10000
	s_addc_u32 s101, s101, 0
	v_lshl_add_u64 v[230:231], v[180:181], 0, s[100:101]
	global_load_dwordx4 v[174:177], v[130:131], off
	global_load_dwordx4 v[170:173], v[132:133], off
	global_load_dwordx4 v[166:169], v[134:135], off
	global_load_dwordx4 v[162:165], v[136:137], off
	global_load_dwordx4 v[158:161], v[138:139], off
	global_load_dwordx4 v[154:157], v[140:141], off
	global_load_dwordx4 v[150:153], v[142:143], off
	global_load_dwordx4 v[146:149], v[144:145], off
	global_load_dwordx4 v[142:145], v[224:225], off
	global_load_dwordx4 v[134:137], v[226:227], off
	global_load_dwordx4 v[130:133], v[228:229], off
	global_load_dwordx4 v[138:141], v[230:231], off
	ds_read_b128 v[224:227], v182
	ds_read_b128 v[228:231], v183 offset:36864
	ds_read_b128 v[232:235], v183 offset:41472
	ds_read_b128 v[184:187], v182 offset:4608
	ds_read_b128 v[236:239], v183 offset:46080
	ds_read_b128 v[240:243], v183 offset:50688
	s_waitcnt lgkmcnt(4)
	v_mfma_f32_32x32x16_bf16 v[114:129], v[224:227], v[228:231], v[114:129]
	ds_read_b128 v[188:191], v183 offset:36896
	ds_read_b128 v[192:195], v183 offset:41504
	s_waitcnt lgkmcnt(5)
	v_mfma_f32_32x32x16_bf16 v[82:97], v[224:227], v[232:235], v[82:97]
	ds_read_b128 v[196:199], v183 offset:46112
	ds_read_b128 v[200:203], v183 offset:50720
	s_waitcnt lgkmcnt(5)
	v_mfma_f32_32x32x16_bf16 v[98:113], v[224:227], v[236:239], v[98:113]
	s_waitcnt lgkmcnt(4)
	v_mfma_f32_32x32x16_bf16 v[66:81], v[224:227], v[240:243], v[66:81]
	ds_read_b128 v[224:227], v182 offset:32
	v_mfma_f32_32x32x16_bf16 v[50:65], v[184:187], v[228:231], v[50:65]
	v_mfma_f32_32x32x16_bf16 v[16:31], v[184:187], v[232:235], v[16:31]
	v_mfma_f32_32x32x16_bf16 v[34:49], v[184:187], v[236:239], v[34:49]
	v_mfma_f32_32x32x16_bf16 v[0:15], v[184:187], v[240:243], v[0:15]
	ds_read_b128 v[184:187], v182 offset:4640
	s_waitcnt lgkmcnt(1)
	v_mfma_f32_32x32x16_bf16 v[114:129], v[224:227], v[188:191], v[114:129]
	ds_read_b128 v[228:231], v183 offset:36928
	ds_read_b128 v[232:235], v183 offset:41536
	v_mfma_f32_32x32x16_bf16 v[82:97], v[224:227], v[192:195], v[82:97]
	ds_read_b128 v[236:239], v183 offset:46144
	ds_read_b128 v[240:243], v183 offset:50752
	v_mfma_f32_32x32x16_bf16 v[98:113], v[224:227], v[196:199], v[98:113]
	v_mfma_f32_32x32x16_bf16 v[66:81], v[224:227], v[200:203], v[66:81]
	ds_read_b128 v[224:227], v182 offset:64
	s_waitcnt lgkmcnt(5)
	v_mfma_f32_32x32x16_bf16 v[50:65], v[184:187], v[188:191], v[50:65]
	v_mfma_f32_32x32x16_bf16 v[16:31], v[184:187], v[192:195], v[16:31]
	v_mfma_f32_32x32x16_bf16 v[34:49], v[184:187], v[196:199], v[34:49]
	v_mfma_f32_32x32x16_bf16 v[0:15], v[184:187], v[200:203], v[0:15]
	ds_read_b128 v[184:187], v182 offset:4672
	s_waitcnt lgkmcnt(1)
	v_mfma_f32_32x32x16_bf16 v[114:129], v[224:227], v[228:231], v[114:129]
	ds_read_b128 v[188:191], v183 offset:36960
	ds_read_b128 v[192:195], v183 offset:41568
	v_mfma_f32_32x32x16_bf16 v[82:97], v[224:227], v[232:235], v[82:97]
	ds_read_b128 v[196:199], v183 offset:46176
	ds_read_b128 v[200:203], v183 offset:50784
	v_mfma_f32_32x32x16_bf16 v[98:113], v[224:227], v[236:239], v[98:113]
	v_mfma_f32_32x32x16_bf16 v[66:81], v[224:227], v[240:243], v[66:81]
	ds_read_b128 v[224:227], v182 offset:96
	s_waitcnt lgkmcnt(5)
	v_mfma_f32_32x32x16_bf16 v[50:65], v[184:187], v[228:231], v[50:65]
	v_mfma_f32_32x32x16_bf16 v[16:31], v[184:187], v[232:235], v[16:31]
	v_mfma_f32_32x32x16_bf16 v[34:49], v[184:187], v[236:239], v[34:49]
	v_mfma_f32_32x32x16_bf16 v[0:15], v[184:187], v[240:243], v[0:15]
	ds_read_b128 v[184:187], v182 offset:4704
	s_waitcnt lgkmcnt(1)
	v_mfma_f32_32x32x16_bf16 v[114:129], v[224:227], v[188:191], v[114:129]
	v_mfma_f32_32x32x16_bf16 v[82:97], v[224:227], v[192:195], v[82:97]
	v_mfma_f32_32x32x16_bf16 v[98:113], v[224:227], v[196:199], v[98:113]
	v_mfma_f32_32x32x16_bf16 v[66:81], v[224:227], v[200:203], v[66:81]
	s_waitcnt lgkmcnt(0)
	v_mfma_f32_32x32x16_bf16 v[50:65], v[184:187], v[188:191], v[50:65]
	v_mfma_f32_32x32x16_bf16 v[16:31], v[184:187], v[192:195], v[16:31]
	v_mfma_f32_32x32x16_bf16 v[34:49], v[184:187], v[196:199], v[34:49]
	v_mfma_f32_32x32x16_bf16 v[0:15], v[184:187], v[200:203], v[0:15]
	s_mov_b32 s1, s3
	s_cmp_lg_u32 s3, 16
	s_cbranch_scc1 .LBB0_1018
	s_lshl_b32 s1, s2, 8
	s_bfe_i32 s2, s2, 0x10017
	s_lshr_b32 s2, s2, 19
	v_writelane_b32 v251, s12, 29
	s_add_i32 s2, s1, s2
	s_and_b32 s2, s2, 0xffffe000
	v_writelane_b32 v251, s13, 30
	s_ashr_i32 s12, s8, 8
	s_add_i32 s12, s12, s9
	s_sub_i32 s17, s1, s2
	s_cmp_gt_i32 s0, 15
	s_mov_b64 s[2:3], -1
	s_barrier
	s_cbranch_scc0 .LBB0_1025
	s_cmp_gt_u32 s0, 31
	s_cbranch_scc0 .LBB0_1022
	v_mov_b32_e32 v32, v206
	v_readlane_b32 s24, v249, 18
	s_waitcnt vmcnt(1)
	v_and_b32_e32 v130, 0xffffffc0, v32
	v_lshrrev_b32_e32 v131, 3, v32
	v_and_or_b32 v130, v131, 4, v130
	v_add_u32_e32 v132, s1, v130
	s_lshl_b32 s1, s0, 8
	v_readlane_b32 s26, v249, 20
	v_and_b32_e32 v32, 31, v32
	v_readlane_b32 s27, v249, 21
	s_add_u32 s2, s26, s1
	s_addc_u32 s3, s27, 0
	v_lshlrev_b32_e32 v32, 1, v32
	v_lshl_add_u64 v[130:131], s[2:3], 0, v[32:33]
	v_mul_f32_e32 v32, 0xbfb8aa3b, v114
	v_exp_f32_e32 v32, v32
	s_movk_i32 s2, 0xe000
	s_mov_b32 s3, -1
	v_lshl_add_u64 v[130:131], v[130:131], 0, s[2:3]
	v_add_f32_e32 v32, 1.0, v32
	v_div_scale_f32 v134, s[2:3], v32, v32, v114
	v_rcp_f32_e32 v135, v134
	v_ashrrev_i32_e32 v133, 31, v132
	s_movk_i32 s1, 0x7fff
	v_readlane_b32 s25, v249, 19
	v_fma_f32 v136, -v134, v135, 1.0
	v_fmac_f32_e32 v135, v136, v135
	v_div_scale_f32 v136, vcc, v114, v32, v114
	v_mul_f32_e32 v137, v136, v135
	s_waitcnt vmcnt(0)
	v_fma_f32 v138, -v134, v137, v136
	v_fmac_f32_e32 v137, v138, v135
	v_fma_f32 v134, -v134, v137, v136
	v_div_fmas_f32 v134, v134, v135, v137
	v_div_fixup_f32 v32, v134, v32, v114
	v_bfe_u32 v134, v32, 16, 1
	v_add3_u32 v32, v32, v134, s1
	v_lshlrev_b64 v[134:135], 12, v[132:133]
	v_lshl_add_u64 v[134:135], v[130:131], 0, v[134:135]
	global_store_short_d16_hi v[134:135], v32, off
	v_mul_f32_e32 v32, 0xbfb8aa3b, v98
	v_exp_f32_e32 v32, v32
	v_readlane_b32 s28, v249, 22
	v_readlane_b32 s29, v249, 23
	v_readlane_b32 s30, v249, 24
	v_add_f32_e32 v32, 1.0, v32
	v_div_scale_f32 v133, s[2:3], v32, v32, v98
	v_rcp_f32_e32 v136, v133
	v_readlane_b32 s31, v249, 25
	v_fma_f32 v137, -v133, v136, 1.0
	v_fmac_f32_e32 v136, v137, v136
	v_div_scale_f32 v137, vcc, v98, v32, v98
	v_mul_f32_e32 v138, v137, v136
	v_fma_f32 v139, -v133, v138, v137
	v_fmac_f32_e32 v138, v139, v136
	v_fma_f32 v133, -v133, v138, v137
	v_div_fmas_f32 v133, v133, v136, v138
	v_div_fixup_f32 v32, v133, v32, v98
	v_bfe_u32 v133, v32, 16, 1
	v_add3_u32 v32, v32, v133, s1
	global_store_short_d16_hi v[134:135], v32, off offset:128
	v_mul_f32_e32 v32, 0xbfb8aa3b, v115
	v_exp_f32_e32 v32, v32
	v_or_b32_e32 v136, 1, v132
	v_ashrrev_i32_e32 v137, 31, v136
	v_lshlrev_b64 v[136:137], 12, v[136:137]
	v_add_f32_e32 v32, 1.0, v32
	v_div_scale_f32 v133, s[2:3], v32, v32, v115
	v_rcp_f32_e32 v138, v133
	v_lshl_add_u64 v[136:137], v[130:131], 0, v[136:137]
	v_fma_f32 v139, -v133, v138, 1.0
	v_fmac_f32_e32 v138, v139, v138
	v_div_scale_f32 v139, vcc, v115, v32, v115
	v_mul_f32_e32 v140, v139, v138
	v_fma_f32 v141, -v133, v140, v139
	v_fmac_f32_e32 v140, v141, v138
	v_fma_f32 v133, -v133, v140, v139
	v_div_fmas_f32 v133, v133, v138, v140
	v_div_fixup_f32 v32, v133, v32, v115
	v_bfe_u32 v133, v32, 16, 1
	v_add3_u32 v32, v32, v133, s1
	global_store_short_d16_hi v[136:137], v32, off
	v_mul_f32_e32 v32, 0xbfb8aa3b, v99
	v_exp_f32_e32 v32, v32
	s_nop 0
	v_add_f32_e32 v32, 1.0, v32
	v_div_scale_f32 v133, s[2:3], v32, v32, v99
	v_rcp_f32_e32 v138, v133
	s_nop 0
	v_fma_f32 v139, -v133, v138, 1.0
	v_fmac_f32_e32 v138, v139, v138
	v_div_scale_f32 v139, vcc, v99, v32, v99
	v_mul_f32_e32 v140, v139, v138
	v_fma_f32 v141, -v133, v140, v139
	v_fmac_f32_e32 v140, v141, v138
	v_fma_f32 v133, -v133, v140, v139
	v_div_fmas_f32 v133, v133, v138, v140
	v_div_fixup_f32 v32, v133, v32, v99
	v_bfe_u32 v133, v32, 16, 1
	v_add3_u32 v32, v32, v133, s1
	global_store_short_d16_hi v[136:137], v32, off offset:128
	v_mul_f32_e32 v32, 0xbfb8aa3b, v116
	v_exp_f32_e32 v32, v32
	v_or_b32_e32 v138, 2, v132
	v_ashrrev_i32_e32 v139, 31, v138
	v_lshlrev_b64 v[138:139], 12, v[138:139]
	v_add_f32_e32 v32, 1.0, v32
	v_div_scale_f32 v133, s[2:3], v32, v32, v116
	v_rcp_f32_e32 v140, v133
	v_lshl_add_u64 v[138:139], v[130:131], 0, v[138:139]
	v_fma_f32 v141, -v133, v140, 1.0
	v_fmac_f32_e32 v140, v141, v140
	v_div_scale_f32 v141, vcc, v116, v32, v116
	v_mul_f32_e32 v142, v141, v140
	v_fma_f32 v143, -v133, v142, v141
	v_fmac_f32_e32 v142, v143, v140
	v_fma_f32 v133, -v133, v142, v141
	v_div_fmas_f32 v133, v133, v140, v142
	v_div_fixup_f32 v32, v133, v32, v116
	v_bfe_u32 v133, v32, 16, 1
	v_add3_u32 v32, v32, v133, s1
	global_store_short_d16_hi v[138:139], v32, off
	v_mul_f32_e32 v32, 0xbfb8aa3b, v100
	v_exp_f32_e32 v32, v32
	s_nop 0
	v_add_f32_e32 v32, 1.0, v32
	v_div_scale_f32 v133, s[2:3], v32, v32, v100
	v_rcp_f32_e32 v140, v133
	s_nop 0
	v_fma_f32 v141, -v133, v140, 1.0
	v_fmac_f32_e32 v140, v141, v140
	v_div_scale_f32 v141, vcc, v100, v32, v100
	v_mul_f32_e32 v142, v141, v140
	v_fma_f32 v143, -v133, v142, v141
	v_fmac_f32_e32 v142, v143, v140
	v_fma_f32 v133, -v133, v142, v141
	v_div_fmas_f32 v133, v133, v140, v142
	v_div_fixup_f32 v32, v133, v32, v100
	v_bfe_u32 v133, v32, 16, 1
	v_add3_u32 v32, v32, v133, s1
	global_store_short_d16_hi v[138:139], v32, off offset:128
	v_mul_f32_e32 v32, 0xbfb8aa3b, v117
	v_exp_f32_e32 v32, v32
	v_or_b32_e32 v140, 3, v132
	v_ashrrev_i32_e32 v141, 31, v140
	v_lshlrev_b64 v[140:141], 12, v[140:141]
	v_add_f32_e32 v32, 1.0, v32
	v_div_scale_f32 v133, s[2:3], v32, v32, v117
	v_rcp_f32_e32 v142, v133
	v_lshl_add_u64 v[140:141], v[130:131], 0, v[140:141]
	v_fma_f32 v143, -v133, v142, 1.0
	v_fmac_f32_e32 v142, v143, v142
	v_div_scale_f32 v143, vcc, v117, v32, v117
	v_mul_f32_e32 v144, v143, v142
	v_fma_f32 v145, -v133, v144, v143
	v_fmac_f32_e32 v144, v145, v142
	v_fma_f32 v133, -v133, v144, v143
	v_div_fmas_f32 v133, v133, v142, v144
	v_div_fixup_f32 v32, v133, v32, v117
	v_bfe_u32 v133, v32, 16, 1
	v_add3_u32 v32, v32, v133, s1
	global_store_short_d16_hi v[140:141], v32, off
	v_mul_f32_e32 v32, 0xbfb8aa3b, v101
	v_exp_f32_e32 v32, v32
	s_nop 0
	v_add_f32_e32 v32, 1.0, v32
	v_div_scale_f32 v133, s[2:3], v32, v32, v101
	v_rcp_f32_e32 v142, v133
	s_nop 0
	v_fma_f32 v143, -v133, v142, 1.0
	v_fmac_f32_e32 v142, v143, v142
	v_div_scale_f32 v143, vcc, v101, v32, v101
	v_mul_f32_e32 v144, v143, v142
	v_fma_f32 v145, -v133, v144, v143
	v_fmac_f32_e32 v144, v145, v142
	v_fma_f32 v133, -v133, v144, v143
	v_div_fmas_f32 v133, v133, v142, v144
	v_div_fixup_f32 v32, v133, v32, v101
	v_bfe_u32 v133, v32, 16, 1
	v_add3_u32 v32, v32, v133, s1
	global_store_short_d16_hi v[140:141], v32, off offset:128
	v_mul_f32_e32 v32, 0xbfb8aa3b, v118
	v_exp_f32_e32 v32, v32
	v_or_b32_e32 v142, 8, v132
	v_ashrrev_i32_e32 v143, 31, v142
	v_lshlrev_b64 v[142:143], 12, v[142:143]
	v_add_f32_e32 v32, 1.0, v32
	v_div_scale_f32 v133, s[2:3], v32, v32, v118
	v_rcp_f32_e32 v144, v133
	v_lshl_add_u64 v[142:143], v[130:131], 0, v[142:143]
	v_fma_f32 v145, -v133, v144, 1.0
	v_fmac_f32_e32 v144, v145, v144
	v_div_scale_f32 v145, vcc, v118, v32, v118
	v_mul_f32_e32 v146, v145, v144
	v_fma_f32 v147, -v133, v146, v145
	v_fmac_f32_e32 v146, v147, v144
	v_fma_f32 v133, -v133, v146, v145
	v_div_fmas_f32 v133, v133, v144, v146
	v_div_fixup_f32 v32, v133, v32, v118
	v_bfe_u32 v133, v32, 16, 1
	v_add3_u32 v32, v32, v133, s1
	global_store_short_d16_hi v[142:143], v32, off
	v_mul_f32_e32 v32, 0xbfb8aa3b, v102
	v_exp_f32_e32 v32, v32
	s_nop 0
	v_add_f32_e32 v32, 1.0, v32
	v_div_scale_f32 v133, s[2:3], v32, v32, v102
	v_rcp_f32_e32 v144, v133
	s_nop 0
	v_fma_f32 v145, -v133, v144, 1.0
	v_fmac_f32_e32 v144, v145, v144
	v_div_scale_f32 v145, vcc, v102, v32, v102
	v_mul_f32_e32 v146, v145, v144
	v_fma_f32 v147, -v133, v146, v145
	v_fmac_f32_e32 v146, v147, v144
	v_fma_f32 v133, -v133, v146, v145
	v_div_fmas_f32 v133, v133, v144, v146
	v_div_fixup_f32 v32, v133, v32, v102
	v_bfe_u32 v133, v32, 16, 1
	v_add3_u32 v32, v32, v133, s1
	global_store_short_d16_hi v[142:143], v32, off offset:128
	v_mul_f32_e32 v32, 0xbfb8aa3b, v119
	v_exp_f32_e32 v32, v32
	v_or_b32_e32 v144, 9, v132
	v_ashrrev_i32_e32 v145, 31, v144
	v_lshlrev_b64 v[144:145], 12, v[144:145]
	v_add_f32_e32 v32, 1.0, v32
	v_div_scale_f32 v133, s[2:3], v32, v32, v119
	v_rcp_f32_e32 v146, v133
	v_lshl_add_u64 v[144:145], v[130:131], 0, v[144:145]
	v_fma_f32 v147, -v133, v146, 1.0
	v_fmac_f32_e32 v146, v147, v146
	v_div_scale_f32 v147, vcc, v119, v32, v119
	v_mul_f32_e32 v148, v147, v146
	v_fma_f32 v149, -v133, v148, v147
	v_fmac_f32_e32 v148, v149, v146
	v_fma_f32 v133, -v133, v148, v147
	v_div_fmas_f32 v133, v133, v146, v148
	v_div_fixup_f32 v32, v133, v32, v119
	v_bfe_u32 v133, v32, 16, 1
	v_add3_u32 v32, v32, v133, s1
	global_store_short_d16_hi v[144:145], v32, off
	v_mul_f32_e32 v32, 0xbfb8aa3b, v103
	v_exp_f32_e32 v32, v32
	s_nop 0
	v_add_f32_e32 v32, 1.0, v32
	v_div_scale_f32 v133, s[2:3], v32, v32, v103
	v_rcp_f32_e32 v146, v133
	s_nop 0
	v_fma_f32 v147, -v133, v146, 1.0
	v_fmac_f32_e32 v146, v147, v146
	v_div_scale_f32 v147, vcc, v103, v32, v103
	v_mul_f32_e32 v148, v147, v146
	v_fma_f32 v149, -v133, v148, v147
	v_fmac_f32_e32 v148, v149, v146
	v_fma_f32 v133, -v133, v148, v147
	v_div_fmas_f32 v133, v133, v146, v148
	v_div_fixup_f32 v32, v133, v32, v103
	v_bfe_u32 v133, v32, 16, 1
	v_add3_u32 v32, v32, v133, s1
	global_store_short_d16_hi v[144:145], v32, off offset:128
	v_mul_f32_e32 v32, 0xbfb8aa3b, v120
	v_exp_f32_e32 v32, v32
	v_or_b32_e32 v146, 10, v132
	v_ashrrev_i32_e32 v147, 31, v146
	v_lshlrev_b64 v[146:147], 12, v[146:147]
	v_add_f32_e32 v32, 1.0, v32
	v_div_scale_f32 v133, s[2:3], v32, v32, v120
	v_rcp_f32_e32 v148, v133
	v_lshl_add_u64 v[146:147], v[130:131], 0, v[146:147]
	v_fma_f32 v149, -v133, v148, 1.0
	v_fmac_f32_e32 v148, v149, v148
	v_div_scale_f32 v149, vcc, v120, v32, v120
	v_mul_f32_e32 v150, v149, v148
	v_fma_f32 v151, -v133, v150, v149
	v_fmac_f32_e32 v150, v151, v148
	v_fma_f32 v133, -v133, v150, v149
	v_div_fmas_f32 v133, v133, v148, v150
	v_div_fixup_f32 v32, v133, v32, v120
	v_bfe_u32 v133, v32, 16, 1
	v_add3_u32 v32, v32, v133, s1
	global_store_short_d16_hi v[146:147], v32, off
	v_mul_f32_e32 v32, 0xbfb8aa3b, v104
	v_exp_f32_e32 v32, v32
	s_nop 0
	v_add_f32_e32 v32, 1.0, v32
	v_div_scale_f32 v133, s[2:3], v32, v32, v104
	v_rcp_f32_e32 v148, v133
	s_nop 0
	v_fma_f32 v149, -v133, v148, 1.0
	v_fmac_f32_e32 v148, v149, v148
	v_div_scale_f32 v149, vcc, v104, v32, v104
	v_mul_f32_e32 v150, v149, v148
	v_fma_f32 v151, -v133, v150, v149
	v_fmac_f32_e32 v150, v151, v148
	v_fma_f32 v133, -v133, v150, v149
	v_div_fmas_f32 v133, v133, v148, v150
	v_div_fixup_f32 v32, v133, v32, v104
	v_bfe_u32 v133, v32, 16, 1
	v_add3_u32 v32, v32, v133, s1
	global_store_short_d16_hi v[146:147], v32, off offset:128
	v_mul_f32_e32 v32, 0xbfb8aa3b, v121
	v_exp_f32_e32 v32, v32
	v_or_b32_e32 v148, 11, v132
	v_ashrrev_i32_e32 v149, 31, v148
	v_lshlrev_b64 v[148:149], 12, v[148:149]
	v_add_f32_e32 v32, 1.0, v32
	v_div_scale_f32 v133, s[2:3], v32, v32, v121
	v_rcp_f32_e32 v150, v133
	v_lshl_add_u64 v[148:149], v[130:131], 0, v[148:149]
	v_fma_f32 v151, -v133, v150, 1.0
	v_fmac_f32_e32 v150, v151, v150
	v_div_scale_f32 v151, vcc, v121, v32, v121
	v_mul_f32_e32 v152, v151, v150
	v_fma_f32 v153, -v133, v152, v151
	v_fmac_f32_e32 v152, v153, v150
	v_fma_f32 v133, -v133, v152, v151
	v_div_fmas_f32 v133, v133, v150, v152
	v_div_fixup_f32 v32, v133, v32, v121
	v_bfe_u32 v133, v32, 16, 1
	v_add3_u32 v32, v32, v133, s1
	global_store_short_d16_hi v[148:149], v32, off
	v_mul_f32_e32 v32, 0xbfb8aa3b, v105
	v_exp_f32_e32 v32, v32
	s_nop 0
	v_add_f32_e32 v32, 1.0, v32
	v_div_scale_f32 v133, s[2:3], v32, v32, v105
	v_rcp_f32_e32 v150, v133
	s_nop 0
	v_fma_f32 v151, -v133, v150, 1.0
	v_fmac_f32_e32 v150, v151, v150
	v_div_scale_f32 v151, vcc, v105, v32, v105
	v_mul_f32_e32 v152, v151, v150
	v_fma_f32 v153, -v133, v152, v151
	v_fmac_f32_e32 v152, v153, v150
	v_fma_f32 v133, -v133, v152, v151
	v_div_fmas_f32 v133, v133, v150, v152
	v_div_fixup_f32 v32, v133, v32, v105
	v_bfe_u32 v133, v32, 16, 1
	v_add3_u32 v32, v32, v133, s1
	global_store_short_d16_hi v[148:149], v32, off offset:128
	v_mul_f32_e32 v32, 0xbfb8aa3b, v122
	v_exp_f32_e32 v32, v32
	v_or_b32_e32 v150, 16, v132
	v_ashrrev_i32_e32 v151, 31, v150
	v_lshlrev_b64 v[150:151], 12, v[150:151]
	v_add_f32_e32 v32, 1.0, v32
	v_div_scale_f32 v133, s[2:3], v32, v32, v122
	v_rcp_f32_e32 v152, v133
	v_lshl_add_u64 v[150:151], v[130:131], 0, v[150:151]
	v_fma_f32 v153, -v133, v152, 1.0
	v_fmac_f32_e32 v152, v153, v152
	v_div_scale_f32 v153, vcc, v122, v32, v122
	v_mul_f32_e32 v154, v153, v152
	v_fma_f32 v155, -v133, v154, v153
	v_fmac_f32_e32 v154, v155, v152
	v_fma_f32 v133, -v133, v154, v153
	v_div_fmas_f32 v133, v133, v152, v154
	v_div_fixup_f32 v32, v133, v32, v122
	v_bfe_u32 v133, v32, 16, 1
	v_add3_u32 v32, v32, v133, s1
	global_store_short_d16_hi v[150:151], v32, off
	v_mul_f32_e32 v32, 0xbfb8aa3b, v106
	v_exp_f32_e32 v32, v32
	s_nop 0
	v_add_f32_e32 v32, 1.0, v32
	v_div_scale_f32 v133, s[2:3], v32, v32, v106
	v_rcp_f32_e32 v152, v133
	s_nop 0
	v_fma_f32 v153, -v133, v152, 1.0
	v_fmac_f32_e32 v152, v153, v152
	v_div_scale_f32 v153, vcc, v106, v32, v106
	v_mul_f32_e32 v154, v153, v152
	v_fma_f32 v155, -v133, v154, v153
	v_fmac_f32_e32 v154, v155, v152
	v_fma_f32 v133, -v133, v154, v153
	v_div_fmas_f32 v133, v133, v152, v154
	v_div_fixup_f32 v32, v133, v32, v106
	v_bfe_u32 v133, v32, 16, 1
	v_add3_u32 v32, v32, v133, s1
	global_store_short_d16_hi v[150:151], v32, off offset:128
	v_mul_f32_e32 v32, 0xbfb8aa3b, v123
	v_exp_f32_e32 v32, v32
	v_or_b32_e32 v152, 17, v132
	v_ashrrev_i32_e32 v153, 31, v152
	v_lshlrev_b64 v[152:153], 12, v[152:153]
	v_add_f32_e32 v32, 1.0, v32
	v_div_scale_f32 v133, s[2:3], v32, v32, v123
	v_rcp_f32_e32 v154, v133
	v_lshl_add_u64 v[152:153], v[130:131], 0, v[152:153]
	v_fma_f32 v155, -v133, v154, 1.0
	v_fmac_f32_e32 v154, v155, v154
	v_div_scale_f32 v155, vcc, v123, v32, v123
	v_mul_f32_e32 v156, v155, v154
	v_fma_f32 v157, -v133, v156, v155
	v_fmac_f32_e32 v156, v157, v154
	v_fma_f32 v133, -v133, v156, v155
	v_div_fmas_f32 v133, v133, v154, v156
	v_div_fixup_f32 v32, v133, v32, v123
	v_bfe_u32 v133, v32, 16, 1
	v_add3_u32 v32, v32, v133, s1
	global_store_short_d16_hi v[152:153], v32, off
	v_mul_f32_e32 v32, 0xbfb8aa3b, v107
	v_exp_f32_e32 v32, v32
	s_nop 0
	v_add_f32_e32 v32, 1.0, v32
	v_div_scale_f32 v133, s[2:3], v32, v32, v107
	v_rcp_f32_e32 v154, v133
	s_nop 0
	v_fma_f32 v155, -v133, v154, 1.0
	v_fmac_f32_e32 v154, v155, v154
	v_div_scale_f32 v155, vcc, v107, v32, v107
	v_mul_f32_e32 v156, v155, v154
	v_fma_f32 v157, -v133, v156, v155
	v_fmac_f32_e32 v156, v157, v154
	v_fma_f32 v133, -v133, v156, v155
	v_div_fmas_f32 v133, v133, v154, v156
	v_div_fixup_f32 v32, v133, v32, v107
	v_bfe_u32 v133, v32, 16, 1
	v_add3_u32 v32, v32, v133, s1
	global_store_short_d16_hi v[152:153], v32, off offset:128
	v_mul_f32_e32 v32, 0xbfb8aa3b, v124
	v_exp_f32_e32 v32, v32
	v_or_b32_e32 v154, 18, v132
	v_ashrrev_i32_e32 v155, 31, v154
	v_lshlrev_b64 v[154:155], 12, v[154:155]
	v_add_f32_e32 v32, 1.0, v32
	v_div_scale_f32 v133, s[2:3], v32, v32, v124
	v_rcp_f32_e32 v156, v133
	v_lshl_add_u64 v[154:155], v[130:131], 0, v[154:155]
	v_fma_f32 v157, -v133, v156, 1.0
	v_fmac_f32_e32 v156, v157, v156
	v_div_scale_f32 v157, vcc, v124, v32, v124
	v_mul_f32_e32 v158, v157, v156
	v_fma_f32 v159, -v133, v158, v157
	v_fmac_f32_e32 v158, v159, v156
	v_fma_f32 v133, -v133, v158, v157
	v_div_fmas_f32 v133, v133, v156, v158
	v_div_fixup_f32 v32, v133, v32, v124
	v_bfe_u32 v133, v32, 16, 1
	v_add3_u32 v32, v32, v133, s1
	global_store_short_d16_hi v[154:155], v32, off
	v_mul_f32_e32 v32, 0xbfb8aa3b, v108
	v_exp_f32_e32 v32, v32
	s_nop 0
	v_add_f32_e32 v32, 1.0, v32
	v_div_scale_f32 v133, s[2:3], v32, v32, v108
	v_rcp_f32_e32 v156, v133
	s_nop 0
	v_fma_f32 v157, -v133, v156, 1.0
	v_fmac_f32_e32 v156, v157, v156
	v_div_scale_f32 v157, vcc, v108, v32, v108
	v_mul_f32_e32 v158, v157, v156
	v_fma_f32 v159, -v133, v158, v157
	v_fmac_f32_e32 v158, v159, v156
	v_fma_f32 v133, -v133, v158, v157
	v_div_fmas_f32 v133, v133, v156, v158
	v_div_fixup_f32 v32, v133, v32, v108
	v_bfe_u32 v133, v32, 16, 1
	v_add3_u32 v32, v32, v133, s1
	global_store_short_d16_hi v[154:155], v32, off offset:128
	v_mul_f32_e32 v32, 0xbfb8aa3b, v125
	v_exp_f32_e32 v32, v32
	v_or_b32_e32 v156, 19, v132
	v_ashrrev_i32_e32 v157, 31, v156
	v_lshlrev_b64 v[156:157], 12, v[156:157]
	v_add_f32_e32 v32, 1.0, v32
	v_div_scale_f32 v133, s[2:3], v32, v32, v125
	v_rcp_f32_e32 v158, v133
	v_lshl_add_u64 v[156:157], v[130:131], 0, v[156:157]
	v_fma_f32 v159, -v133, v158, 1.0
	v_fmac_f32_e32 v158, v159, v158
	v_div_scale_f32 v159, vcc, v125, v32, v125
	v_mul_f32_e32 v160, v159, v158
	v_fma_f32 v161, -v133, v160, v159
	v_fmac_f32_e32 v160, v161, v158
	v_fma_f32 v133, -v133, v160, v159
	v_div_fmas_f32 v133, v133, v158, v160
	v_div_fixup_f32 v32, v133, v32, v125
	v_bfe_u32 v133, v32, 16, 1
	v_add3_u32 v32, v32, v133, s1
	global_store_short_d16_hi v[156:157], v32, off
	v_mul_f32_e32 v32, 0xbfb8aa3b, v109
	v_exp_f32_e32 v32, v32
	s_nop 0
	v_add_f32_e32 v32, 1.0, v32
	v_div_scale_f32 v133, s[2:3], v32, v32, v109
	v_rcp_f32_e32 v158, v133
	s_nop 0
	v_fma_f32 v159, -v133, v158, 1.0
	v_fmac_f32_e32 v158, v159, v158
	v_div_scale_f32 v159, vcc, v109, v32, v109
	v_mul_f32_e32 v160, v159, v158
	v_fma_f32 v161, -v133, v160, v159
	v_fmac_f32_e32 v160, v161, v158
	v_fma_f32 v133, -v133, v160, v159
	v_div_fmas_f32 v133, v133, v158, v160
	v_div_fixup_f32 v32, v133, v32, v109
	v_bfe_u32 v133, v32, 16, 1
	v_add3_u32 v32, v32, v133, s1
	global_store_short_d16_hi v[156:157], v32, off offset:128
	v_mul_f32_e32 v32, 0xbfb8aa3b, v126
	v_exp_f32_e32 v32, v32
	v_or_b32_e32 v158, 24, v132
	v_ashrrev_i32_e32 v159, 31, v158
	v_lshlrev_b64 v[158:159], 12, v[158:159]
	v_add_f32_e32 v32, 1.0, v32
	v_div_scale_f32 v133, s[2:3], v32, v32, v126
	v_rcp_f32_e32 v160, v133
	v_lshl_add_u64 v[158:159], v[130:131], 0, v[158:159]
	v_fma_f32 v161, -v133, v160, 1.0
	v_fmac_f32_e32 v160, v161, v160
	v_div_scale_f32 v161, vcc, v126, v32, v126
	v_mul_f32_e32 v162, v161, v160
	v_fma_f32 v163, -v133, v162, v161
	v_fmac_f32_e32 v162, v163, v160
	v_fma_f32 v133, -v133, v162, v161
	v_div_fmas_f32 v133, v133, v160, v162
	v_div_fixup_f32 v32, v133, v32, v126
	v_bfe_u32 v133, v32, 16, 1
	v_add3_u32 v32, v32, v133, s1
	global_store_short_d16_hi v[158:159], v32, off
	v_mul_f32_e32 v32, 0xbfb8aa3b, v110
	v_exp_f32_e32 v32, v32
	s_nop 0
	v_add_f32_e32 v32, 1.0, v32
	v_div_scale_f32 v133, s[2:3], v32, v32, v110
	v_rcp_f32_e32 v160, v133
	s_nop 0
	v_fma_f32 v161, -v133, v160, 1.0
	v_fmac_f32_e32 v160, v161, v160
	v_div_scale_f32 v161, vcc, v110, v32, v110
	v_mul_f32_e32 v162, v161, v160
	v_fma_f32 v163, -v133, v162, v161
	v_fmac_f32_e32 v162, v163, v160
	v_fma_f32 v133, -v133, v162, v161
	v_div_fmas_f32 v133, v133, v160, v162
	v_div_fixup_f32 v32, v133, v32, v110
	v_bfe_u32 v133, v32, 16, 1
	v_add3_u32 v32, v32, v133, s1
	global_store_short_d16_hi v[158:159], v32, off offset:128
	v_mul_f32_e32 v32, 0xbfb8aa3b, v127
	v_exp_f32_e32 v32, v32
	v_or_b32_e32 v160, 25, v132
	v_ashrrev_i32_e32 v161, 31, v160
	v_lshlrev_b64 v[160:161], 12, v[160:161]
	v_add_f32_e32 v32, 1.0, v32
	v_div_scale_f32 v133, s[2:3], v32, v32, v127
	v_rcp_f32_e32 v162, v133
	v_lshl_add_u64 v[160:161], v[130:131], 0, v[160:161]
	v_fma_f32 v163, -v133, v162, 1.0
	v_fmac_f32_e32 v162, v163, v162
	v_div_scale_f32 v163, vcc, v127, v32, v127
	v_mul_f32_e32 v164, v163, v162
	v_fma_f32 v165, -v133, v164, v163
	v_fmac_f32_e32 v164, v165, v162
	v_fma_f32 v133, -v133, v164, v163
	v_div_fmas_f32 v133, v133, v162, v164
	v_div_fixup_f32 v32, v133, v32, v127
	v_bfe_u32 v133, v32, 16, 1
	v_add3_u32 v32, v32, v133, s1
	global_store_short_d16_hi v[160:161], v32, off
	v_mul_f32_e32 v32, 0xbfb8aa3b, v111
	v_exp_f32_e32 v32, v32
	s_nop 0
	v_add_f32_e32 v32, 1.0, v32
	v_div_scale_f32 v133, s[2:3], v32, v32, v111
	v_rcp_f32_e32 v162, v133
	s_nop 0
	v_fma_f32 v163, -v133, v162, 1.0
	v_fmac_f32_e32 v162, v163, v162
	v_div_scale_f32 v163, vcc, v111, v32, v111
	v_mul_f32_e32 v164, v163, v162
	v_fma_f32 v165, -v133, v164, v163
	v_fmac_f32_e32 v164, v165, v162
	v_fma_f32 v133, -v133, v164, v163
	v_div_fmas_f32 v133, v133, v162, v164
	v_div_fixup_f32 v32, v133, v32, v111
	v_bfe_u32 v133, v32, 16, 1
	v_add3_u32 v32, v32, v133, s1
	global_store_short_d16_hi v[160:161], v32, off offset:128
	v_mul_f32_e32 v32, 0xbfb8aa3b, v128
	v_exp_f32_e32 v32, v32
	v_or_b32_e32 v162, 26, v132
	v_ashrrev_i32_e32 v163, 31, v162
	v_lshlrev_b64 v[162:163], 12, v[162:163]
	v_add_f32_e32 v32, 1.0, v32
	v_div_scale_f32 v133, s[2:3], v32, v32, v128
	v_rcp_f32_e32 v164, v133
	v_lshl_add_u64 v[162:163], v[130:131], 0, v[162:163]
	v_fma_f32 v165, -v133, v164, 1.0
	v_fmac_f32_e32 v164, v165, v164
	v_div_scale_f32 v165, vcc, v128, v32, v128
	v_mul_f32_e32 v166, v165, v164
	v_fma_f32 v167, -v133, v166, v165
	v_fmac_f32_e32 v166, v167, v164
	v_fma_f32 v133, -v133, v166, v165
	v_div_fmas_f32 v133, v133, v164, v166
	v_div_fixup_f32 v32, v133, v32, v128
	v_bfe_u32 v133, v32, 16, 1
	v_add3_u32 v32, v32, v133, s1
	global_store_short_d16_hi v[162:163], v32, off
	v_mul_f32_e32 v32, 0xbfb8aa3b, v112
	v_exp_f32_e32 v32, v32
	s_nop 0
	v_add_f32_e32 v32, 1.0, v32
	v_div_scale_f32 v133, s[2:3], v32, v32, v112
	v_rcp_f32_e32 v164, v133
	s_nop 0
	v_fma_f32 v165, -v133, v164, 1.0
	v_fmac_f32_e32 v164, v165, v164
	v_div_scale_f32 v165, vcc, v112, v32, v112
	v_mul_f32_e32 v166, v165, v164
	v_fma_f32 v167, -v133, v166, v165
	v_fmac_f32_e32 v166, v167, v164
	v_fma_f32 v133, -v133, v166, v165
	v_div_fmas_f32 v133, v133, v164, v166
	v_div_fixup_f32 v32, v133, v32, v112
	v_bfe_u32 v133, v32, 16, 1
	v_add3_u32 v32, v32, v133, s1
	global_store_short_d16_hi v[162:163], v32, off offset:128
	v_mul_f32_e32 v32, 0xbfb8aa3b, v129
	v_exp_f32_e32 v32, v32
	v_or_b32_e32 v164, 27, v132
	v_ashrrev_i32_e32 v165, 31, v164
	v_lshlrev_b64 v[164:165], 12, v[164:165]
	v_add_f32_e32 v32, 1.0, v32
	v_div_scale_f32 v133, s[2:3], v32, v32, v129
	v_rcp_f32_e32 v166, v133
	v_lshl_add_u64 v[164:165], v[130:131], 0, v[164:165]
	v_fma_f32 v167, -v133, v166, 1.0
	v_fmac_f32_e32 v166, v167, v166
	v_div_scale_f32 v167, vcc, v129, v32, v129
	v_mul_f32_e32 v168, v167, v166
	v_fma_f32 v169, -v133, v168, v167
	v_fmac_f32_e32 v168, v169, v166
	v_fma_f32 v133, -v133, v168, v167
	v_div_fmas_f32 v133, v133, v166, v168
	v_div_fixup_f32 v32, v133, v32, v129
	v_bfe_u32 v133, v32, 16, 1
	v_add3_u32 v32, v32, v133, s1
	global_store_short_d16_hi v[164:165], v32, off
	v_mul_f32_e32 v32, 0xbfb8aa3b, v113
	v_exp_f32_e32 v32, v32
	s_nop 0
	v_add_f32_e32 v32, 1.0, v32
	v_div_scale_f32 v133, s[2:3], v32, v32, v113
	v_rcp_f32_e32 v166, v133
	s_nop 0
	v_fma_f32 v167, -v133, v166, 1.0
	v_fmac_f32_e32 v166, v167, v166
	v_div_scale_f32 v167, vcc, v113, v32, v113
	v_mul_f32_e32 v168, v167, v166
	v_fma_f32 v169, -v133, v168, v167
	v_fmac_f32_e32 v168, v169, v166
	v_fma_f32 v133, -v133, v168, v167
	v_div_fmas_f32 v133, v133, v166, v168
	v_div_fixup_f32 v32, v133, v32, v113
	v_bfe_u32 v133, v32, 16, 1
	v_add3_u32 v32, v32, v133, s1
	global_store_short_d16_hi v[164:165], v32, off offset:128
	v_mul_f32_e32 v32, 0xbfb8aa3b, v82
	v_exp_f32_e32 v32, v32
	s_nop 0
	v_add_f32_e32 v32, 1.0, v32
	v_div_scale_f32 v133, s[2:3], v32, v32, v82
	v_rcp_f32_e32 v166, v133
	s_nop 0
	v_fma_f32 v167, -v133, v166, 1.0
	v_fmac_f32_e32 v166, v167, v166
	v_div_scale_f32 v167, vcc, v82, v32, v82
	v_mul_f32_e32 v168, v167, v166
	v_fma_f32 v169, -v133, v168, v167
	v_fmac_f32_e32 v168, v169, v166
	v_fma_f32 v133, -v133, v168, v167
	v_div_fmas_f32 v133, v133, v166, v168
	v_div_fixup_f32 v32, v133, v32, v82
	v_bfe_u32 v133, v32, 16, 1
	v_add3_u32 v32, v32, v133, s1
	global_store_short_d16_hi v[134:135], v32, off offset:64
	v_mul_f32_e32 v32, 0xbfb8aa3b, v66
	v_exp_f32_e32 v32, v32
	s_nop 0
	v_add_f32_e32 v32, 1.0, v32
	v_div_scale_f32 v133, s[2:3], v32, v32, v66
	v_rcp_f32_e32 v166, v133
	s_nop 0
	v_fma_f32 v167, -v133, v166, 1.0
	v_fmac_f32_e32 v166, v167, v166
	v_div_scale_f32 v167, vcc, v66, v32, v66
	v_mul_f32_e32 v168, v167, v166
	v_fma_f32 v169, -v133, v168, v167
	v_fmac_f32_e32 v168, v169, v166
	v_fma_f32 v133, -v133, v168, v167
	v_div_fmas_f32 v133, v133, v166, v168
	v_div_fixup_f32 v32, v133, v32, v66
	v_bfe_u32 v133, v32, 16, 1
	v_add3_u32 v32, v32, v133, s1
	global_store_short_d16_hi v[134:135], v32, off offset:192
	v_mul_f32_e32 v32, 0xbfb8aa3b, v83
	v_exp_f32_e32 v32, v32
	s_nop 0
	v_add_f32_e32 v32, 1.0, v32
	v_div_scale_f32 v133, s[2:3], v32, v32, v83
	v_rcp_f32_e32 v134, v133
	s_nop 0
	v_fma_f32 v135, -v133, v134, 1.0
	v_fmac_f32_e32 v134, v135, v134
	v_div_scale_f32 v135, vcc, v83, v32, v83
	v_mul_f32_e32 v166, v135, v134
	v_fma_f32 v167, -v133, v166, v135
	v_fmac_f32_e32 v166, v167, v134
	v_fma_f32 v133, -v133, v166, v135
	v_div_fmas_f32 v133, v133, v134, v166
	v_div_fixup_f32 v32, v133, v32, v83
	v_bfe_u32 v133, v32, 16, 1
	v_add3_u32 v32, v32, v133, s1
	global_store_short_d16_hi v[136:137], v32, off offset:64
	v_mul_f32_e32 v32, 0xbfb8aa3b, v67
	v_exp_f32_e32 v32, v32
	s_nop 0
	v_add_f32_e32 v32, 1.0, v32
	v_div_scale_f32 v133, s[2:3], v32, v32, v67
	v_rcp_f32_e32 v134, v133
	s_nop 0
	v_fma_f32 v135, -v133, v134, 1.0
	v_fmac_f32_e32 v134, v135, v134
	v_div_scale_f32 v135, vcc, v67, v32, v67
	v_mul_f32_e32 v166, v135, v134
	v_fma_f32 v167, -v133, v166, v135
	v_fmac_f32_e32 v166, v167, v134
	v_fma_f32 v133, -v133, v166, v135
	v_div_fmas_f32 v133, v133, v134, v166
	v_div_fixup_f32 v32, v133, v32, v67
	v_bfe_u32 v133, v32, 16, 1
	v_add3_u32 v32, v32, v133, s1
	global_store_short_d16_hi v[136:137], v32, off offset:192
	v_mul_f32_e32 v32, 0xbfb8aa3b, v84
	v_exp_f32_e32 v32, v32
	s_nop 0
	v_add_f32_e32 v32, 1.0, v32
	v_div_scale_f32 v133, s[2:3], v32, v32, v84
	v_rcp_f32_e32 v134, v133
	s_nop 0
	v_fma_f32 v135, -v133, v134, 1.0
	v_fmac_f32_e32 v134, v135, v134
	v_div_scale_f32 v135, vcc, v84, v32, v84
	v_mul_f32_e32 v136, v135, v134
	v_fma_f32 v137, -v133, v136, v135
	v_fmac_f32_e32 v136, v137, v134
	v_fma_f32 v133, -v133, v136, v135
	v_div_fmas_f32 v133, v133, v134, v136
	v_div_fixup_f32 v32, v133, v32, v84
	v_bfe_u32 v133, v32, 16, 1
	v_add3_u32 v32, v32, v133, s1
	global_store_short_d16_hi v[138:139], v32, off offset:64
	v_mul_f32_e32 v32, 0xbfb8aa3b, v68
	v_exp_f32_e32 v32, v32
	s_nop 0
	v_add_f32_e32 v32, 1.0, v32
	v_div_scale_f32 v133, s[2:3], v32, v32, v68
	v_rcp_f32_e32 v134, v133
	s_nop 0
	v_fma_f32 v135, -v133, v134, 1.0
	v_fmac_f32_e32 v134, v135, v134
	v_div_scale_f32 v135, vcc, v68, v32, v68
	v_mul_f32_e32 v136, v135, v134
	v_fma_f32 v137, -v133, v136, v135
	v_fmac_f32_e32 v136, v137, v134
	v_fma_f32 v133, -v133, v136, v135
	v_div_fmas_f32 v133, v133, v134, v136
	v_div_fixup_f32 v32, v133, v32, v68
	v_bfe_u32 v133, v32, 16, 1
	v_add3_u32 v32, v32, v133, s1
	global_store_short_d16_hi v[138:139], v32, off offset:192
	v_mul_f32_e32 v32, 0xbfb8aa3b, v85
	v_exp_f32_e32 v32, v32
	s_nop 0
	v_add_f32_e32 v32, 1.0, v32
	v_div_scale_f32 v133, s[2:3], v32, v32, v85
	v_rcp_f32_e32 v134, v133
	s_nop 0
	v_fma_f32 v135, -v133, v134, 1.0
	v_fmac_f32_e32 v134, v135, v134
	v_div_scale_f32 v135, vcc, v85, v32, v85
	v_mul_f32_e32 v136, v135, v134
	v_fma_f32 v137, -v133, v136, v135
	v_fmac_f32_e32 v136, v137, v134
	v_fma_f32 v133, -v133, v136, v135
	v_div_fmas_f32 v133, v133, v134, v136
	v_div_fixup_f32 v32, v133, v32, v85
	v_bfe_u32 v133, v32, 16, 1
	v_add3_u32 v32, v32, v133, s1
	global_store_short_d16_hi v[140:141], v32, off offset:64
	v_mul_f32_e32 v32, 0xbfb8aa3b, v69
	v_exp_f32_e32 v32, v32
	s_nop 0
	v_add_f32_e32 v32, 1.0, v32
	v_div_scale_f32 v133, s[2:3], v32, v32, v69
	v_rcp_f32_e32 v134, v133
	s_nop 0
	v_fma_f32 v135, -v133, v134, 1.0
	v_fmac_f32_e32 v134, v135, v134
	v_div_scale_f32 v135, vcc, v69, v32, v69
	v_mul_f32_e32 v136, v135, v134
	v_fma_f32 v137, -v133, v136, v135
	v_fmac_f32_e32 v136, v137, v134
	v_fma_f32 v133, -v133, v136, v135
	v_div_fmas_f32 v133, v133, v134, v136
	v_div_fixup_f32 v32, v133, v32, v69
	v_bfe_u32 v133, v32, 16, 1
	v_add3_u32 v32, v32, v133, s1
	global_store_short_d16_hi v[140:141], v32, off offset:192
	v_mul_f32_e32 v32, 0xbfb8aa3b, v86
	v_exp_f32_e32 v32, v32
	s_nop 0
	v_add_f32_e32 v32, 1.0, v32
	v_div_scale_f32 v133, s[2:3], v32, v32, v86
	v_rcp_f32_e32 v134, v133
	s_nop 0
	v_fma_f32 v135, -v133, v134, 1.0
	v_fmac_f32_e32 v134, v135, v134
	v_div_scale_f32 v135, vcc, v86, v32, v86
	v_mul_f32_e32 v136, v135, v134
	v_fma_f32 v137, -v133, v136, v135
	v_fmac_f32_e32 v136, v137, v134
	v_fma_f32 v133, -v133, v136, v135
	v_div_fmas_f32 v133, v133, v134, v136
	v_div_fixup_f32 v32, v133, v32, v86
	v_bfe_u32 v133, v32, 16, 1
	v_add3_u32 v32, v32, v133, s1
	global_store_short_d16_hi v[142:143], v32, off offset:64
	v_mul_f32_e32 v32, 0xbfb8aa3b, v70
	v_exp_f32_e32 v32, v32
	s_nop 0
	v_add_f32_e32 v32, 1.0, v32
	v_div_scale_f32 v133, s[2:3], v32, v32, v70
	v_rcp_f32_e32 v134, v133
	s_nop 0
	v_fma_f32 v135, -v133, v134, 1.0
	v_fmac_f32_e32 v134, v135, v134
	v_div_scale_f32 v135, vcc, v70, v32, v70
	v_mul_f32_e32 v136, v135, v134
	v_fma_f32 v137, -v133, v136, v135
	v_fmac_f32_e32 v136, v137, v134
	v_fma_f32 v133, -v133, v136, v135
	v_div_fmas_f32 v133, v133, v134, v136
	v_div_fixup_f32 v32, v133, v32, v70
	v_bfe_u32 v133, v32, 16, 1
	v_add3_u32 v32, v32, v133, s1
	global_store_short_d16_hi v[142:143], v32, off offset:192
	v_mul_f32_e32 v32, 0xbfb8aa3b, v87
	v_exp_f32_e32 v32, v32
	s_nop 0
	v_add_f32_e32 v32, 1.0, v32
	v_div_scale_f32 v133, s[2:3], v32, v32, v87
	v_rcp_f32_e32 v134, v133
	s_nop 0
	v_fma_f32 v135, -v133, v134, 1.0
	v_fmac_f32_e32 v134, v135, v134
	v_div_scale_f32 v135, vcc, v87, v32, v87
	v_mul_f32_e32 v136, v135, v134
	v_fma_f32 v137, -v133, v136, v135
	v_fmac_f32_e32 v136, v137, v134
	v_fma_f32 v133, -v133, v136, v135
	v_div_fmas_f32 v133, v133, v134, v136
	v_div_fixup_f32 v32, v133, v32, v87
	v_bfe_u32 v133, v32, 16, 1
	v_add3_u32 v32, v32, v133, s1
	global_store_short_d16_hi v[144:145], v32, off offset:64
	v_mul_f32_e32 v32, 0xbfb8aa3b, v71
	v_exp_f32_e32 v32, v32
	s_nop 0
	v_add_f32_e32 v32, 1.0, v32
	v_div_scale_f32 v133, s[2:3], v32, v32, v71
	v_rcp_f32_e32 v134, v133
	s_nop 0
	v_fma_f32 v135, -v133, v134, 1.0
	v_fmac_f32_e32 v134, v135, v134
	v_div_scale_f32 v135, vcc, v71, v32, v71
	v_mul_f32_e32 v136, v135, v134
	v_fma_f32 v137, -v133, v136, v135
	v_fmac_f32_e32 v136, v137, v134
	v_fma_f32 v133, -v133, v136, v135
	v_div_fmas_f32 v133, v133, v134, v136
	v_div_fixup_f32 v32, v133, v32, v71
	v_bfe_u32 v133, v32, 16, 1
	v_add3_u32 v32, v32, v133, s1
	global_store_short_d16_hi v[144:145], v32, off offset:192
	v_mul_f32_e32 v32, 0xbfb8aa3b, v88
	v_exp_f32_e32 v32, v32
	s_nop 0
	v_add_f32_e32 v32, 1.0, v32
	v_div_scale_f32 v133, s[2:3], v32, v32, v88
	v_rcp_f32_e32 v134, v133
	s_nop 0
	v_fma_f32 v135, -v133, v134, 1.0
	v_fmac_f32_e32 v134, v135, v134
	v_div_scale_f32 v135, vcc, v88, v32, v88
	v_mul_f32_e32 v136, v135, v134
	v_fma_f32 v137, -v133, v136, v135
	v_fmac_f32_e32 v136, v137, v134
	v_fma_f32 v133, -v133, v136, v135
	v_div_fmas_f32 v133, v133, v134, v136
	v_div_fixup_f32 v32, v133, v32, v88
	v_bfe_u32 v133, v32, 16, 1
	v_add3_u32 v32, v32, v133, s1
	global_store_short_d16_hi v[146:147], v32, off offset:64
	v_mul_f32_e32 v32, 0xbfb8aa3b, v72
	v_exp_f32_e32 v32, v32
	s_nop 0
	v_add_f32_e32 v32, 1.0, v32
	v_div_scale_f32 v133, s[2:3], v32, v32, v72
	v_rcp_f32_e32 v134, v133
	s_nop 0
	v_fma_f32 v135, -v133, v134, 1.0
	v_fmac_f32_e32 v134, v135, v134
	v_div_scale_f32 v135, vcc, v72, v32, v72
	v_mul_f32_e32 v136, v135, v134
	v_fma_f32 v137, -v133, v136, v135
	v_fmac_f32_e32 v136, v137, v134
	v_fma_f32 v133, -v133, v136, v135
	v_div_fmas_f32 v133, v133, v134, v136
	v_div_fixup_f32 v32, v133, v32, v72
	v_bfe_u32 v133, v32, 16, 1
	v_add3_u32 v32, v32, v133, s1
	global_store_short_d16_hi v[146:147], v32, off offset:192
	v_mul_f32_e32 v32, 0xbfb8aa3b, v89
	v_exp_f32_e32 v32, v32
	s_nop 0
	v_add_f32_e32 v32, 1.0, v32
	v_div_scale_f32 v133, s[2:3], v32, v32, v89
	v_rcp_f32_e32 v134, v133
	s_nop 0
	v_fma_f32 v135, -v133, v134, 1.0
	v_fmac_f32_e32 v134, v135, v134
	v_div_scale_f32 v135, vcc, v89, v32, v89
	v_mul_f32_e32 v136, v135, v134
	v_fma_f32 v137, -v133, v136, v135
	v_fmac_f32_e32 v136, v137, v134
	v_fma_f32 v133, -v133, v136, v135
	v_div_fmas_f32 v133, v133, v134, v136
	v_div_fixup_f32 v32, v133, v32, v89
	v_bfe_u32 v133, v32, 16, 1
	v_add3_u32 v32, v32, v133, s1
	global_store_short_d16_hi v[148:149], v32, off offset:64
	v_mul_f32_e32 v32, 0xbfb8aa3b, v73
	v_exp_f32_e32 v32, v32
	s_nop 0
	v_add_f32_e32 v32, 1.0, v32
	v_div_scale_f32 v133, s[2:3], v32, v32, v73
	v_rcp_f32_e32 v134, v133
	s_nop 0
	v_fma_f32 v135, -v133, v134, 1.0
	v_fmac_f32_e32 v134, v135, v134
	v_div_scale_f32 v135, vcc, v73, v32, v73
	v_mul_f32_e32 v136, v135, v134
	v_fma_f32 v137, -v133, v136, v135
	v_fmac_f32_e32 v136, v137, v134
	v_fma_f32 v133, -v133, v136, v135
	v_div_fmas_f32 v133, v133, v134, v136
	v_div_fixup_f32 v32, v133, v32, v73
	v_bfe_u32 v133, v32, 16, 1
	v_add3_u32 v32, v32, v133, s1
	global_store_short_d16_hi v[148:149], v32, off offset:192
	v_mul_f32_e32 v32, 0xbfb8aa3b, v90
	v_exp_f32_e32 v32, v32
	s_nop 0
	v_add_f32_e32 v32, 1.0, v32
	v_div_scale_f32 v133, s[2:3], v32, v32, v90
	v_rcp_f32_e32 v134, v133
	s_nop 0
	v_fma_f32 v135, -v133, v134, 1.0
	v_fmac_f32_e32 v134, v135, v134
	v_div_scale_f32 v135, vcc, v90, v32, v90
	v_mul_f32_e32 v136, v135, v134
	v_fma_f32 v137, -v133, v136, v135
	v_fmac_f32_e32 v136, v137, v134
	v_fma_f32 v133, -v133, v136, v135
	v_div_fmas_f32 v133, v133, v134, v136
	v_div_fixup_f32 v32, v133, v32, v90
	v_bfe_u32 v133, v32, 16, 1
	v_add3_u32 v32, v32, v133, s1
	global_store_short_d16_hi v[150:151], v32, off offset:64
	v_mul_f32_e32 v32, 0xbfb8aa3b, v74
	v_exp_f32_e32 v32, v32
	s_nop 0
	v_add_f32_e32 v32, 1.0, v32
	v_div_scale_f32 v133, s[2:3], v32, v32, v74
	v_rcp_f32_e32 v134, v133
	s_nop 0
	v_fma_f32 v135, -v133, v134, 1.0
	v_fmac_f32_e32 v134, v135, v134
	v_div_scale_f32 v135, vcc, v74, v32, v74
	v_mul_f32_e32 v136, v135, v134
	v_fma_f32 v137, -v133, v136, v135
	v_fmac_f32_e32 v136, v137, v134
	v_fma_f32 v133, -v133, v136, v135
	v_div_fmas_f32 v133, v133, v134, v136
	v_div_fixup_f32 v32, v133, v32, v74
	v_bfe_u32 v133, v32, 16, 1
	v_add3_u32 v32, v32, v133, s1
	global_store_short_d16_hi v[150:151], v32, off offset:192
	v_mul_f32_e32 v32, 0xbfb8aa3b, v91
	v_exp_f32_e32 v32, v32
	s_nop 0
	v_add_f32_e32 v32, 1.0, v32
	v_div_scale_f32 v133, s[2:3], v32, v32, v91
	v_rcp_f32_e32 v134, v133
	s_nop 0
	v_fma_f32 v135, -v133, v134, 1.0
	v_fmac_f32_e32 v134, v135, v134
	v_div_scale_f32 v135, vcc, v91, v32, v91
	v_mul_f32_e32 v136, v135, v134
	v_fma_f32 v137, -v133, v136, v135
	v_fmac_f32_e32 v136, v137, v134
	v_fma_f32 v133, -v133, v136, v135
	v_div_fmas_f32 v133, v133, v134, v136
	v_div_fixup_f32 v32, v133, v32, v91
	v_bfe_u32 v133, v32, 16, 1
	v_add3_u32 v32, v32, v133, s1
	global_store_short_d16_hi v[152:153], v32, off offset:64
	v_mul_f32_e32 v32, 0xbfb8aa3b, v75
	v_exp_f32_e32 v32, v32
	s_nop 0
	v_add_f32_e32 v32, 1.0, v32
	v_div_scale_f32 v133, s[2:3], v32, v32, v75
	v_rcp_f32_e32 v134, v133
	s_nop 0
	v_fma_f32 v135, -v133, v134, 1.0
	v_fmac_f32_e32 v134, v135, v134
	v_div_scale_f32 v135, vcc, v75, v32, v75
	v_mul_f32_e32 v136, v135, v134
	v_fma_f32 v137, -v133, v136, v135
	v_fmac_f32_e32 v136, v137, v134
	v_fma_f32 v133, -v133, v136, v135
	v_div_fmas_f32 v133, v133, v134, v136
	v_div_fixup_f32 v32, v133, v32, v75
	v_bfe_u32 v133, v32, 16, 1
	v_add3_u32 v32, v32, v133, s1
	global_store_short_d16_hi v[152:153], v32, off offset:192
	v_mul_f32_e32 v32, 0xbfb8aa3b, v92
	v_exp_f32_e32 v32, v32
	s_nop 0
	v_add_f32_e32 v32, 1.0, v32
	v_div_scale_f32 v133, s[2:3], v32, v32, v92
	v_rcp_f32_e32 v134, v133
	s_nop 0
	v_fma_f32 v135, -v133, v134, 1.0
	v_fmac_f32_e32 v134, v135, v134
	v_div_scale_f32 v135, vcc, v92, v32, v92
	v_mul_f32_e32 v136, v135, v134
	v_fma_f32 v137, -v133, v136, v135
	v_fmac_f32_e32 v136, v137, v134
	v_fma_f32 v133, -v133, v136, v135
	v_div_fmas_f32 v133, v133, v134, v136
	v_div_fixup_f32 v32, v133, v32, v92
	v_bfe_u32 v133, v32, 16, 1
	v_add3_u32 v32, v32, v133, s1
	global_store_short_d16_hi v[154:155], v32, off offset:64
	v_mul_f32_e32 v32, 0xbfb8aa3b, v76
	v_exp_f32_e32 v32, v32
	s_nop 0
	v_add_f32_e32 v32, 1.0, v32
	v_div_scale_f32 v133, s[2:3], v32, v32, v76
	v_rcp_f32_e32 v134, v133
	s_nop 0
	v_fma_f32 v135, -v133, v134, 1.0
	v_fmac_f32_e32 v134, v135, v134
	v_div_scale_f32 v135, vcc, v76, v32, v76
	v_mul_f32_e32 v136, v135, v134
	v_fma_f32 v137, -v133, v136, v135
	v_fmac_f32_e32 v136, v137, v134
	v_fma_f32 v133, -v133, v136, v135
	v_div_fmas_f32 v133, v133, v134, v136
	v_div_fixup_f32 v32, v133, v32, v76
	v_bfe_u32 v133, v32, 16, 1
	v_add3_u32 v32, v32, v133, s1
	global_store_short_d16_hi v[154:155], v32, off offset:192
	v_mul_f32_e32 v32, 0xbfb8aa3b, v93
	v_exp_f32_e32 v32, v32
	s_nop 0
	v_add_f32_e32 v32, 1.0, v32
	v_div_scale_f32 v133, s[2:3], v32, v32, v93
	v_rcp_f32_e32 v134, v133
	s_nop 0
	v_fma_f32 v135, -v133, v134, 1.0
	v_fmac_f32_e32 v134, v135, v134
	v_div_scale_f32 v135, vcc, v93, v32, v93
	v_mul_f32_e32 v136, v135, v134
	v_fma_f32 v137, -v133, v136, v135
	v_fmac_f32_e32 v136, v137, v134
	v_fma_f32 v133, -v133, v136, v135
	v_div_fmas_f32 v133, v133, v134, v136
	v_div_fixup_f32 v32, v133, v32, v93
	v_bfe_u32 v133, v32, 16, 1
	v_add3_u32 v32, v32, v133, s1
	global_store_short_d16_hi v[156:157], v32, off offset:64
	v_mul_f32_e32 v32, 0xbfb8aa3b, v77
	v_exp_f32_e32 v32, v32
	s_nop 0
	v_add_f32_e32 v32, 1.0, v32
	v_div_scale_f32 v133, s[2:3], v32, v32, v77
	v_rcp_f32_e32 v134, v133
	s_nop 0
	v_fma_f32 v135, -v133, v134, 1.0
	v_fmac_f32_e32 v134, v135, v134
	v_div_scale_f32 v135, vcc, v77, v32, v77
	v_mul_f32_e32 v136, v135, v134
	v_fma_f32 v137, -v133, v136, v135
	v_fmac_f32_e32 v136, v137, v134
	v_fma_f32 v133, -v133, v136, v135
	v_div_fmas_f32 v133, v133, v134, v136
	v_div_fixup_f32 v32, v133, v32, v77
	v_bfe_u32 v133, v32, 16, 1
	v_add3_u32 v32, v32, v133, s1
	global_store_short_d16_hi v[156:157], v32, off offset:192
	v_mul_f32_e32 v32, 0xbfb8aa3b, v94
	v_exp_f32_e32 v32, v32
	s_nop 0
	v_add_f32_e32 v32, 1.0, v32
	v_div_scale_f32 v133, s[2:3], v32, v32, v94
	v_rcp_f32_e32 v134, v133
	s_nop 0
	v_fma_f32 v135, -v133, v134, 1.0
	v_fmac_f32_e32 v134, v135, v134
	v_div_scale_f32 v135, vcc, v94, v32, v94
	v_mul_f32_e32 v136, v135, v134
	v_fma_f32 v137, -v133, v136, v135
	v_fmac_f32_e32 v136, v137, v134
	v_fma_f32 v133, -v133, v136, v135
	v_div_fmas_f32 v133, v133, v134, v136
	v_div_fixup_f32 v32, v133, v32, v94
	v_bfe_u32 v133, v32, 16, 1
	v_add3_u32 v32, v32, v133, s1
	global_store_short_d16_hi v[158:159], v32, off offset:64
	v_mul_f32_e32 v32, 0xbfb8aa3b, v78
	v_exp_f32_e32 v32, v32
	s_nop 0
	v_add_f32_e32 v32, 1.0, v32
	v_div_scale_f32 v133, s[2:3], v32, v32, v78
	v_rcp_f32_e32 v134, v133
	s_nop 0
	v_fma_f32 v135, -v133, v134, 1.0
	v_fmac_f32_e32 v134, v135, v134
	v_div_scale_f32 v135, vcc, v78, v32, v78
	v_mul_f32_e32 v136, v135, v134
	v_fma_f32 v137, -v133, v136, v135
	v_fmac_f32_e32 v136, v137, v134
	v_fma_f32 v133, -v133, v136, v135
	v_div_fmas_f32 v133, v133, v134, v136
	v_div_fixup_f32 v32, v133, v32, v78
	v_bfe_u32 v133, v32, 16, 1
	v_add3_u32 v32, v32, v133, s1
	global_store_short_d16_hi v[158:159], v32, off offset:192
	v_mul_f32_e32 v32, 0xbfb8aa3b, v95
	v_exp_f32_e32 v32, v32
	s_nop 0
	v_add_f32_e32 v32, 1.0, v32
	v_div_scale_f32 v133, s[2:3], v32, v32, v95
	v_rcp_f32_e32 v134, v133
	s_nop 0
	v_fma_f32 v135, -v133, v134, 1.0
	v_fmac_f32_e32 v134, v135, v134
	v_div_scale_f32 v135, vcc, v95, v32, v95
	v_mul_f32_e32 v136, v135, v134
	v_fma_f32 v137, -v133, v136, v135
	v_fmac_f32_e32 v136, v137, v134
	v_fma_f32 v133, -v133, v136, v135
	v_div_fmas_f32 v133, v133, v134, v136
	v_div_fixup_f32 v32, v133, v32, v95
	v_bfe_u32 v133, v32, 16, 1
	v_add3_u32 v32, v32, v133, s1
	global_store_short_d16_hi v[160:161], v32, off offset:64
	v_mul_f32_e32 v32, 0xbfb8aa3b, v79
	v_exp_f32_e32 v32, v32
	s_nop 0
	v_add_f32_e32 v32, 1.0, v32
	v_div_scale_f32 v133, s[2:3], v32, v32, v79
	v_rcp_f32_e32 v134, v133
	s_nop 0
	v_fma_f32 v135, -v133, v134, 1.0
	v_fmac_f32_e32 v134, v135, v134
	v_div_scale_f32 v135, vcc, v79, v32, v79
	v_mul_f32_e32 v136, v135, v134
	v_fma_f32 v137, -v133, v136, v135
	v_fmac_f32_e32 v136, v137, v134
	v_fma_f32 v133, -v133, v136, v135
	v_div_fmas_f32 v133, v133, v134, v136
	v_div_fixup_f32 v32, v133, v32, v79
	v_bfe_u32 v133, v32, 16, 1
	v_add3_u32 v32, v32, v133, s1
	global_store_short_d16_hi v[160:161], v32, off offset:192
	v_mul_f32_e32 v32, 0xbfb8aa3b, v96
	v_exp_f32_e32 v32, v32
	s_nop 0
	v_add_f32_e32 v32, 1.0, v32
	v_div_scale_f32 v133, s[2:3], v32, v32, v96
	v_rcp_f32_e32 v134, v133
	s_nop 0
	v_fma_f32 v135, -v133, v134, 1.0
	v_fmac_f32_e32 v134, v135, v134
	v_div_scale_f32 v135, vcc, v96, v32, v96
	v_mul_f32_e32 v136, v135, v134
	v_fma_f32 v137, -v133, v136, v135
	v_fmac_f32_e32 v136, v137, v134
	v_fma_f32 v133, -v133, v136, v135
	v_div_fmas_f32 v133, v133, v134, v136
	v_div_fixup_f32 v32, v133, v32, v96
	v_bfe_u32 v133, v32, 16, 1
	v_add3_u32 v32, v32, v133, s1
	global_store_short_d16_hi v[162:163], v32, off offset:64
	v_mul_f32_e32 v32, 0xbfb8aa3b, v80
	v_exp_f32_e32 v32, v32
	s_nop 0
	v_add_f32_e32 v32, 1.0, v32
	v_div_scale_f32 v133, s[2:3], v32, v32, v80
	v_rcp_f32_e32 v134, v133
	s_nop 0
	v_fma_f32 v135, -v133, v134, 1.0
	v_fmac_f32_e32 v134, v135, v134
	v_div_scale_f32 v135, vcc, v80, v32, v80
	v_mul_f32_e32 v136, v135, v134
	v_fma_f32 v137, -v133, v136, v135
	v_fmac_f32_e32 v136, v137, v134
	v_fma_f32 v133, -v133, v136, v135
	v_div_fmas_f32 v133, v133, v134, v136
	v_div_fixup_f32 v32, v133, v32, v80
	v_bfe_u32 v133, v32, 16, 1
	v_add3_u32 v32, v32, v133, s1
	global_store_short_d16_hi v[162:163], v32, off offset:192
	v_mul_f32_e32 v32, 0xbfb8aa3b, v97
	v_exp_f32_e32 v32, v32
	s_nop 0
	v_add_f32_e32 v32, 1.0, v32
	v_div_scale_f32 v133, s[2:3], v32, v32, v97
	v_rcp_f32_e32 v134, v133
	s_nop 0
	v_fma_f32 v135, -v133, v134, 1.0
	v_fmac_f32_e32 v134, v135, v134
	v_div_scale_f32 v135, vcc, v97, v32, v97
	v_mul_f32_e32 v136, v135, v134
	v_fma_f32 v137, -v133, v136, v135
	v_fmac_f32_e32 v136, v137, v134
	v_fma_f32 v133, -v133, v136, v135
	v_div_fmas_f32 v133, v133, v134, v136
	v_div_fixup_f32 v32, v133, v32, v97
	v_bfe_u32 v133, v32, 16, 1
	v_add3_u32 v32, v32, v133, s1
	global_store_short_d16_hi v[164:165], v32, off offset:64
	v_mul_f32_e32 v32, 0xbfb8aa3b, v81
	v_exp_f32_e32 v32, v32
	s_nop 0
	v_add_f32_e32 v32, 1.0, v32
	v_div_scale_f32 v133, s[2:3], v32, v32, v81
	v_rcp_f32_e32 v134, v133
	s_nop 0
	v_fma_f32 v135, -v133, v134, 1.0
	v_fmac_f32_e32 v134, v135, v134
	v_div_scale_f32 v135, vcc, v81, v32, v81
	v_mul_f32_e32 v136, v135, v134
	v_fma_f32 v137, -v133, v136, v135
	v_fmac_f32_e32 v136, v137, v134
	v_fma_f32 v133, -v133, v136, v135
	v_div_fmas_f32 v133, v133, v134, v136
	v_div_fixup_f32 v32, v133, v32, v81
	v_bfe_u32 v133, v32, 16, 1
	v_add3_u32 v32, v32, v133, s1
	global_store_short_d16_hi v[164:165], v32, off offset:192
	v_mul_f32_e32 v32, 0xbfb8aa3b, v50
	v_exp_f32_e32 v32, v32
	v_or_b32_e32 v134, 32, v132
	v_ashrrev_i32_e32 v135, 31, v134
	v_lshlrev_b64 v[134:135], 12, v[134:135]
	v_add_f32_e32 v32, 1.0, v32
	v_div_scale_f32 v133, s[2:3], v32, v32, v50
	v_rcp_f32_e32 v136, v133
	v_lshl_add_u64 v[134:135], v[130:131], 0, v[134:135]
	v_fma_f32 v137, -v133, v136, 1.0
	v_fmac_f32_e32 v136, v137, v136
	v_div_scale_f32 v137, vcc, v50, v32, v50
	v_mul_f32_e32 v138, v137, v136
	v_fma_f32 v139, -v133, v138, v137
	v_fmac_f32_e32 v138, v139, v136
	v_fma_f32 v133, -v133, v138, v137
	v_div_fmas_f32 v133, v133, v136, v138
	v_div_fixup_f32 v32, v133, v32, v50
	v_bfe_u32 v133, v32, 16, 1
	v_add3_u32 v32, v32, v133, s1
	global_store_short_d16_hi v[134:135], v32, off
	v_mul_f32_e32 v32, 0xbfb8aa3b, v34
	v_exp_f32_e32 v32, v32
	s_nop 0
	v_add_f32_e32 v32, 1.0, v32
	v_div_scale_f32 v133, s[2:3], v32, v32, v34
	v_rcp_f32_e32 v136, v133
	s_nop 0
	v_fma_f32 v137, -v133, v136, 1.0
	v_fmac_f32_e32 v136, v137, v136
	v_div_scale_f32 v137, vcc, v34, v32, v34
	v_mul_f32_e32 v138, v137, v136
	v_fma_f32 v139, -v133, v138, v137
	v_fmac_f32_e32 v138, v139, v136
	v_fma_f32 v133, -v133, v138, v137
	v_div_fmas_f32 v133, v133, v136, v138
	v_div_fixup_f32 v32, v133, v32, v34
	v_bfe_u32 v133, v32, 16, 1
	v_add3_u32 v32, v32, v133, s1
	global_store_short_d16_hi v[134:135], v32, off offset:128
	v_mul_f32_e32 v32, 0xbfb8aa3b, v51
	v_exp_f32_e32 v32, v32
	v_or_b32_e32 v136, 33, v132
	v_ashrrev_i32_e32 v137, 31, v136
	v_lshlrev_b64 v[136:137], 12, v[136:137]
	v_add_f32_e32 v32, 1.0, v32
	v_div_scale_f32 v133, s[2:3], v32, v32, v51
	v_rcp_f32_e32 v138, v133
	v_lshl_add_u64 v[136:137], v[130:131], 0, v[136:137]
	v_fma_f32 v139, -v133, v138, 1.0
	v_fmac_f32_e32 v138, v139, v138
	v_div_scale_f32 v139, vcc, v51, v32, v51
	v_mul_f32_e32 v140, v139, v138
	v_fma_f32 v141, -v133, v140, v139
	v_fmac_f32_e32 v140, v141, v138
	v_fma_f32 v133, -v133, v140, v139
	v_div_fmas_f32 v133, v133, v138, v140
	v_div_fixup_f32 v32, v133, v32, v51
	v_bfe_u32 v133, v32, 16, 1
	v_add3_u32 v32, v32, v133, s1
	global_store_short_d16_hi v[136:137], v32, off
	v_mul_f32_e32 v32, 0xbfb8aa3b, v35
	v_exp_f32_e32 v32, v32
	s_nop 0
	v_add_f32_e32 v32, 1.0, v32
	v_div_scale_f32 v133, s[2:3], v32, v32, v35
	v_rcp_f32_e32 v138, v133
	s_nop 0
	v_fma_f32 v139, -v133, v138, 1.0
	v_fmac_f32_e32 v138, v139, v138
	v_div_scale_f32 v139, vcc, v35, v32, v35
	v_mul_f32_e32 v140, v139, v138
	v_fma_f32 v141, -v133, v140, v139
	v_fmac_f32_e32 v140, v141, v138
	v_fma_f32 v133, -v133, v140, v139
	v_div_fmas_f32 v133, v133, v138, v140
	v_div_fixup_f32 v32, v133, v32, v35
	v_bfe_u32 v133, v32, 16, 1
	v_add3_u32 v32, v32, v133, s1
	global_store_short_d16_hi v[136:137], v32, off offset:128
	v_mul_f32_e32 v32, 0xbfb8aa3b, v52
	v_exp_f32_e32 v32, v32
	v_or_b32_e32 v138, 34, v132
	v_ashrrev_i32_e32 v139, 31, v138
	v_lshlrev_b64 v[138:139], 12, v[138:139]
	v_add_f32_e32 v32, 1.0, v32
	v_div_scale_f32 v133, s[2:3], v32, v32, v52
	v_rcp_f32_e32 v140, v133
	v_lshl_add_u64 v[138:139], v[130:131], 0, v[138:139]
	v_fma_f32 v141, -v133, v140, 1.0
	v_fmac_f32_e32 v140, v141, v140
	v_div_scale_f32 v141, vcc, v52, v32, v52
	v_mul_f32_e32 v142, v141, v140
	v_fma_f32 v143, -v133, v142, v141
	v_fmac_f32_e32 v142, v143, v140
	v_fma_f32 v133, -v133, v142, v141
	v_div_fmas_f32 v133, v133, v140, v142
	v_div_fixup_f32 v32, v133, v32, v52
	v_bfe_u32 v133, v32, 16, 1
	v_add3_u32 v32, v32, v133, s1
	global_store_short_d16_hi v[138:139], v32, off
	v_mul_f32_e32 v32, 0xbfb8aa3b, v36
	v_exp_f32_e32 v32, v32
	s_nop 0
	v_add_f32_e32 v32, 1.0, v32
	v_div_scale_f32 v133, s[2:3], v32, v32, v36
	v_rcp_f32_e32 v140, v133
	s_nop 0
	v_fma_f32 v141, -v133, v140, 1.0
	v_fmac_f32_e32 v140, v141, v140
	v_div_scale_f32 v141, vcc, v36, v32, v36
	v_mul_f32_e32 v142, v141, v140
	v_fma_f32 v143, -v133, v142, v141
	v_fmac_f32_e32 v142, v143, v140
	v_fma_f32 v133, -v133, v142, v141
	v_div_fmas_f32 v133, v133, v140, v142
	v_div_fixup_f32 v32, v133, v32, v36
	v_bfe_u32 v133, v32, 16, 1
	v_add3_u32 v32, v32, v133, s1
	global_store_short_d16_hi v[138:139], v32, off offset:128
	v_mul_f32_e32 v32, 0xbfb8aa3b, v53
	v_exp_f32_e32 v32, v32
	v_or_b32_e32 v140, 35, v132
	v_ashrrev_i32_e32 v141, 31, v140
	v_lshlrev_b64 v[140:141], 12, v[140:141]
	v_add_f32_e32 v32, 1.0, v32
	v_div_scale_f32 v133, s[2:3], v32, v32, v53
	v_rcp_f32_e32 v142, v133
	v_lshl_add_u64 v[140:141], v[130:131], 0, v[140:141]
	v_fma_f32 v143, -v133, v142, 1.0
	v_fmac_f32_e32 v142, v143, v142
	v_div_scale_f32 v143, vcc, v53, v32, v53
	v_mul_f32_e32 v144, v143, v142
	v_fma_f32 v145, -v133, v144, v143
	v_fmac_f32_e32 v144, v145, v142
	v_fma_f32 v133, -v133, v144, v143
	v_div_fmas_f32 v133, v133, v142, v144
	v_div_fixup_f32 v32, v133, v32, v53
	v_bfe_u32 v133, v32, 16, 1
	v_add3_u32 v32, v32, v133, s1
	global_store_short_d16_hi v[140:141], v32, off
	v_mul_f32_e32 v32, 0xbfb8aa3b, v37
	v_exp_f32_e32 v32, v32
	s_nop 0
	v_add_f32_e32 v32, 1.0, v32
	v_div_scale_f32 v133, s[2:3], v32, v32, v37
	v_rcp_f32_e32 v142, v133
	s_nop 0
	v_fma_f32 v143, -v133, v142, 1.0
	v_fmac_f32_e32 v142, v143, v142
	v_div_scale_f32 v143, vcc, v37, v32, v37
	v_mul_f32_e32 v144, v143, v142
	v_fma_f32 v145, -v133, v144, v143
	v_fmac_f32_e32 v144, v145, v142
	v_fma_f32 v133, -v133, v144, v143
	v_div_fmas_f32 v133, v133, v142, v144
	v_div_fixup_f32 v32, v133, v32, v37
	v_bfe_u32 v133, v32, 16, 1
	v_add3_u32 v32, v32, v133, s1
	global_store_short_d16_hi v[140:141], v32, off offset:128
	v_mul_f32_e32 v32, 0xbfb8aa3b, v54
	v_exp_f32_e32 v32, v32
	v_or_b32_e32 v142, 40, v132
	v_ashrrev_i32_e32 v143, 31, v142
	v_lshlrev_b64 v[142:143], 12, v[142:143]
	v_add_f32_e32 v32, 1.0, v32
	v_div_scale_f32 v133, s[2:3], v32, v32, v54
	v_rcp_f32_e32 v144, v133
	v_lshl_add_u64 v[142:143], v[130:131], 0, v[142:143]
	v_fma_f32 v145, -v133, v144, 1.0
	v_fmac_f32_e32 v144, v145, v144
	v_div_scale_f32 v145, vcc, v54, v32, v54
	v_mul_f32_e32 v146, v145, v144
	v_fma_f32 v147, -v133, v146, v145
	v_fmac_f32_e32 v146, v147, v144
	v_fma_f32 v133, -v133, v146, v145
	v_div_fmas_f32 v133, v133, v144, v146
	v_div_fixup_f32 v32, v133, v32, v54
	v_bfe_u32 v133, v32, 16, 1
	v_add3_u32 v32, v32, v133, s1
	global_store_short_d16_hi v[142:143], v32, off
	v_mul_f32_e32 v32, 0xbfb8aa3b, v38
	v_exp_f32_e32 v32, v32
	s_nop 0
	v_add_f32_e32 v32, 1.0, v32
	v_div_scale_f32 v133, s[2:3], v32, v32, v38
	v_rcp_f32_e32 v144, v133
	s_nop 0
	v_fma_f32 v145, -v133, v144, 1.0
	v_fmac_f32_e32 v144, v145, v144
	v_div_scale_f32 v145, vcc, v38, v32, v38
	v_mul_f32_e32 v146, v145, v144
	v_fma_f32 v147, -v133, v146, v145
	v_fmac_f32_e32 v146, v147, v144
	v_fma_f32 v133, -v133, v146, v145
	v_div_fmas_f32 v133, v133, v144, v146
	v_div_fixup_f32 v32, v133, v32, v38
	v_bfe_u32 v133, v32, 16, 1
	v_add3_u32 v32, v32, v133, s1
	global_store_short_d16_hi v[142:143], v32, off offset:128
	v_mul_f32_e32 v32, 0xbfb8aa3b, v55
	v_exp_f32_e32 v32, v32
	v_or_b32_e32 v144, 41, v132
	v_ashrrev_i32_e32 v145, 31, v144
	v_lshlrev_b64 v[144:145], 12, v[144:145]
	v_add_f32_e32 v32, 1.0, v32
	v_div_scale_f32 v133, s[2:3], v32, v32, v55
	v_rcp_f32_e32 v146, v133
	v_lshl_add_u64 v[144:145], v[130:131], 0, v[144:145]
	v_fma_f32 v147, -v133, v146, 1.0
	v_fmac_f32_e32 v146, v147, v146
	v_div_scale_f32 v147, vcc, v55, v32, v55
	v_mul_f32_e32 v148, v147, v146
	v_fma_f32 v149, -v133, v148, v147
	v_fmac_f32_e32 v148, v149, v146
	v_fma_f32 v133, -v133, v148, v147
	v_div_fmas_f32 v133, v133, v146, v148
	v_div_fixup_f32 v32, v133, v32, v55
	v_bfe_u32 v133, v32, 16, 1
	v_add3_u32 v32, v32, v133, s1
	global_store_short_d16_hi v[144:145], v32, off
	v_mul_f32_e32 v32, 0xbfb8aa3b, v39
	v_exp_f32_e32 v32, v32
	s_nop 0
	v_add_f32_e32 v32, 1.0, v32
	v_div_scale_f32 v133, s[2:3], v32, v32, v39
	v_rcp_f32_e32 v146, v133
	s_nop 0
	v_fma_f32 v147, -v133, v146, 1.0
	v_fmac_f32_e32 v146, v147, v146
	v_div_scale_f32 v147, vcc, v39, v32, v39
	v_mul_f32_e32 v148, v147, v146
	v_fma_f32 v149, -v133, v148, v147
	v_fmac_f32_e32 v148, v149, v146
	v_fma_f32 v133, -v133, v148, v147
	v_div_fmas_f32 v133, v133, v146, v148
	v_div_fixup_f32 v32, v133, v32, v39
	v_bfe_u32 v133, v32, 16, 1
	v_add3_u32 v32, v32, v133, s1
	global_store_short_d16_hi v[144:145], v32, off offset:128
	v_mul_f32_e32 v32, 0xbfb8aa3b, v56
	v_exp_f32_e32 v32, v32
	v_or_b32_e32 v146, 42, v132
	v_ashrrev_i32_e32 v147, 31, v146
	v_lshlrev_b64 v[146:147], 12, v[146:147]
	v_add_f32_e32 v32, 1.0, v32
	v_div_scale_f32 v133, s[2:3], v32, v32, v56
	v_rcp_f32_e32 v148, v133
	v_lshl_add_u64 v[146:147], v[130:131], 0, v[146:147]
	v_fma_f32 v149, -v133, v148, 1.0
	v_fmac_f32_e32 v148, v149, v148
	v_div_scale_f32 v149, vcc, v56, v32, v56
	v_mul_f32_e32 v150, v149, v148
	v_fma_f32 v151, -v133, v150, v149
	v_fmac_f32_e32 v150, v151, v148
	v_fma_f32 v133, -v133, v150, v149
	v_div_fmas_f32 v133, v133, v148, v150
	v_div_fixup_f32 v32, v133, v32, v56
	v_bfe_u32 v133, v32, 16, 1
	v_add3_u32 v32, v32, v133, s1
	global_store_short_d16_hi v[146:147], v32, off
	v_mul_f32_e32 v32, 0xbfb8aa3b, v40
	v_exp_f32_e32 v32, v32
	s_nop 0
	v_add_f32_e32 v32, 1.0, v32
	v_div_scale_f32 v133, s[2:3], v32, v32, v40
	v_rcp_f32_e32 v148, v133
	s_nop 0
	v_fma_f32 v149, -v133, v148, 1.0
	v_fmac_f32_e32 v148, v149, v148
	v_div_scale_f32 v149, vcc, v40, v32, v40
	v_mul_f32_e32 v150, v149, v148
	v_fma_f32 v151, -v133, v150, v149
	v_fmac_f32_e32 v150, v151, v148
	v_fma_f32 v133, -v133, v150, v149
	v_div_fmas_f32 v133, v133, v148, v150
	v_div_fixup_f32 v32, v133, v32, v40
	v_bfe_u32 v133, v32, 16, 1
	v_add3_u32 v32, v32, v133, s1
	global_store_short_d16_hi v[146:147], v32, off offset:128
	v_mul_f32_e32 v32, 0xbfb8aa3b, v57
	v_exp_f32_e32 v32, v32
	v_or_b32_e32 v148, 43, v132
	v_ashrrev_i32_e32 v149, 31, v148
	v_lshlrev_b64 v[148:149], 12, v[148:149]
	v_add_f32_e32 v32, 1.0, v32
	v_div_scale_f32 v133, s[2:3], v32, v32, v57
	v_rcp_f32_e32 v150, v133
	v_lshl_add_u64 v[148:149], v[130:131], 0, v[148:149]
	v_fma_f32 v151, -v133, v150, 1.0
	v_fmac_f32_e32 v150, v151, v150
	v_div_scale_f32 v151, vcc, v57, v32, v57
	v_mul_f32_e32 v152, v151, v150
	v_fma_f32 v153, -v133, v152, v151
	v_fmac_f32_e32 v152, v153, v150
	v_fma_f32 v133, -v133, v152, v151
	v_div_fmas_f32 v133, v133, v150, v152
	v_div_fixup_f32 v32, v133, v32, v57
	v_bfe_u32 v133, v32, 16, 1
	v_add3_u32 v32, v32, v133, s1
	global_store_short_d16_hi v[148:149], v32, off
	v_mul_f32_e32 v32, 0xbfb8aa3b, v41
	v_exp_f32_e32 v32, v32
	s_nop 0
	v_add_f32_e32 v32, 1.0, v32
	v_div_scale_f32 v133, s[2:3], v32, v32, v41
	v_rcp_f32_e32 v150, v133
	s_nop 0
	v_fma_f32 v151, -v133, v150, 1.0
	v_fmac_f32_e32 v150, v151, v150
	v_div_scale_f32 v151, vcc, v41, v32, v41
	v_mul_f32_e32 v152, v151, v150
	v_fma_f32 v153, -v133, v152, v151
	v_fmac_f32_e32 v152, v153, v150
	v_fma_f32 v133, -v133, v152, v151
	v_div_fmas_f32 v133, v133, v150, v152
	v_div_fixup_f32 v32, v133, v32, v41
	v_bfe_u32 v133, v32, 16, 1
	v_add3_u32 v32, v32, v133, s1
	global_store_short_d16_hi v[148:149], v32, off offset:128
	v_mul_f32_e32 v32, 0xbfb8aa3b, v58
	v_exp_f32_e32 v32, v32
	v_or_b32_e32 v150, 48, v132
	v_ashrrev_i32_e32 v151, 31, v150
	v_lshlrev_b64 v[150:151], 12, v[150:151]
	v_add_f32_e32 v32, 1.0, v32
	v_div_scale_f32 v133, s[2:3], v32, v32, v58
	v_rcp_f32_e32 v152, v133
	v_lshl_add_u64 v[150:151], v[130:131], 0, v[150:151]
	v_fma_f32 v153, -v133, v152, 1.0
	v_fmac_f32_e32 v152, v153, v152
	v_div_scale_f32 v153, vcc, v58, v32, v58
	v_mul_f32_e32 v154, v153, v152
	v_fma_f32 v155, -v133, v154, v153
	v_fmac_f32_e32 v154, v155, v152
	v_fma_f32 v133, -v133, v154, v153
	v_div_fmas_f32 v133, v133, v152, v154
	v_div_fixup_f32 v32, v133, v32, v58
	v_bfe_u32 v133, v32, 16, 1
	v_add3_u32 v32, v32, v133, s1
	global_store_short_d16_hi v[150:151], v32, off
	v_mul_f32_e32 v32, 0xbfb8aa3b, v42
	v_exp_f32_e32 v32, v32
	s_nop 0
	v_add_f32_e32 v32, 1.0, v32
	v_div_scale_f32 v133, s[2:3], v32, v32, v42
	v_rcp_f32_e32 v152, v133
	s_nop 0
	v_fma_f32 v153, -v133, v152, 1.0
	v_fmac_f32_e32 v152, v153, v152
	v_div_scale_f32 v153, vcc, v42, v32, v42
	v_mul_f32_e32 v154, v153, v152
	v_fma_f32 v155, -v133, v154, v153
	v_fmac_f32_e32 v154, v155, v152
	v_fma_f32 v133, -v133, v154, v153
	v_div_fmas_f32 v133, v133, v152, v154
	v_div_fixup_f32 v32, v133, v32, v42
	v_bfe_u32 v133, v32, 16, 1
	v_add3_u32 v32, v32, v133, s1
	global_store_short_d16_hi v[150:151], v32, off offset:128
	v_mul_f32_e32 v32, 0xbfb8aa3b, v59
	v_exp_f32_e32 v32, v32
	v_or_b32_e32 v152, 49, v132
	v_ashrrev_i32_e32 v153, 31, v152
	v_lshlrev_b64 v[152:153], 12, v[152:153]
	v_add_f32_e32 v32, 1.0, v32
	v_div_scale_f32 v133, s[2:3], v32, v32, v59
	v_rcp_f32_e32 v154, v133
	v_lshl_add_u64 v[152:153], v[130:131], 0, v[152:153]
	v_fma_f32 v155, -v133, v154, 1.0
	v_fmac_f32_e32 v154, v155, v154
	v_div_scale_f32 v155, vcc, v59, v32, v59
	v_mul_f32_e32 v156, v155, v154
	v_fma_f32 v157, -v133, v156, v155
	v_fmac_f32_e32 v156, v157, v154
	v_fma_f32 v133, -v133, v156, v155
	v_div_fmas_f32 v133, v133, v154, v156
	v_div_fixup_f32 v32, v133, v32, v59
	v_bfe_u32 v133, v32, 16, 1
	v_add3_u32 v32, v32, v133, s1
	global_store_short_d16_hi v[152:153], v32, off
	v_mul_f32_e32 v32, 0xbfb8aa3b, v43
	v_exp_f32_e32 v32, v32
	s_nop 0
	v_add_f32_e32 v32, 1.0, v32
	v_div_scale_f32 v133, s[2:3], v32, v32, v43
	v_rcp_f32_e32 v154, v133
	s_nop 0
	v_fma_f32 v155, -v133, v154, 1.0
	v_fmac_f32_e32 v154, v155, v154
	v_div_scale_f32 v155, vcc, v43, v32, v43
	v_mul_f32_e32 v156, v155, v154
	v_fma_f32 v157, -v133, v156, v155
	v_fmac_f32_e32 v156, v157, v154
	v_fma_f32 v133, -v133, v156, v155
	v_div_fmas_f32 v133, v133, v154, v156
	v_div_fixup_f32 v32, v133, v32, v43
	v_bfe_u32 v133, v32, 16, 1
	v_add3_u32 v32, v32, v133, s1
	global_store_short_d16_hi v[152:153], v32, off offset:128
	v_mul_f32_e32 v32, 0xbfb8aa3b, v60
	v_exp_f32_e32 v32, v32
	v_or_b32_e32 v154, 50, v132
	v_ashrrev_i32_e32 v155, 31, v154
	v_lshlrev_b64 v[154:155], 12, v[154:155]
	v_add_f32_e32 v32, 1.0, v32
	v_div_scale_f32 v133, s[2:3], v32, v32, v60
	v_rcp_f32_e32 v156, v133
	v_lshl_add_u64 v[154:155], v[130:131], 0, v[154:155]
	v_fma_f32 v157, -v133, v156, 1.0
	v_fmac_f32_e32 v156, v157, v156
	v_div_scale_f32 v157, vcc, v60, v32, v60
	v_mul_f32_e32 v158, v157, v156
	v_fma_f32 v159, -v133, v158, v157
	v_fmac_f32_e32 v158, v159, v156
	v_fma_f32 v133, -v133, v158, v157
	v_div_fmas_f32 v133, v133, v156, v158
	v_div_fixup_f32 v32, v133, v32, v60
	v_bfe_u32 v133, v32, 16, 1
	v_add3_u32 v32, v32, v133, s1
	global_store_short_d16_hi v[154:155], v32, off
	v_mul_f32_e32 v32, 0xbfb8aa3b, v44
	v_exp_f32_e32 v32, v32
	s_nop 0
	v_add_f32_e32 v32, 1.0, v32
	v_div_scale_f32 v133, s[2:3], v32, v32, v44
	v_rcp_f32_e32 v156, v133
	s_nop 0
	v_fma_f32 v157, -v133, v156, 1.0
	v_fmac_f32_e32 v156, v157, v156
	v_div_scale_f32 v157, vcc, v44, v32, v44
	v_mul_f32_e32 v158, v157, v156
	v_fma_f32 v159, -v133, v158, v157
	v_fmac_f32_e32 v158, v159, v156
	v_fma_f32 v133, -v133, v158, v157
	v_div_fmas_f32 v133, v133, v156, v158
	v_div_fixup_f32 v32, v133, v32, v44
	v_bfe_u32 v133, v32, 16, 1
	v_add3_u32 v32, v32, v133, s1
	global_store_short_d16_hi v[154:155], v32, off offset:128
	v_mul_f32_e32 v32, 0xbfb8aa3b, v61
	v_exp_f32_e32 v32, v32
	v_or_b32_e32 v156, 51, v132
	v_ashrrev_i32_e32 v157, 31, v156
	v_lshlrev_b64 v[156:157], 12, v[156:157]
	v_add_f32_e32 v32, 1.0, v32
	v_div_scale_f32 v133, s[2:3], v32, v32, v61
	v_rcp_f32_e32 v158, v133
	v_lshl_add_u64 v[156:157], v[130:131], 0, v[156:157]
	v_fma_f32 v159, -v133, v158, 1.0
	v_fmac_f32_e32 v158, v159, v158
	v_div_scale_f32 v159, vcc, v61, v32, v61
	v_mul_f32_e32 v160, v159, v158
	v_fma_f32 v161, -v133, v160, v159
	v_fmac_f32_e32 v160, v161, v158
	v_fma_f32 v133, -v133, v160, v159
	v_div_fmas_f32 v133, v133, v158, v160
	v_div_fixup_f32 v32, v133, v32, v61
	v_bfe_u32 v133, v32, 16, 1
	v_add3_u32 v32, v32, v133, s1
	global_store_short_d16_hi v[156:157], v32, off
	v_mul_f32_e32 v32, 0xbfb8aa3b, v45
	v_exp_f32_e32 v32, v32
	s_nop 0
	v_add_f32_e32 v32, 1.0, v32
	v_div_scale_f32 v133, s[2:3], v32, v32, v45
	v_rcp_f32_e32 v158, v133
	s_nop 0
	v_fma_f32 v159, -v133, v158, 1.0
	v_fmac_f32_e32 v158, v159, v158
	v_div_scale_f32 v159, vcc, v45, v32, v45
	v_mul_f32_e32 v160, v159, v158
	v_fma_f32 v161, -v133, v160, v159
	v_fmac_f32_e32 v160, v161, v158
	v_fma_f32 v133, -v133, v160, v159
	v_div_fmas_f32 v133, v133, v158, v160
	v_div_fixup_f32 v32, v133, v32, v45
	v_bfe_u32 v133, v32, 16, 1
	v_add3_u32 v32, v32, v133, s1
	global_store_short_d16_hi v[156:157], v32, off offset:128
	v_mul_f32_e32 v32, 0xbfb8aa3b, v62
	v_exp_f32_e32 v32, v32
	v_or_b32_e32 v158, 56, v132
	v_ashrrev_i32_e32 v159, 31, v158
	v_lshlrev_b64 v[158:159], 12, v[158:159]
	v_add_f32_e32 v32, 1.0, v32
	v_div_scale_f32 v133, s[2:3], v32, v32, v62
	v_rcp_f32_e32 v160, v133
	v_lshl_add_u64 v[158:159], v[130:131], 0, v[158:159]
	v_fma_f32 v161, -v133, v160, 1.0
	v_fmac_f32_e32 v160, v161, v160
	v_div_scale_f32 v161, vcc, v62, v32, v62
	v_mul_f32_e32 v162, v161, v160
	v_fma_f32 v163, -v133, v162, v161
	v_fmac_f32_e32 v162, v163, v160
	v_fma_f32 v133, -v133, v162, v161
	v_div_fmas_f32 v133, v133, v160, v162
	v_div_fixup_f32 v32, v133, v32, v62
	v_bfe_u32 v133, v32, 16, 1
	v_add3_u32 v32, v32, v133, s1
	global_store_short_d16_hi v[158:159], v32, off
	v_mul_f32_e32 v32, 0xbfb8aa3b, v46
	v_exp_f32_e32 v32, v32
	s_nop 0
	v_add_f32_e32 v32, 1.0, v32
	v_div_scale_f32 v133, s[2:3], v32, v32, v46
	v_rcp_f32_e32 v160, v133
	s_nop 0
	v_fma_f32 v161, -v133, v160, 1.0
	v_fmac_f32_e32 v160, v161, v160
	v_div_scale_f32 v161, vcc, v46, v32, v46
	v_mul_f32_e32 v162, v161, v160
	v_fma_f32 v163, -v133, v162, v161
	v_fmac_f32_e32 v162, v163, v160
	v_fma_f32 v133, -v133, v162, v161
	v_div_fmas_f32 v133, v133, v160, v162
	v_div_fixup_f32 v32, v133, v32, v46
	v_bfe_u32 v133, v32, 16, 1
	v_add3_u32 v32, v32, v133, s1
	global_store_short_d16_hi v[158:159], v32, off offset:128
	v_mul_f32_e32 v32, 0xbfb8aa3b, v63
	v_exp_f32_e32 v32, v32
	v_or_b32_e32 v160, 57, v132
	v_ashrrev_i32_e32 v161, 31, v160
	v_lshlrev_b64 v[160:161], 12, v[160:161]
	v_add_f32_e32 v32, 1.0, v32
	v_div_scale_f32 v133, s[2:3], v32, v32, v63
	v_rcp_f32_e32 v162, v133
	v_lshl_add_u64 v[160:161], v[130:131], 0, v[160:161]
	v_fma_f32 v163, -v133, v162, 1.0
	v_fmac_f32_e32 v162, v163, v162
	v_div_scale_f32 v163, vcc, v63, v32, v63
	v_mul_f32_e32 v164, v163, v162
	v_fma_f32 v165, -v133, v164, v163
	v_fmac_f32_e32 v164, v165, v162
	v_fma_f32 v133, -v133, v164, v163
	v_div_fmas_f32 v133, v133, v162, v164
	v_div_fixup_f32 v32, v133, v32, v63
	v_bfe_u32 v133, v32, 16, 1
	v_add3_u32 v32, v32, v133, s1
	global_store_short_d16_hi v[160:161], v32, off
	v_mul_f32_e32 v32, 0xbfb8aa3b, v47
	v_exp_f32_e32 v32, v32
	s_nop 0
	v_add_f32_e32 v32, 1.0, v32
	v_div_scale_f32 v133, s[2:3], v32, v32, v47
	v_rcp_f32_e32 v162, v133
	s_nop 0
	v_fma_f32 v163, -v133, v162, 1.0
	v_fmac_f32_e32 v162, v163, v162
	v_div_scale_f32 v163, vcc, v47, v32, v47
	v_mul_f32_e32 v164, v163, v162
	v_fma_f32 v165, -v133, v164, v163
	v_fmac_f32_e32 v164, v165, v162
	v_fma_f32 v133, -v133, v164, v163
	v_div_fmas_f32 v133, v133, v162, v164
	v_div_fixup_f32 v32, v133, v32, v47
	v_bfe_u32 v133, v32, 16, 1
	v_add3_u32 v32, v32, v133, s1
	global_store_short_d16_hi v[160:161], v32, off offset:128
	v_mul_f32_e32 v32, 0xbfb8aa3b, v64
	v_exp_f32_e32 v32, v32
	v_or_b32_e32 v162, 58, v132
	v_ashrrev_i32_e32 v163, 31, v162
	v_lshlrev_b64 v[162:163], 12, v[162:163]
	v_add_f32_e32 v32, 1.0, v32
	v_div_scale_f32 v133, s[2:3], v32, v32, v64
	v_rcp_f32_e32 v164, v133
	v_lshl_add_u64 v[162:163], v[130:131], 0, v[162:163]
	v_or_b32_e32 v132, 59, v132
	v_fma_f32 v165, -v133, v164, 1.0
	v_fmac_f32_e32 v164, v165, v164
	v_div_scale_f32 v165, vcc, v64, v32, v64
	v_mul_f32_e32 v166, v165, v164
	v_fma_f32 v167, -v133, v166, v165
	v_fmac_f32_e32 v166, v167, v164
	v_fma_f32 v133, -v133, v166, v165
	v_div_fmas_f32 v133, v133, v164, v166
	v_div_fixup_f32 v32, v133, v32, v64
	v_bfe_u32 v133, v32, 16, 1
	v_add3_u32 v32, v32, v133, s1
	global_store_short_d16_hi v[162:163], v32, off
	v_mul_f32_e32 v32, 0xbfb8aa3b, v48
	v_exp_f32_e32 v32, v32
	s_nop 0
	v_add_f32_e32 v32, 1.0, v32
	v_div_scale_f32 v133, s[2:3], v32, v32, v48
	v_rcp_f32_e32 v164, v133
	s_nop 0
	v_fma_f32 v165, -v133, v164, 1.0
	v_fmac_f32_e32 v164, v165, v164
	v_div_scale_f32 v165, vcc, v48, v32, v48
	v_mul_f32_e32 v166, v165, v164
	v_fma_f32 v167, -v133, v166, v165
	v_fmac_f32_e32 v166, v167, v164
	v_fma_f32 v133, -v133, v166, v165
	v_div_fmas_f32 v133, v133, v164, v166
	v_div_fixup_f32 v32, v133, v32, v48
	v_bfe_u32 v133, v32, 16, 1
	v_add3_u32 v32, v32, v133, s1
	global_store_short_d16_hi v[162:163], v32, off offset:128
	v_mul_f32_e32 v32, 0xbfb8aa3b, v65
	v_exp_f32_e32 v32, v32
	v_ashrrev_i32_e32 v133, 31, v132
	v_lshlrev_b64 v[132:133], 12, v[132:133]
	v_lshl_add_u64 v[130:131], v[130:131], 0, v[132:133]
	v_add_f32_e32 v32, 1.0, v32
	v_div_scale_f32 v164, s[2:3], v32, v32, v65
	v_rcp_f32_e32 v165, v164
	s_nop 0
	v_fma_f32 v166, -v164, v165, 1.0
	v_fmac_f32_e32 v165, v166, v165
	v_div_scale_f32 v166, vcc, v65, v32, v65
	v_mul_f32_e32 v167, v166, v165
	v_fma_f32 v168, -v164, v167, v166
	v_fmac_f32_e32 v167, v168, v165
	v_fma_f32 v164, -v164, v167, v166
	v_div_fmas_f32 v164, v164, v165, v167
	v_div_fixup_f32 v32, v164, v32, v65
	v_bfe_u32 v164, v32, 16, 1
	v_add3_u32 v32, v32, v164, s1
	global_store_short_d16_hi v[130:131], v32, off
	v_mul_f32_e32 v32, 0xbfb8aa3b, v49
	v_exp_f32_e32 v32, v32
	s_nop 0
	v_add_f32_e32 v32, 1.0, v32
	v_div_scale_f32 v132, s[2:3], v32, v32, v49
	v_rcp_f32_e32 v133, v132
	s_nop 0
	v_fma_f32 v164, -v132, v133, 1.0
	v_fmac_f32_e32 v133, v164, v133
	v_div_scale_f32 v164, vcc, v49, v32, v49
	v_mul_f32_e32 v165, v164, v133
	v_fma_f32 v166, -v132, v165, v164
	v_fmac_f32_e32 v165, v166, v133
	v_fma_f32 v132, -v132, v165, v164
	v_div_fmas_f32 v132, v132, v133, v165
	v_div_fixup_f32 v32, v132, v32, v49
	v_bfe_u32 v132, v32, 16, 1
	v_add3_u32 v32, v32, v132, s1
	global_store_short_d16_hi v[130:131], v32, off offset:128
	v_mul_f32_e32 v32, 0xbfb8aa3b, v16
	v_exp_f32_e32 v32, v32
	s_nop 0
	v_add_f32_e32 v32, 1.0, v32
	v_div_scale_f32 v132, s[2:3], v32, v32, v16
	v_rcp_f32_e32 v133, v132
	s_nop 0
	v_fma_f32 v164, -v132, v133, 1.0
	v_fmac_f32_e32 v133, v164, v133
	v_div_scale_f32 v164, vcc, v16, v32, v16
	v_mul_f32_e32 v165, v164, v133
	v_fma_f32 v166, -v132, v165, v164
	v_fmac_f32_e32 v165, v166, v133
	v_fma_f32 v132, -v132, v165, v164
	v_div_fmas_f32 v132, v132, v133, v165
	v_div_fixup_f32 v32, v132, v32, v16
	v_bfe_u32 v132, v32, 16, 1
	v_add3_u32 v32, v32, v132, s1
	global_store_short_d16_hi v[134:135], v32, off offset:64
	v_mul_f32_e32 v32, 0xbfb8aa3b, v0
	v_exp_f32_e32 v32, v32
	s_nop 0
	v_add_f32_e32 v32, 1.0, v32
	v_div_scale_f32 v132, s[2:3], v32, v32, v0
	v_rcp_f32_e32 v133, v132
	s_nop 0
	v_fma_f32 v164, -v132, v133, 1.0
	v_fmac_f32_e32 v133, v164, v133
	v_div_scale_f32 v164, vcc, v0, v32, v0
	v_mul_f32_e32 v165, v164, v133
	v_fma_f32 v166, -v132, v165, v164
	v_fmac_f32_e32 v165, v166, v133
	v_fma_f32 v132, -v132, v165, v164
	v_div_fmas_f32 v132, v132, v133, v165
	v_div_fixup_f32 v32, v132, v32, v0
	v_bfe_u32 v132, v32, 16, 1
	v_add3_u32 v32, v32, v132, s1
	global_store_short_d16_hi v[134:135], v32, off offset:192
	v_mul_f32_e32 v32, 0xbfb8aa3b, v17
	v_exp_f32_e32 v32, v32
	s_nop 0
	v_add_f32_e32 v32, 1.0, v32
	v_div_scale_f32 v132, s[2:3], v32, v32, v17
	v_rcp_f32_e32 v133, v132
	s_nop 0
	v_fma_f32 v134, -v132, v133, 1.0
	v_fmac_f32_e32 v133, v134, v133
	v_div_scale_f32 v134, vcc, v17, v32, v17
	v_mul_f32_e32 v135, v134, v133
	v_fma_f32 v164, -v132, v135, v134
	v_fmac_f32_e32 v135, v164, v133
	v_fma_f32 v132, -v132, v135, v134
	v_div_fmas_f32 v132, v132, v133, v135
	v_div_fixup_f32 v32, v132, v32, v17
	v_bfe_u32 v132, v32, 16, 1
	v_add3_u32 v32, v32, v132, s1
	global_store_short_d16_hi v[136:137], v32, off offset:64
	v_mul_f32_e32 v32, 0xbfb8aa3b, v1
	v_exp_f32_e32 v32, v32
	s_nop 0
	v_add_f32_e32 v32, 1.0, v32
	v_div_scale_f32 v132, s[2:3], v32, v32, v1
	v_rcp_f32_e32 v133, v132
	s_nop 0
	v_fma_f32 v134, -v132, v133, 1.0
	v_fmac_f32_e32 v133, v134, v133
	v_div_scale_f32 v134, vcc, v1, v32, v1
	v_mul_f32_e32 v135, v134, v133
	v_fma_f32 v164, -v132, v135, v134
	v_fmac_f32_e32 v135, v164, v133
	v_fma_f32 v132, -v132, v135, v134
	v_div_fmas_f32 v132, v132, v133, v135
	v_div_fixup_f32 v32, v132, v32, v1
	v_bfe_u32 v132, v32, 16, 1
	v_add3_u32 v32, v32, v132, s1
	global_store_short_d16_hi v[136:137], v32, off offset:192
	v_mul_f32_e32 v32, 0xbfb8aa3b, v18
	v_exp_f32_e32 v32, v32
	s_nop 0
	v_add_f32_e32 v32, 1.0, v32
	v_div_scale_f32 v132, s[2:3], v32, v32, v18
	v_rcp_f32_e32 v133, v132
	s_nop 0
	v_fma_f32 v134, -v132, v133, 1.0
	v_fmac_f32_e32 v133, v134, v133
	v_div_scale_f32 v134, vcc, v18, v32, v18
	v_mul_f32_e32 v135, v134, v133
	v_fma_f32 v136, -v132, v135, v134
	v_fmac_f32_e32 v135, v136, v133
	v_fma_f32 v132, -v132, v135, v134
	v_div_fmas_f32 v132, v132, v133, v135
	v_div_fixup_f32 v32, v132, v32, v18
	v_bfe_u32 v132, v32, 16, 1
	v_add3_u32 v32, v32, v132, s1
	global_store_short_d16_hi v[138:139], v32, off offset:64
	v_mul_f32_e32 v32, 0xbfb8aa3b, v2
	v_exp_f32_e32 v32, v32
	s_nop 0
	v_add_f32_e32 v32, 1.0, v32
	v_div_scale_f32 v132, s[2:3], v32, v32, v2
	v_rcp_f32_e32 v133, v132
	s_nop 0
	v_fma_f32 v134, -v132, v133, 1.0
	v_fmac_f32_e32 v133, v134, v133
	v_div_scale_f32 v134, vcc, v2, v32, v2
	v_mul_f32_e32 v135, v134, v133
	v_fma_f32 v136, -v132, v135, v134
	v_fmac_f32_e32 v135, v136, v133
	v_fma_f32 v132, -v132, v135, v134
	v_div_fmas_f32 v132, v132, v133, v135
	v_div_fixup_f32 v32, v132, v32, v2
	v_bfe_u32 v132, v32, 16, 1
	v_add3_u32 v32, v32, v132, s1
	global_store_short_d16_hi v[138:139], v32, off offset:192
	v_mul_f32_e32 v32, 0xbfb8aa3b, v19
	v_exp_f32_e32 v32, v32
	s_nop 0
	v_add_f32_e32 v32, 1.0, v32
	v_div_scale_f32 v132, s[2:3], v32, v32, v19
	v_rcp_f32_e32 v133, v132
	s_nop 0
	v_fma_f32 v134, -v132, v133, 1.0
	v_fmac_f32_e32 v133, v134, v133
	v_div_scale_f32 v134, vcc, v19, v32, v19
	v_mul_f32_e32 v135, v134, v133
	v_fma_f32 v136, -v132, v135, v134
	v_fmac_f32_e32 v135, v136, v133
	v_fma_f32 v132, -v132, v135, v134
	v_div_fmas_f32 v132, v132, v133, v135
	v_div_fixup_f32 v32, v132, v32, v19
	v_bfe_u32 v132, v32, 16, 1
	v_add3_u32 v32, v32, v132, s1
	global_store_short_d16_hi v[140:141], v32, off offset:64
	v_mul_f32_e32 v32, 0xbfb8aa3b, v3
	v_exp_f32_e32 v32, v32
	s_nop 0
	v_add_f32_e32 v32, 1.0, v32
	v_div_scale_f32 v132, s[2:3], v32, v32, v3
	v_rcp_f32_e32 v133, v132
	s_nop 0
	v_fma_f32 v134, -v132, v133, 1.0
	v_fmac_f32_e32 v133, v134, v133
	v_div_scale_f32 v134, vcc, v3, v32, v3
	v_mul_f32_e32 v135, v134, v133
	v_fma_f32 v136, -v132, v135, v134
	v_fmac_f32_e32 v135, v136, v133
	v_fma_f32 v132, -v132, v135, v134
	v_div_fmas_f32 v132, v132, v133, v135
	v_div_fixup_f32 v32, v132, v32, v3
	v_bfe_u32 v132, v32, 16, 1
	v_add3_u32 v32, v32, v132, s1
	global_store_short_d16_hi v[140:141], v32, off offset:192
	v_mul_f32_e32 v32, 0xbfb8aa3b, v20
	v_exp_f32_e32 v32, v32
	s_nop 0
	v_add_f32_e32 v32, 1.0, v32
	v_div_scale_f32 v132, s[2:3], v32, v32, v20
	v_rcp_f32_e32 v133, v132
	s_nop 0
	v_fma_f32 v134, -v132, v133, 1.0
	v_fmac_f32_e32 v133, v134, v133
	v_div_scale_f32 v134, vcc, v20, v32, v20
	v_mul_f32_e32 v135, v134, v133
	v_fma_f32 v136, -v132, v135, v134
	v_fmac_f32_e32 v135, v136, v133
	v_fma_f32 v132, -v132, v135, v134
	v_div_fmas_f32 v132, v132, v133, v135
	v_div_fixup_f32 v32, v132, v32, v20
	v_bfe_u32 v132, v32, 16, 1
	v_add3_u32 v32, v32, v132, s1
	global_store_short_d16_hi v[142:143], v32, off offset:64
	v_mul_f32_e32 v32, 0xbfb8aa3b, v4
	v_exp_f32_e32 v32, v32
	s_nop 0
	v_add_f32_e32 v32, 1.0, v32
	v_div_scale_f32 v132, s[2:3], v32, v32, v4
	v_rcp_f32_e32 v133, v132
	s_nop 0
	v_fma_f32 v134, -v132, v133, 1.0
	v_fmac_f32_e32 v133, v134, v133
	v_div_scale_f32 v134, vcc, v4, v32, v4
	v_mul_f32_e32 v135, v134, v133
	v_fma_f32 v136, -v132, v135, v134
	v_fmac_f32_e32 v135, v136, v133
	v_fma_f32 v132, -v132, v135, v134
	v_div_fmas_f32 v132, v132, v133, v135
	v_div_fixup_f32 v32, v132, v32, v4
	v_bfe_u32 v132, v32, 16, 1
	v_add3_u32 v32, v32, v132, s1
	global_store_short_d16_hi v[142:143], v32, off offset:192
	v_mul_f32_e32 v32, 0xbfb8aa3b, v21
	v_exp_f32_e32 v32, v32
	s_nop 0
	v_add_f32_e32 v32, 1.0, v32
	v_div_scale_f32 v132, s[2:3], v32, v32, v21
	v_rcp_f32_e32 v133, v132
	s_nop 0
	v_fma_f32 v134, -v132, v133, 1.0
	v_fmac_f32_e32 v133, v134, v133
	v_div_scale_f32 v134, vcc, v21, v32, v21
	v_mul_f32_e32 v135, v134, v133
	v_fma_f32 v136, -v132, v135, v134
	v_fmac_f32_e32 v135, v136, v133
	v_fma_f32 v132, -v132, v135, v134
	v_div_fmas_f32 v132, v132, v133, v135
	v_div_fixup_f32 v32, v132, v32, v21
	v_bfe_u32 v132, v32, 16, 1
	v_add3_u32 v32, v32, v132, s1
	global_store_short_d16_hi v[144:145], v32, off offset:64
	v_mul_f32_e32 v32, 0xbfb8aa3b, v5
	v_exp_f32_e32 v32, v32
	s_nop 0
	v_add_f32_e32 v32, 1.0, v32
	v_div_scale_f32 v132, s[2:3], v32, v32, v5
	v_rcp_f32_e32 v133, v132
	s_nop 0
	v_fma_f32 v134, -v132, v133, 1.0
	v_fmac_f32_e32 v133, v134, v133
	v_div_scale_f32 v134, vcc, v5, v32, v5
	v_mul_f32_e32 v135, v134, v133
	v_fma_f32 v136, -v132, v135, v134
	v_fmac_f32_e32 v135, v136, v133
	v_fma_f32 v132, -v132, v135, v134
	v_div_fmas_f32 v132, v132, v133, v135
	v_div_fixup_f32 v32, v132, v32, v5
	v_bfe_u32 v132, v32, 16, 1
	v_add3_u32 v32, v32, v132, s1
	global_store_short_d16_hi v[144:145], v32, off offset:192
	v_mul_f32_e32 v32, 0xbfb8aa3b, v22
	v_exp_f32_e32 v32, v32
	s_nop 0
	v_add_f32_e32 v32, 1.0, v32
	v_div_scale_f32 v132, s[2:3], v32, v32, v22
	v_rcp_f32_e32 v133, v132
	s_nop 0
	v_fma_f32 v134, -v132, v133, 1.0
	v_fmac_f32_e32 v133, v134, v133
	v_div_scale_f32 v134, vcc, v22, v32, v22
	v_mul_f32_e32 v135, v134, v133
	v_fma_f32 v136, -v132, v135, v134
	v_fmac_f32_e32 v135, v136, v133
	v_fma_f32 v132, -v132, v135, v134
	v_div_fmas_f32 v132, v132, v133, v135
	v_div_fixup_f32 v32, v132, v32, v22
	v_bfe_u32 v132, v32, 16, 1
	v_add3_u32 v32, v32, v132, s1
	global_store_short_d16_hi v[146:147], v32, off offset:64
	v_mul_f32_e32 v32, 0xbfb8aa3b, v6
	v_exp_f32_e32 v32, v32
	s_nop 0
	v_add_f32_e32 v32, 1.0, v32
	v_div_scale_f32 v132, s[2:3], v32, v32, v6
	v_rcp_f32_e32 v133, v132
	s_nop 0
	v_fma_f32 v134, -v132, v133, 1.0
	v_fmac_f32_e32 v133, v134, v133
	v_div_scale_f32 v134, vcc, v6, v32, v6
	v_mul_f32_e32 v135, v134, v133
	v_fma_f32 v136, -v132, v135, v134
	v_fmac_f32_e32 v135, v136, v133
	v_fma_f32 v132, -v132, v135, v134
	v_div_fmas_f32 v132, v132, v133, v135
	v_div_fixup_f32 v32, v132, v32, v6
	v_bfe_u32 v132, v32, 16, 1
	v_add3_u32 v32, v32, v132, s1
	global_store_short_d16_hi v[146:147], v32, off offset:192
	v_mul_f32_e32 v32, 0xbfb8aa3b, v23
	v_exp_f32_e32 v32, v32
	s_nop 0
	v_add_f32_e32 v32, 1.0, v32
	v_div_scale_f32 v132, s[2:3], v32, v32, v23
	v_rcp_f32_e32 v133, v132
	s_nop 0
	v_fma_f32 v134, -v132, v133, 1.0
	v_fmac_f32_e32 v133, v134, v133
	v_div_scale_f32 v134, vcc, v23, v32, v23
	v_mul_f32_e32 v135, v134, v133
	v_fma_f32 v136, -v132, v135, v134
	v_fmac_f32_e32 v135, v136, v133
	v_fma_f32 v132, -v132, v135, v134
	v_div_fmas_f32 v132, v132, v133, v135
	v_div_fixup_f32 v32, v132, v32, v23
	v_bfe_u32 v132, v32, 16, 1
	v_add3_u32 v32, v32, v132, s1
	global_store_short_d16_hi v[148:149], v32, off offset:64
	v_mul_f32_e32 v32, 0xbfb8aa3b, v7
	v_exp_f32_e32 v32, v32
	s_nop 0
	v_add_f32_e32 v32, 1.0, v32
	v_div_scale_f32 v132, s[2:3], v32, v32, v7
	v_rcp_f32_e32 v133, v132
	s_nop 0
	v_fma_f32 v134, -v132, v133, 1.0
	v_fmac_f32_e32 v133, v134, v133
	v_div_scale_f32 v134, vcc, v7, v32, v7
	v_mul_f32_e32 v135, v134, v133
	v_fma_f32 v136, -v132, v135, v134
	v_fmac_f32_e32 v135, v136, v133
	v_fma_f32 v132, -v132, v135, v134
	v_div_fmas_f32 v132, v132, v133, v135
	v_div_fixup_f32 v32, v132, v32, v7
	v_bfe_u32 v132, v32, 16, 1
	v_add3_u32 v32, v32, v132, s1
	global_store_short_d16_hi v[148:149], v32, off offset:192
	v_mul_f32_e32 v32, 0xbfb8aa3b, v24
	v_exp_f32_e32 v32, v32
	s_nop 0
	v_add_f32_e32 v32, 1.0, v32
	v_div_scale_f32 v132, s[2:3], v32, v32, v24
	v_rcp_f32_e32 v133, v132
	s_nop 0
	v_fma_f32 v134, -v132, v133, 1.0
	v_fmac_f32_e32 v133, v134, v133
	v_div_scale_f32 v134, vcc, v24, v32, v24
	v_mul_f32_e32 v135, v134, v133
	v_fma_f32 v136, -v132, v135, v134
	v_fmac_f32_e32 v135, v136, v133
	v_fma_f32 v132, -v132, v135, v134
	v_div_fmas_f32 v132, v132, v133, v135
	v_div_fixup_f32 v32, v132, v32, v24
	v_bfe_u32 v132, v32, 16, 1
	v_add3_u32 v32, v32, v132, s1
	global_store_short_d16_hi v[150:151], v32, off offset:64
	v_mul_f32_e32 v32, 0xbfb8aa3b, v8
	v_exp_f32_e32 v32, v32
	s_nop 0
	v_add_f32_e32 v32, 1.0, v32
	v_div_scale_f32 v132, s[2:3], v32, v32, v8
	v_rcp_f32_e32 v133, v132
	s_nop 0
	v_fma_f32 v134, -v132, v133, 1.0
	v_fmac_f32_e32 v133, v134, v133
	v_div_scale_f32 v134, vcc, v8, v32, v8
	v_mul_f32_e32 v135, v134, v133
	v_fma_f32 v136, -v132, v135, v134
	v_fmac_f32_e32 v135, v136, v133
	v_fma_f32 v132, -v132, v135, v134
	v_div_fmas_f32 v132, v132, v133, v135
	v_div_fixup_f32 v32, v132, v32, v8
	v_bfe_u32 v132, v32, 16, 1
	v_add3_u32 v32, v32, v132, s1
	global_store_short_d16_hi v[150:151], v32, off offset:192
	v_mul_f32_e32 v32, 0xbfb8aa3b, v25
	v_exp_f32_e32 v32, v32
	s_nop 0
	v_add_f32_e32 v32, 1.0, v32
	v_div_scale_f32 v132, s[2:3], v32, v32, v25
	v_rcp_f32_e32 v133, v132
	s_nop 0
	v_fma_f32 v134, -v132, v133, 1.0
	v_fmac_f32_e32 v133, v134, v133
	v_div_scale_f32 v134, vcc, v25, v32, v25
	v_mul_f32_e32 v135, v134, v133
	v_fma_f32 v136, -v132, v135, v134
	v_fmac_f32_e32 v135, v136, v133
	v_fma_f32 v132, -v132, v135, v134
	v_div_fmas_f32 v132, v132, v133, v135
	v_div_fixup_f32 v32, v132, v32, v25
	v_bfe_u32 v132, v32, 16, 1
	v_add3_u32 v32, v32, v132, s1
	global_store_short_d16_hi v[152:153], v32, off offset:64
	v_mul_f32_e32 v32, 0xbfb8aa3b, v9
	v_exp_f32_e32 v32, v32
	s_nop 0
	v_add_f32_e32 v32, 1.0, v32
	v_div_scale_f32 v132, s[2:3], v32, v32, v9
	v_rcp_f32_e32 v133, v132
	s_nop 0
	v_fma_f32 v134, -v132, v133, 1.0
	v_fmac_f32_e32 v133, v134, v133
	v_div_scale_f32 v134, vcc, v9, v32, v9
	v_mul_f32_e32 v135, v134, v133
	v_fma_f32 v136, -v132, v135, v134
	v_fmac_f32_e32 v135, v136, v133
	v_fma_f32 v132, -v132, v135, v134
	v_div_fmas_f32 v132, v132, v133, v135
	v_div_fixup_f32 v32, v132, v32, v9
	v_bfe_u32 v132, v32, 16, 1
	v_add3_u32 v32, v32, v132, s1
	global_store_short_d16_hi v[152:153], v32, off offset:192
	v_mul_f32_e32 v32, 0xbfb8aa3b, v26
	v_exp_f32_e32 v32, v32
	s_nop 0
	v_add_f32_e32 v32, 1.0, v32
	v_div_scale_f32 v132, s[2:3], v32, v32, v26
	v_rcp_f32_e32 v133, v132
	s_nop 0
	v_fma_f32 v134, -v132, v133, 1.0
	v_fmac_f32_e32 v133, v134, v133
	v_div_scale_f32 v134, vcc, v26, v32, v26
	v_mul_f32_e32 v135, v134, v133
	v_fma_f32 v136, -v132, v135, v134
	v_fmac_f32_e32 v135, v136, v133
	v_fma_f32 v132, -v132, v135, v134
	v_div_fmas_f32 v132, v132, v133, v135
	v_div_fixup_f32 v32, v132, v32, v26
	v_bfe_u32 v132, v32, 16, 1
	v_add3_u32 v32, v32, v132, s1
	global_store_short_d16_hi v[154:155], v32, off offset:64
	v_mul_f32_e32 v32, 0xbfb8aa3b, v10
	v_exp_f32_e32 v32, v32
	s_nop 0
	v_add_f32_e32 v32, 1.0, v32
	v_div_scale_f32 v132, s[2:3], v32, v32, v10
	v_rcp_f32_e32 v133, v132
	s_nop 0
	v_fma_f32 v134, -v132, v133, 1.0
	v_fmac_f32_e32 v133, v134, v133
	v_div_scale_f32 v134, vcc, v10, v32, v10
	v_mul_f32_e32 v135, v134, v133
	v_fma_f32 v136, -v132, v135, v134
	v_fmac_f32_e32 v135, v136, v133
	v_fma_f32 v132, -v132, v135, v134
	v_div_fmas_f32 v132, v132, v133, v135
	v_div_fixup_f32 v32, v132, v32, v10
	v_bfe_u32 v132, v32, 16, 1
	v_add3_u32 v32, v32, v132, s1
	global_store_short_d16_hi v[154:155], v32, off offset:192
	v_mul_f32_e32 v32, 0xbfb8aa3b, v27
	v_exp_f32_e32 v32, v32
	s_nop 0
	v_add_f32_e32 v32, 1.0, v32
	v_div_scale_f32 v132, s[2:3], v32, v32, v27
	v_rcp_f32_e32 v133, v132
	s_nop 0
	v_fma_f32 v134, -v132, v133, 1.0
	v_fmac_f32_e32 v133, v134, v133
	v_div_scale_f32 v134, vcc, v27, v32, v27
	v_mul_f32_e32 v135, v134, v133
	v_fma_f32 v136, -v132, v135, v134
	v_fmac_f32_e32 v135, v136, v133
	v_fma_f32 v132, -v132, v135, v134
	v_div_fmas_f32 v132, v132, v133, v135
	v_div_fixup_f32 v32, v132, v32, v27
	v_bfe_u32 v132, v32, 16, 1
	v_add3_u32 v32, v32, v132, s1
	global_store_short_d16_hi v[156:157], v32, off offset:64
	v_mul_f32_e32 v32, 0xbfb8aa3b, v11
	v_exp_f32_e32 v32, v32
	s_nop 0
	v_add_f32_e32 v32, 1.0, v32
	v_div_scale_f32 v132, s[2:3], v32, v32, v11
	v_rcp_f32_e32 v133, v132
	s_nop 0
	v_fma_f32 v134, -v132, v133, 1.0
	v_fmac_f32_e32 v133, v134, v133
	v_div_scale_f32 v134, vcc, v11, v32, v11
	v_mul_f32_e32 v135, v134, v133
	v_fma_f32 v136, -v132, v135, v134
	v_fmac_f32_e32 v135, v136, v133
	v_fma_f32 v132, -v132, v135, v134
	v_div_fmas_f32 v132, v132, v133, v135
	v_div_fixup_f32 v32, v132, v32, v11
	v_bfe_u32 v132, v32, 16, 1
	v_add3_u32 v32, v32, v132, s1
	global_store_short_d16_hi v[156:157], v32, off offset:192
	v_mul_f32_e32 v32, 0xbfb8aa3b, v28
	v_exp_f32_e32 v32, v32
	s_nop 0
	v_add_f32_e32 v32, 1.0, v32
	v_div_scale_f32 v132, s[2:3], v32, v32, v28
	v_rcp_f32_e32 v133, v132
	s_nop 0
	v_fma_f32 v134, -v132, v133, 1.0
	v_fmac_f32_e32 v133, v134, v133
	v_div_scale_f32 v134, vcc, v28, v32, v28
	v_mul_f32_e32 v135, v134, v133
	v_fma_f32 v136, -v132, v135, v134
	v_fmac_f32_e32 v135, v136, v133
	v_fma_f32 v132, -v132, v135, v134
	v_div_fmas_f32 v132, v132, v133, v135
	v_div_fixup_f32 v32, v132, v32, v28
	v_bfe_u32 v132, v32, 16, 1
	v_add3_u32 v32, v32, v132, s1
	global_store_short_d16_hi v[158:159], v32, off offset:64
	v_mul_f32_e32 v32, 0xbfb8aa3b, v12
	v_exp_f32_e32 v32, v32
	s_nop 0
	v_add_f32_e32 v32, 1.0, v32
	v_div_scale_f32 v132, s[2:3], v32, v32, v12
	v_rcp_f32_e32 v133, v132
	s_nop 0
	v_fma_f32 v134, -v132, v133, 1.0
	v_fmac_f32_e32 v133, v134, v133
	v_div_scale_f32 v134, vcc, v12, v32, v12
	v_mul_f32_e32 v135, v134, v133
	v_fma_f32 v136, -v132, v135, v134
	v_fmac_f32_e32 v135, v136, v133
	v_fma_f32 v132, -v132, v135, v134
	v_div_fmas_f32 v132, v132, v133, v135
	v_div_fixup_f32 v32, v132, v32, v12
	v_bfe_u32 v132, v32, 16, 1
	v_add3_u32 v32, v32, v132, s1
	global_store_short_d16_hi v[158:159], v32, off offset:192
	v_mul_f32_e32 v32, 0xbfb8aa3b, v29
	v_exp_f32_e32 v32, v32
	s_nop 0
	v_add_f32_e32 v32, 1.0, v32
	v_div_scale_f32 v132, s[2:3], v32, v32, v29
	v_rcp_f32_e32 v133, v132
	s_nop 0
	v_fma_f32 v134, -v132, v133, 1.0
	v_fmac_f32_e32 v133, v134, v133
	v_div_scale_f32 v134, vcc, v29, v32, v29
	v_mul_f32_e32 v135, v134, v133
	v_fma_f32 v136, -v132, v135, v134
	v_fmac_f32_e32 v135, v136, v133
	v_fma_f32 v132, -v132, v135, v134
	v_div_fmas_f32 v132, v132, v133, v135
	v_div_fixup_f32 v32, v132, v32, v29
	v_bfe_u32 v132, v32, 16, 1
	v_add3_u32 v32, v32, v132, s1
	global_store_short_d16_hi v[160:161], v32, off offset:64
	v_mul_f32_e32 v32, 0xbfb8aa3b, v13
	v_exp_f32_e32 v32, v32
	s_nop 0
	v_add_f32_e32 v32, 1.0, v32
	v_div_scale_f32 v132, s[2:3], v32, v32, v13
	v_rcp_f32_e32 v133, v132
	s_nop 0
	v_fma_f32 v134, -v132, v133, 1.0
	v_fmac_f32_e32 v133, v134, v133
	v_div_scale_f32 v134, vcc, v13, v32, v13
	v_mul_f32_e32 v135, v134, v133
	v_fma_f32 v136, -v132, v135, v134
	v_fmac_f32_e32 v135, v136, v133
	v_fma_f32 v132, -v132, v135, v134
	v_div_fmas_f32 v132, v132, v133, v135
	v_div_fixup_f32 v32, v132, v32, v13
	v_bfe_u32 v132, v32, 16, 1
	v_add3_u32 v32, v32, v132, s1
	global_store_short_d16_hi v[160:161], v32, off offset:192
	v_mul_f32_e32 v32, 0xbfb8aa3b, v30
	v_exp_f32_e32 v32, v32
	s_nop 0
	v_add_f32_e32 v32, 1.0, v32
	v_div_scale_f32 v132, s[2:3], v32, v32, v30
	v_rcp_f32_e32 v133, v132
	s_nop 0
	v_fma_f32 v134, -v132, v133, 1.0
	v_fmac_f32_e32 v133, v134, v133
	v_div_scale_f32 v134, vcc, v30, v32, v30
	v_mul_f32_e32 v135, v134, v133
	v_fma_f32 v136, -v132, v135, v134
	v_fmac_f32_e32 v135, v136, v133
	v_fma_f32 v132, -v132, v135, v134
	v_div_fmas_f32 v132, v132, v133, v135
	v_div_fixup_f32 v32, v132, v32, v30
	v_bfe_u32 v132, v32, 16, 1
	v_add3_u32 v32, v32, v132, s1
	global_store_short_d16_hi v[162:163], v32, off offset:64
	v_mul_f32_e32 v32, 0xbfb8aa3b, v14
	v_exp_f32_e32 v32, v32
	s_nop 0
	v_add_f32_e32 v32, 1.0, v32
	v_div_scale_f32 v132, s[2:3], v32, v32, v14
	v_rcp_f32_e32 v133, v132
	s_nop 0
	v_fma_f32 v134, -v132, v133, 1.0
	v_fmac_f32_e32 v133, v134, v133
	v_div_scale_f32 v134, vcc, v14, v32, v14
	v_mul_f32_e32 v135, v134, v133
	v_fma_f32 v136, -v132, v135, v134
	v_fmac_f32_e32 v135, v136, v133
	v_fma_f32 v132, -v132, v135, v134
	v_div_fmas_f32 v132, v132, v133, v135
	v_div_fixup_f32 v32, v132, v32, v14
	v_bfe_u32 v132, v32, 16, 1
	v_add3_u32 v32, v32, v132, s1
	global_store_short_d16_hi v[162:163], v32, off offset:192
	v_mul_f32_e32 v32, 0xbfb8aa3b, v31
	v_exp_f32_e32 v32, v32
	s_nop 0
	v_add_f32_e32 v32, 1.0, v32
	v_div_scale_f32 v132, s[2:3], v32, v32, v31
	v_rcp_f32_e32 v133, v132
	s_nop 0
	v_fma_f32 v134, -v132, v133, 1.0
	v_fmac_f32_e32 v133, v134, v133
	v_div_scale_f32 v134, vcc, v31, v32, v31
	v_mul_f32_e32 v135, v134, v133
	v_fma_f32 v136, -v132, v135, v134
	v_fmac_f32_e32 v135, v136, v133
	v_fma_f32 v132, -v132, v135, v134
	v_div_fmas_f32 v132, v132, v133, v135
	v_div_fixup_f32 v32, v132, v32, v31
	v_bfe_u32 v132, v32, 16, 1
	v_add3_u32 v32, v32, v132, s1
	global_store_short_d16_hi v[130:131], v32, off offset:64
	v_mul_f32_e32 v32, 0xbfb8aa3b, v15
	v_exp_f32_e32 v32, v32
	s_nop 0
	v_add_f32_e32 v32, 1.0, v32
	v_div_scale_f32 v132, s[2:3], v32, v32, v15
	v_rcp_f32_e32 v133, v132
	s_mov_b64 s[2:3], 0
	v_fma_f32 v134, -v132, v133, 1.0
	v_fmac_f32_e32 v133, v134, v133
	v_div_scale_f32 v134, vcc, v15, v32, v15
	v_mul_f32_e32 v135, v134, v133
	v_fma_f32 v136, -v132, v135, v134
	v_fmac_f32_e32 v135, v136, v133
	v_fma_f32 v132, -v132, v135, v134
	v_div_fmas_f32 v132, v132, v133, v135
	v_div_fixup_f32 v32, v132, v32, v15
	v_bfe_u32 v132, v32, 16, 1
	v_add3_u32 v32, v32, v132, s1
	global_store_short_d16_hi v[130:131], v32, off offset:192

.LBB0_1696:
	s_add_i32 s7, s3, 1
	s_cmp_lt_u32 s3, 31
	s_cselect_b32 s3, s7, s3
	s_lshl_b32 s16, s3, 6
	s_lshl_b64 s[14:15], s[16:17], 1
	s_barrier
	s_waitcnt vmcnt(0)
	ds_write_b128 v204, v[174:177]
	ds_write_b128 v204, v[170:173] offset:4608
	ds_write_b128 v204, v[166:169] offset:9216
	ds_write_b128 v204, v[162:165] offset:13824
	ds_write_b128 v204, v[158:161] offset:18432
	ds_write_b128 v204, v[154:157] offset:23040
	ds_write_b128 v204, v[150:153] offset:27648
	ds_write_b128 v204, v[146:149] offset:32256
	ds_write_b128 v204, v[142:145] offset:36864
	ds_write_b128 v204, v[134:137] offset:41472
	ds_write_b128 v204, v[130:133] offset:46080
	ds_write_b128 v204, v[138:141] offset:50688
	v_lshl_add_u64 v[130:131], v[178:179], 0, s[14:15]
	s_add_u32 s100, s14, 0x20000
	s_addc_u32 s101, s15, 0
	v_lshl_add_u64 v[132:133], v[178:179], 0, s[100:101]
	s_add_u32 s100, s100, 0x20000
	s_addc_u32 s101, s101, 0
	v_lshl_add_u64 v[134:135], v[178:179], 0, s[100:101]
	s_add_u32 s100, s100, 0x20000
	s_addc_u32 s101, s101, 0
	v_lshl_add_u64 v[136:137], v[178:179], 0, s[100:101]
	s_add_u32 s100, s100, 0x20000
	s_addc_u32 s101, s101, 0
	v_lshl_add_u64 v[138:139], v[178:179], 0, s[100:101]
	s_add_u32 s100, s100, 0x20000
	s_addc_u32 s101, s101, 0
	v_lshl_add_u64 v[140:141], v[178:179], 0, s[100:101]
	s_add_u32 s100, s100, 0x20000
	s_addc_u32 s101, s101, 0
	v_lshl_add_u64 v[142:143], v[178:179], 0, s[100:101]
	s_add_u32 s100, s100, 0x20000
	s_addc_u32 s101, s101, 0
	v_lshl_add_u64 v[144:145], v[178:179], 0, s[100:101]
	s_waitcnt lgkmcnt(0)
	s_barrier
	v_lshl_add_u64 v[224:225], v[180:181], 0, s[14:15]
	s_add_u32 s100, s14, 0x20000
	s_addc_u32 s101, s15, 0
	v_lshl_add_u64 v[226:227], v[180:181], 0, s[100:101]
	s_add_u32 s100, s100, 0x20000
	s_addc_u32 s101, s101, 0
	v_lshl_add_u64 v[228:229], v[180:181], 0, s[100:101]
	s_add_u32 s100, s100, 0x20000
	s_addc_u32 s101, s101, 0
	v_lshl_add_u64 v[230:231], v[180:181], 0, s[100:101]
	global_load_dwordx4 v[174:177], v[130:131], off
	global_load_dwordx4 v[170:173], v[132:133], off
	global_load_dwordx4 v[166:169], v[134:135], off
	global_load_dwordx4 v[162:165], v[136:137], off
	global_load_dwordx4 v[158:161], v[138:139], off
	global_load_dwordx4 v[154:157], v[140:141], off
	global_load_dwordx4 v[150:153], v[142:143], off
	global_load_dwordx4 v[146:149], v[144:145], off
	global_load_dwordx4 v[142:145], v[224:225], off
	global_load_dwordx4 v[134:137], v[226:227], off
	global_load_dwordx4 v[130:133], v[228:229], off
	global_load_dwordx4 v[138:141], v[230:231], off
	ds_read_b128 v[224:227], v182
	ds_read_b128 v[228:231], v183 offset:36864
	ds_read_b128 v[232:235], v183 offset:41472
	ds_read_b128 v[184:187], v182 offset:4608
	ds_read_b128 v[236:239], v183 offset:46080
	ds_read_b128 v[240:243], v183 offset:50688
	s_waitcnt lgkmcnt(4)
	v_mfma_f32_32x32x16_bf16 v[114:129], v[224:227], v[228:231], v[114:129]
	ds_read_b128 v[188:191], v183 offset:36896
	ds_read_b128 v[192:195], v183 offset:41504
	s_waitcnt lgkmcnt(5)
	v_mfma_f32_32x32x16_bf16 v[82:97], v[224:227], v[232:235], v[82:97]
	ds_read_b128 v[196:199], v183 offset:46112
	ds_read_b128 v[200:203], v183 offset:50720
	s_waitcnt lgkmcnt(5)
	v_mfma_f32_32x32x16_bf16 v[98:113], v[224:227], v[236:239], v[98:113]
	s_waitcnt lgkmcnt(4)
	v_mfma_f32_32x32x16_bf16 v[66:81], v[224:227], v[240:243], v[66:81]
	ds_read_b128 v[224:227], v182 offset:32
	v_mfma_f32_32x32x16_bf16 v[50:65], v[184:187], v[228:231], v[50:65]
	v_mfma_f32_32x32x16_bf16 v[16:31], v[184:187], v[232:235], v[16:31]
	v_mfma_f32_32x32x16_bf16 v[34:49], v[184:187], v[236:239], v[34:49]
	v_mfma_f32_32x32x16_bf16 v[0:15], v[184:187], v[240:243], v[0:15]
	ds_read_b128 v[184:187], v182 offset:4640
	s_waitcnt lgkmcnt(1)
	v_mfma_f32_32x32x16_bf16 v[114:129], v[224:227], v[188:191], v[114:129]
	ds_read_b128 v[228:231], v183 offset:36928
	ds_read_b128 v[232:235], v183 offset:41536
	v_mfma_f32_32x32x16_bf16 v[82:97], v[224:227], v[192:195], v[82:97]
	ds_read_b128 v[236:239], v183 offset:46144
	ds_read_b128 v[240:243], v183 offset:50752
	v_mfma_f32_32x32x16_bf16 v[98:113], v[224:227], v[196:199], v[98:113]
	v_mfma_f32_32x32x16_bf16 v[66:81], v[224:227], v[200:203], v[66:81]
	ds_read_b128 v[224:227], v182 offset:64
	s_waitcnt lgkmcnt(5)
	v_mfma_f32_32x32x16_bf16 v[50:65], v[184:187], v[188:191], v[50:65]
	v_mfma_f32_32x32x16_bf16 v[16:31], v[184:187], v[192:195], v[16:31]
	v_mfma_f32_32x32x16_bf16 v[34:49], v[184:187], v[196:199], v[34:49]
	v_mfma_f32_32x32x16_bf16 v[0:15], v[184:187], v[200:203], v[0:15]
	ds_read_b128 v[184:187], v182 offset:4672
	s_waitcnt lgkmcnt(1)
	v_mfma_f32_32x32x16_bf16 v[114:129], v[224:227], v[228:231], v[114:129]
	ds_read_b128 v[188:191], v183 offset:36960
	ds_read_b128 v[192:195], v183 offset:41568
	v_mfma_f32_32x32x16_bf16 v[82:97], v[224:227], v[232:235], v[82:97]
	ds_read_b128 v[196:199], v183 offset:46176
	ds_read_b128 v[200:203], v183 offset:50784
	v_mfma_f32_32x32x16_bf16 v[98:113], v[224:227], v[236:239], v[98:113]
	v_mfma_f32_32x32x16_bf16 v[66:81], v[224:227], v[240:243], v[66:81]
	ds_read_b128 v[224:227], v182 offset:96
	s_waitcnt lgkmcnt(5)
	v_mfma_f32_32x32x16_bf16 v[50:65], v[184:187], v[228:231], v[50:65]
	v_mfma_f32_32x32x16_bf16 v[16:31], v[184:187], v[232:235], v[16:31]
	v_mfma_f32_32x32x16_bf16 v[34:49], v[184:187], v[236:239], v[34:49]
	v_mfma_f32_32x32x16_bf16 v[0:15], v[184:187], v[240:243], v[0:15]
	ds_read_b128 v[184:187], v182 offset:4704
	s_waitcnt lgkmcnt(1)
	v_mfma_f32_32x32x16_bf16 v[114:129], v[224:227], v[188:191], v[114:129]
	v_mfma_f32_32x32x16_bf16 v[82:97], v[224:227], v[192:195], v[82:97]
	v_mfma_f32_32x32x16_bf16 v[98:113], v[224:227], v[196:199], v[98:113]
	v_mfma_f32_32x32x16_bf16 v[66:81], v[224:227], v[200:203], v[66:81]
	s_waitcnt lgkmcnt(0)
	v_mfma_f32_32x32x16_bf16 v[50:65], v[184:187], v[188:191], v[50:65]
	v_mfma_f32_32x32x16_bf16 v[16:31], v[184:187], v[192:195], v[16:31]
	v_mfma_f32_32x32x16_bf16 v[34:49], v[184:187], v[196:199], v[34:49]
	v_mfma_f32_32x32x16_bf16 v[0:15], v[184:187], v[200:203], v[0:15]
	s_mov_b32 s3, s7
	s_cmp_lg_u32 s7, 32
	s_cbranch_scc1 .LBB0_1696
	s_lshl_b32 s3, s6, 7
	s_lshr_b32 s6, s13, 24
	s_add_i32 s6, s12, s6
	s_lshr_b32 s6, s6, 8
	s_add_i32 s6, s6, s10
	v_mov_b32_e32 v32, v206
	s_barrier
	s_mulk_i32 s6, 0x1800
	s_ashr_i32 s7, s6, 31
	s_waitcnt vmcnt(1)
	v_and_b32_e32 v131, 0xffffffc0, v32
	v_lshrrev_b32_e32 v132, 3, v32
	v_readlane_b32 s36, v248, 46
	v_and_or_b32 v130, v32, 31, s3
	v_and_or_b32 v32, v132, 4, v131
	s_lshl_b64 s[6:7], s[6:7], 2
	v_readlane_b32 s40, v248, 50
	v_lshl_add_u32 v132, s2, 8, v32
	v_readlane_b32 s41, v248, 51
	s_add_u32 s6, s40, s6
	v_ashrrev_i32_e32 v133, 31, v132
	s_addc_u32 s7, s41, s7
	v_ashrrev_i32_e32 v131, 31, v130
	v_lshlrev_b64 v[136:137], 10, v[132:133]
	s_add_u32 s6, s6, 0x2000
	v_lshl_add_u64 v[136:137], v[136:137], 0, v[130:131]
	s_addc_u32 s7, s7, 0
	s_waitcnt vmcnt(0)
	v_lshlrev_b64 v[138:139], 2, v[136:137]
	v_lshl_add_u64 v[134:135], v[130:131], 2, s[6:7]
	v_lshl_add_u64 v[136:137], s[0:1], 0, v[138:139]
	global_load_dword v32, v[134:135], off
	global_load_dword v148, v[134:135], off offset:256
	global_load_dword v133, v[136:137], off
	v_readlane_b32 s48, v248, 58
	v_readlane_b32 s49, v248, 59
	v_or_b32_e32 v140, 1, v132
	v_ashrrev_i32_e32 v141, 31, v140
	v_lshl_add_u64 v[138:139], s[48:49], 0, v[138:139]
	v_lshlrev_b64 v[140:141], 10, v[140:141]
	v_lshl_add_u64 v[140:141], v[140:141], 0, v[130:131]
	v_lshlrev_b64 v[142:143], 2, v[140:141]
	v_lshl_add_u64 v[140:141], s[0:1], 0, v[142:143]
	v_writelane_b32 v251, s16, 29
	v_readlane_b32 s37, v248, 47
	v_readlane_b32 s38, v248, 48
	v_writelane_b32 v251, s17, 30
	v_readlane_b32 s39, v248, 49
	v_readlane_b32 s2, v251, 24
	s_add_i32 s11, s11, s2
	s_cmpk_lt_i32 s11, 0x200
	v_readlane_b32 s42, v248, 52
	v_readlane_b32 s43, v248, 53
	v_readlane_b32 s44, v248, 54
	v_readlane_b32 s45, v248, 55
	v_readlane_b32 s46, v248, 56
	v_readlane_b32 s47, v248, 57
	v_readlane_b32 s50, v248, 60
	v_readlane_b32 s51, v248, 61
	v_readlane_b32 s3, v251, 25
	s_waitcnt vmcnt(0)
	v_mul_f32_e32 v133, 0x3fd744fd, v133
	v_fmac_f32_e32 v133, v114, v32
	global_store_dword v[138:139], v133, off
	global_load_dword v114, v[136:137], off offset:256
	s_waitcnt vmcnt(0)
	v_mul_f32_e32 v114, 0x3fd744fd, v114
	v_fmac_f32_e32 v114, v98, v148
	global_store_dword v[138:139], v114, off offset:256
	global_load_dword v98, v[140:141], off
	s_waitcnt vmcnt(0)
	v_mul_f32_e32 v98, 0x3fd744fd, v98
	v_fmac_f32_e32 v98, v115, v32
	v_lshl_add_u64 v[114:115], s[48:49], 0, v[142:143]
	global_store_dword v[114:115], v98, off
	global_load_dword v98, v[140:141], off offset:256
	s_waitcnt vmcnt(0)
	v_mul_f32_e32 v98, 0x3fd744fd, v98
	v_fmac_f32_e32 v98, v99, v148
	global_store_dword v[114:115], v98, off offset:256
	v_or_b32_e32 v98, 2, v132
	v_ashrrev_i32_e32 v99, 31, v98
	v_lshlrev_b64 v[98:99], 10, v[98:99]
	v_lshl_add_u64 v[98:99], v[98:99], 0, v[130:131]
	v_lshlrev_b64 v[98:99], 2, v[98:99]
	v_lshl_add_u64 v[142:143], s[0:1], 0, v[98:99]
	global_load_dword v133, v[142:143], off
	v_lshl_add_u64 v[144:145], s[48:49], 0, v[98:99]
	s_waitcnt vmcnt(0)
	v_mul_f32_e32 v133, 0x3fd744fd, v133
	v_fmac_f32_e32 v133, v116, v32
	global_store_dword v[144:145], v133, off
	global_load_dword v98, v[142:143], off offset:256
	s_waitcnt vmcnt(0)
	v_mul_f32_e32 v98, 0x3fd744fd, v98
	v_fmac_f32_e32 v98, v100, v148
	global_store_dword v[144:145], v98, off offset:256
	v_or_b32_e32 v98, 3, v132
	v_ashrrev_i32_e32 v99, 31, v98
	v_lshlrev_b64 v[98:99], 10, v[98:99]
	v_lshl_add_u64 v[98:99], v[98:99], 0, v[130:131]
	v_lshlrev_b64 v[98:99], 2, v[98:99]
	v_lshl_add_u64 v[146:147], s[0:1], 0, v[98:99]
	global_load_dword v100, v[146:147], off
	s_waitcnt vmcnt(0)
	v_mul_f32_e32 v100, 0x3fd744fd, v100
	v_fmac_f32_e32 v100, v117, v32
	v_lshl_add_u64 v[116:117], s[48:49], 0, v[98:99]
	global_store_dword v[116:117], v100, off
	global_load_dword v32, v[146:147], off offset:256
	v_or_b32_e32 v98, 8, v132
	v_ashrrev_i32_e32 v99, 31, v98
	v_lshlrev_b64 v[98:99], 10, v[98:99]
	v_lshl_add_u64 v[98:99], v[98:99], 0, v[130:131]
	v_lshlrev_b64 v[98:99], 2, v[98:99]
	s_waitcnt vmcnt(0)
	v_mul_f32_e32 v32, 0x3fd744fd, v32
	v_fmac_f32_e32 v32, v101, v148
	global_store_dword v[116:117], v32, off offset:256
	v_lshl_add_u64 v[100:101], s[0:1], 0, v[98:99]
	global_load_dword v32, v[134:135], off
	global_load_dword v133, v[134:135], off offset:256
	global_load_dword v148, v[100:101], off
	s_waitcnt vmcnt(0)
	v_mul_f32_e32 v150, 0x3fd744fd, v148
	v_fmac_f32_e32 v150, v118, v32
	v_lshl_add_u64 v[148:149], s[48:49], 0, v[98:99]
	global_store_dword v[148:149], v150, off
	global_load_dword v98, v[100:101], off offset:256
	s_waitcnt vmcnt(0)
	v_mul_f32_e32 v98, 0x3fd744fd, v98
	v_fmac_f32_e32 v98, v102, v133
	global_store_dword v[148:149], v98, off offset:256
	v_or_b32_e32 v98, 9, v132
	v_ashrrev_i32_e32 v99, 31, v98
	v_lshlrev_b64 v[98:99], 10, v[98:99]
	v_lshl_add_u64 v[98:99], v[98:99], 0, v[130:131]
	v_lshlrev_b64 v[98:99], 2, v[98:99]
	v_lshl_add_u64 v[150:151], s[0:1], 0, v[98:99]
	global_load_dword v102, v[150:151], off
	s_waitcnt vmcnt(0)
	v_mul_f32_e32 v102, 0x3fd744fd, v102
	v_fmac_f32_e32 v102, v119, v32
	v_lshl_add_u64 v[118:119], s[48:49], 0, v[98:99]
	global_store_dword v[118:119], v102, off
	global_load_dword v98, v[150:151], off offset:256
	s_waitcnt vmcnt(0)
	v_mul_f32_e32 v98, 0x3fd744fd, v98
	v_fmac_f32_e32 v98, v103, v133
	global_store_dword v[118:119], v98, off offset:256
	v_or_b32_e32 v98, 10, v132
	v_ashrrev_i32_e32 v99, 31, v98
	v_lshlrev_b64 v[98:99], 10, v[98:99]
	v_lshl_add_u64 v[98:99], v[98:99], 0, v[130:131]
	v_lshlrev_b64 v[98:99], 2, v[98:99]
	v_lshl_add_u64 v[102:103], s[0:1], 0, v[98:99]
	global_load_dword v152, v[102:103], off
	s_waitcnt vmcnt(0)
	v_mul_f32_e32 v154, 0x3fd744fd, v152
	v_fmac_f32_e32 v154, v120, v32
	v_lshl_add_u64 v[152:153], s[48:49], 0, v[98:99]
	global_store_dword v[152:153], v154, off
	global_load_dword v98, v[102:103], off offset:256
	s_waitcnt vmcnt(0)
	v_mul_f32_e32 v98, 0x3fd744fd, v98
	v_fmac_f32_e32 v98, v104, v133
	global_store_dword v[152:153], v98, off offset:256
	v_or_b32_e32 v98, 11, v132
	v_ashrrev_i32_e32 v99, 31, v98
	v_lshlrev_b64 v[98:99], 10, v[98:99]
	v_lshl_add_u64 v[98:99], v[98:99], 0, v[130:131]
	v_lshlrev_b64 v[98:99], 2, v[98:99]
	v_lshl_add_u64 v[154:155], s[0:1], 0, v[98:99]
	global_load_dword v104, v[154:155], off
	s_waitcnt vmcnt(0)
	v_mul_f32_e32 v104, 0x3fd744fd, v104
	v_fmac_f32_e32 v104, v121, v32
	v_lshl_add_u64 v[120:121], s[48:49], 0, v[98:99]
	global_store_dword v[120:121], v104, off
	global_load_dword v32, v[154:155], off offset:256
	v_or_b32_e32 v98, 16, v132
	v_ashrrev_i32_e32 v99, 31, v98
	v_lshlrev_b64 v[98:99], 10, v[98:99]
	v_lshl_add_u64 v[98:99], v[98:99], 0, v[130:131]
	v_lshlrev_b64 v[98:99], 2, v[98:99]
	s_waitcnt vmcnt(0)
	v_mul_f32_e32 v32, 0x3fd744fd, v32
	v_fmac_f32_e32 v32, v105, v133
	global_store_dword v[120:121], v32, off offset:256
	v_lshl_add_u64 v[104:105], s[0:1], 0, v[98:99]
	global_load_dword v32, v[134:135], off
	global_load_dword v133, v[134:135], off offset:256
	global_load_dword v156, v[104:105], off
	s_waitcnt vmcnt(0)
	v_mul_f32_e32 v158, 0x3fd744fd, v156
	v_fmac_f32_e32 v158, v122, v32
	v_lshl_add_u64 v[156:157], s[48:49], 0, v[98:99]
	global_store_dword v[156:157], v158, off
	global_load_dword v98, v[104:105], off offset:256
	s_waitcnt vmcnt(0)
	v_mul_f32_e32 v98, 0x3fd744fd, v98
	v_fmac_f32_e32 v98, v106, v133
	global_store_dword v[156:157], v98, off offset:256
	v_or_b32_e32 v98, 17, v132
	v_ashrrev_i32_e32 v99, 31, v98
	v_lshlrev_b64 v[98:99], 10, v[98:99]
	v_lshl_add_u64 v[98:99], v[98:99], 0, v[130:131]
	v_lshlrev_b64 v[98:99], 2, v[98:99]
	v_lshl_add_u64 v[158:159], s[0:1], 0, v[98:99]
	global_load_dword v106, v[158:159], off
	s_waitcnt vmcnt(0)
	v_mul_f32_e32 v106, 0x3fd744fd, v106
	v_fmac_f32_e32 v106, v123, v32
	v_lshl_add_u64 v[122:123], s[48:49], 0, v[98:99]
	global_store_dword v[122:123], v106, off
	global_load_dword v98, v[158:159], off offset:256
	s_waitcnt vmcnt(0)
	v_mul_f32_e32 v98, 0x3fd744fd, v98
	v_fmac_f32_e32 v98, v107, v133
	global_store_dword v[122:123], v98, off offset:256
	v_or_b32_e32 v98, 18, v132
	v_ashrrev_i32_e32 v99, 31, v98
	v_lshlrev_b64 v[98:99], 10, v[98:99]
	v_lshl_add_u64 v[98:99], v[98:99], 0, v[130:131]
	v_lshlrev_b64 v[98:99], 2, v[98:99]
	v_lshl_add_u64 v[106:107], s[0:1], 0, v[98:99]
	global_load_dword v160, v[106:107], off
	s_waitcnt vmcnt(0)
	v_mul_f32_e32 v162, 0x3fd744fd, v160
	v_fmac_f32_e32 v162, v124, v32
	v_lshl_add_u64 v[160:161], s[48:49], 0, v[98:99]
	global_store_dword v[160:161], v162, off
	global_load_dword v98, v[106:107], off offset:256
	s_waitcnt vmcnt(0)
	v_mul_f32_e32 v98, 0x3fd744fd, v98
	v_fmac_f32_e32 v98, v108, v133
	global_store_dword v[160:161], v98, off offset:256
	v_or_b32_e32 v98, 19, v132
	v_ashrrev_i32_e32 v99, 31, v98
	v_lshlrev_b64 v[98:99], 10, v[98:99]
	v_lshl_add_u64 v[98:99], v[98:99], 0, v[130:131]
	v_lshlrev_b64 v[98:99], 2, v[98:99]
	v_lshl_add_u64 v[162:163], s[0:1], 0, v[98:99]
	global_load_dword v108, v[162:163], off
	s_waitcnt vmcnt(0)
	v_mul_f32_e32 v108, 0x3fd744fd, v108
	v_fmac_f32_e32 v108, v125, v32
	v_lshl_add_u64 v[124:125], s[48:49], 0, v[98:99]
	global_store_dword v[124:125], v108, off
	global_load_dword v32, v[162:163], off offset:256
	v_or_b32_e32 v98, 24, v132
	v_ashrrev_i32_e32 v99, 31, v98
	v_lshlrev_b64 v[98:99], 10, v[98:99]
	v_lshl_add_u64 v[98:99], v[98:99], 0, v[130:131]
	v_lshlrev_b64 v[98:99], 2, v[98:99]
	s_waitcnt vmcnt(0)
	v_mul_f32_e32 v32, 0x3fd744fd, v32
	v_fmac_f32_e32 v32, v109, v133
	global_store_dword v[124:125], v32, off offset:256
	v_lshl_add_u64 v[108:109], s[0:1], 0, v[98:99]
	global_load_dword v32, v[134:135], off
	global_load_dword v133, v[134:135], off offset:256
	global_load_dword v164, v[108:109], off
	s_waitcnt vmcnt(0)
	v_mul_f32_e32 v166, 0x3fd744fd, v164
	v_fmac_f32_e32 v166, v126, v32
	v_lshl_add_u64 v[164:165], s[48:49], 0, v[98:99]
	global_store_dword v[164:165], v166, off
	global_load_dword v98, v[108:109], off offset:256
	s_waitcnt vmcnt(0)
	v_mul_f32_e32 v98, 0x3fd744fd, v98
	v_fmac_f32_e32 v98, v110, v133
	global_store_dword v[164:165], v98, off offset:256
	v_or_b32_e32 v98, 25, v132
	v_ashrrev_i32_e32 v99, 31, v98
	v_lshlrev_b64 v[98:99], 10, v[98:99]
	v_lshl_add_u64 v[98:99], v[98:99], 0, v[130:131]
	v_lshlrev_b64 v[98:99], 2, v[98:99]
	v_lshl_add_u64 v[166:167], s[0:1], 0, v[98:99]
	global_load_dword v110, v[166:167], off
	s_waitcnt vmcnt(0)
	v_mul_f32_e32 v110, 0x3fd744fd, v110
	v_fmac_f32_e32 v110, v127, v32
	v_lshl_add_u64 v[126:127], s[48:49], 0, v[98:99]
	global_store_dword v[126:127], v110, off
	global_load_dword v98, v[166:167], off offset:256
	s_waitcnt vmcnt(0)
	v_mul_f32_e32 v98, 0x3fd744fd, v98
	v_fmac_f32_e32 v98, v111, v133
	global_store_dword v[126:127], v98, off offset:256
	v_or_b32_e32 v98, 26, v132
	v_ashrrev_i32_e32 v99, 31, v98
	v_lshlrev_b64 v[98:99], 10, v[98:99]
	v_lshl_add_u64 v[98:99], v[98:99], 0, v[130:131]
	v_lshlrev_b64 v[98:99], 2, v[98:99]
	v_lshl_add_u64 v[110:111], s[0:1], 0, v[98:99]
	global_load_dword v168, v[110:111], off
	s_waitcnt vmcnt(0)
	v_mul_f32_e32 v170, 0x3fd744fd, v168
	v_fmac_f32_e32 v170, v128, v32
	v_lshl_add_u64 v[168:169], s[48:49], 0, v[98:99]
	global_store_dword v[168:169], v170, off
	global_load_dword v98, v[110:111], off offset:256
	s_waitcnt vmcnt(0)
	v_mul_f32_e32 v98, 0x3fd744fd, v98
	v_fmac_f32_e32 v98, v112, v133
	global_store_dword v[168:169], v98, off offset:256
	v_or_b32_e32 v98, 27, v132
	v_ashrrev_i32_e32 v99, 31, v98
	v_lshlrev_b64 v[98:99], 10, v[98:99]
	v_lshl_add_u64 v[98:99], v[98:99], 0, v[130:131]
	v_lshlrev_b64 v[98:99], 2, v[98:99]
	v_lshl_add_u64 v[170:171], s[0:1], 0, v[98:99]
	global_load_dword v112, v[170:171], off
	s_waitcnt vmcnt(0)
	v_mul_f32_e32 v112, 0x3fd744fd, v112
	v_fmac_f32_e32 v112, v129, v32
	v_lshl_add_u64 v[128:129], s[48:49], 0, v[98:99]
	global_store_dword v[128:129], v112, off
	global_load_dword v32, v[170:171], off offset:256
	v_or_b32_e32 v98, 32, v130
	v_ashrrev_i32_e32 v99, 31, v98
	v_lshl_add_u64 v[98:99], v[98:99], 2, s[6:7]
	s_waitcnt vmcnt(0)
	v_mul_f32_e32 v32, 0x3fd744fd, v32
	v_fmac_f32_e32 v32, v113, v133
	global_store_dword v[128:129], v32, off offset:256
	global_load_dword v32, v[98:99], off
	s_nop 0
	global_load_dword v112, v[98:99], off offset:256
	global_load_dword v113, v[136:137], off offset:128
	s_waitcnt vmcnt(0)
	v_mul_f32_e32 v113, 0x3fd744fd, v113
	v_fmac_f32_e32 v113, v82, v32
	global_store_dword v[138:139], v113, off offset:128
	global_load_dword v82, v[136:137], off offset:384
	s_waitcnt vmcnt(0)
	v_mul_f32_e32 v82, 0x3fd744fd, v82
	v_fmac_f32_e32 v82, v66, v112
	global_store_dword v[138:139], v82, off offset:384
	global_load_dword v66, v[140:141], off offset:128
	s_waitcnt vmcnt(0)
	v_mul_f32_e32 v66, 0x3fd744fd, v66
	v_fmac_f32_e32 v66, v83, v32
	global_store_dword v[114:115], v66, off offset:128
	global_load_dword v66, v[140:141], off offset:384
	s_waitcnt vmcnt(0)
	v_mul_f32_e32 v66, 0x3fd744fd, v66
	v_fmac_f32_e32 v66, v67, v112
	global_store_dword v[114:115], v66, off offset:384
	global_load_dword v66, v[142:143], off offset:128
	s_waitcnt vmcnt(0)
	v_mul_f32_e32 v66, 0x3fd744fd, v66
	v_fmac_f32_e32 v66, v84, v32
	global_store_dword v[144:145], v66, off offset:128
	global_load_dword v66, v[142:143], off offset:384
	s_waitcnt vmcnt(0)
	v_mul_f32_e32 v66, 0x3fd744fd, v66
	v_fmac_f32_e32 v66, v68, v112
	global_store_dword v[144:145], v66, off offset:384
	global_load_dword v66, v[146:147], off offset:128
	s_waitcnt vmcnt(0)
	v_mul_f32_e32 v66, 0x3fd744fd, v66
	v_fmac_f32_e32 v66, v85, v32
	global_store_dword v[116:117], v66, off offset:128
	global_load_dword v32, v[146:147], off offset:384
	s_waitcnt vmcnt(0)
	v_mul_f32_e32 v32, 0x3fd744fd, v32
	v_fmac_f32_e32 v32, v69, v112
	global_store_dword v[116:117], v32, off offset:384
	global_load_dword v32, v[98:99], off
	s_nop 0
	global_load_dword v66, v[98:99], off offset:256
	global_load_dword v67, v[100:101], off offset:128
	s_waitcnt vmcnt(0)
	v_mul_f32_e32 v67, 0x3fd744fd, v67
	v_fmac_f32_e32 v67, v86, v32
	global_store_dword v[148:149], v67, off offset:128
	global_load_dword v67, v[100:101], off offset:384
	s_waitcnt vmcnt(0)
	v_mul_f32_e32 v67, 0x3fd744fd, v67
	v_fmac_f32_e32 v67, v70, v66
	global_store_dword v[148:149], v67, off offset:384
	global_load_dword v67, v[150:151], off offset:128
	s_waitcnt vmcnt(0)
	v_mul_f32_e32 v67, 0x3fd744fd, v67
	v_fmac_f32_e32 v67, v87, v32
	global_store_dword v[118:119], v67, off offset:128
	global_load_dword v67, v[150:151], off offset:384
	s_waitcnt vmcnt(0)
	v_mul_f32_e32 v67, 0x3fd744fd, v67
	v_fmac_f32_e32 v67, v71, v66
	global_store_dword v[118:119], v67, off offset:384
	global_load_dword v67, v[102:103], off offset:128
	s_waitcnt vmcnt(0)
	v_mul_f32_e32 v67, 0x3fd744fd, v67
	v_fmac_f32_e32 v67, v88, v32
	global_store_dword v[152:153], v67, off offset:128
	global_load_dword v67, v[102:103], off offset:384
	s_waitcnt vmcnt(0)
	v_mul_f32_e32 v67, 0x3fd744fd, v67
	v_fmac_f32_e32 v67, v72, v66
	global_store_dword v[152:153], v67, off offset:384
	global_load_dword v67, v[154:155], off offset:128
	s_waitcnt vmcnt(0)
	v_mul_f32_e32 v67, 0x3fd744fd, v67
	v_fmac_f32_e32 v67, v89, v32
	global_store_dword v[120:121], v67, off offset:128
	global_load_dword v32, v[154:155], off offset:384
	s_waitcnt vmcnt(0)
	v_mul_f32_e32 v32, 0x3fd744fd, v32
	v_fmac_f32_e32 v32, v73, v66
	global_store_dword v[120:121], v32, off offset:384
	global_load_dword v32, v[98:99], off
	s_nop 0
	global_load_dword v66, v[98:99], off offset:256
	global_load_dword v67, v[104:105], off offset:128
	s_waitcnt vmcnt(0)
	v_mul_f32_e32 v67, 0x3fd744fd, v67
	v_fmac_f32_e32 v67, v90, v32
	global_store_dword v[156:157], v67, off offset:128
	global_load_dword v67, v[104:105], off offset:384
	s_waitcnt vmcnt(0)
	v_mul_f32_e32 v67, 0x3fd744fd, v67
	v_fmac_f32_e32 v67, v74, v66
	global_store_dword v[156:157], v67, off offset:384
	global_load_dword v67, v[158:159], off offset:128
	s_waitcnt vmcnt(0)
	v_mul_f32_e32 v67, 0x3fd744fd, v67
	v_fmac_f32_e32 v67, v91, v32
	global_store_dword v[122:123], v67, off offset:128
	global_load_dword v67, v[158:159], off offset:384
	s_waitcnt vmcnt(0)
	v_mul_f32_e32 v67, 0x3fd744fd, v67
	v_fmac_f32_e32 v67, v75, v66
	global_store_dword v[122:123], v67, off offset:384
	global_load_dword v67, v[106:107], off offset:128
	s_waitcnt vmcnt(0)
	v_mul_f32_e32 v67, 0x3fd744fd, v67
	v_fmac_f32_e32 v67, v92, v32
	global_store_dword v[160:161], v67, off offset:128
	global_load_dword v67, v[106:107], off offset:384
	s_waitcnt vmcnt(0)
	v_mul_f32_e32 v67, 0x3fd744fd, v67
	v_fmac_f32_e32 v67, v76, v66
	global_store_dword v[160:161], v67, off offset:384
	global_load_dword v67, v[162:163], off offset:128
	s_waitcnt vmcnt(0)
	v_mul_f32_e32 v67, 0x3fd744fd, v67
	v_fmac_f32_e32 v67, v93, v32
	global_store_dword v[124:125], v67, off offset:128
	global_load_dword v32, v[162:163], off offset:384
	s_waitcnt vmcnt(0)
	v_mul_f32_e32 v32, 0x3fd744fd, v32
	v_fmac_f32_e32 v32, v77, v66
	global_store_dword v[124:125], v32, off offset:384
	global_load_dword v32, v[98:99], off
	s_nop 0
	global_load_dword v66, v[98:99], off offset:256
	global_load_dword v67, v[108:109], off offset:128
	s_waitcnt vmcnt(0)
	v_mul_f32_e32 v67, 0x3fd744fd, v67
	v_fmac_f32_e32 v67, v94, v32
	global_store_dword v[164:165], v67, off offset:128
	global_load_dword v67, v[108:109], off offset:384
	s_waitcnt vmcnt(0)
	v_mul_f32_e32 v67, 0x3fd744fd, v67
	v_fmac_f32_e32 v67, v78, v66
	global_store_dword v[164:165], v67, off offset:384
	global_load_dword v67, v[166:167], off offset:128
	s_waitcnt vmcnt(0)
	v_mul_f32_e32 v67, 0x3fd744fd, v67
	v_fmac_f32_e32 v67, v95, v32
	global_store_dword v[126:127], v67, off offset:128
	global_load_dword v67, v[166:167], off offset:384
	s_waitcnt vmcnt(0)
	v_mul_f32_e32 v67, 0x3fd744fd, v67
	v_fmac_f32_e32 v67, v79, v66
	global_store_dword v[126:127], v67, off offset:384
	global_load_dword v67, v[110:111], off offset:128
	s_waitcnt vmcnt(0)
	v_mul_f32_e32 v67, 0x3fd744fd, v67
	v_fmac_f32_e32 v67, v96, v32
	global_store_dword v[168:169], v67, off offset:128
	global_load_dword v67, v[110:111], off offset:384
	s_waitcnt vmcnt(0)
	v_mul_f32_e32 v67, 0x3fd744fd, v67
	v_fmac_f32_e32 v67, v80, v66
	global_store_dword v[168:169], v67, off offset:384
	global_load_dword v67, v[170:171], off offset:128
	s_waitcnt vmcnt(0)
	v_mul_f32_e32 v67, 0x3fd744fd, v67
	v_fmac_f32_e32 v67, v97, v32
	global_store_dword v[128:129], v67, off offset:128
	global_load_dword v32, v[170:171], off offset:384
	s_waitcnt vmcnt(0)
	v_mul_f32_e32 v32, 0x3fd744fd, v32
	v_fmac_f32_e32 v32, v81, v66
	v_or_b32_e32 v66, 32, v132
	v_ashrrev_i32_e32 v67, 31, v66
	v_lshlrev_b64 v[66:67], 10, v[66:67]
	v_lshl_add_u64 v[66:67], v[66:67], 0, v[130:131]
	v_lshlrev_b64 v[68:69], 2, v[66:67]
	global_store_dword v[128:129], v32, off offset:384
	v_lshl_add_u64 v[66:67], s[0:1], 0, v[68:69]
	global_load_dword v32, v[134:135], off
	global_load_dword v78, v[134:135], off offset:256
	global_load_dword v70, v[66:67], off
	v_lshl_add_u64 v[68:69], s[48:49], 0, v[68:69]
	s_waitcnt vmcnt(0)
	v_mul_f32_e32 v70, 0x3fd744fd, v70
	v_fmac_f32_e32 v70, v50, v32
	global_store_dword v[68:69], v70, off
	global_load_dword v50, v[66:67], off offset:256
	v_or_b32_e32 v70, 33, v132
	v_ashrrev_i32_e32 v71, 31, v70
	v_lshlrev_b64 v[70:71], 10, v[70:71]
	v_lshl_add_u64 v[70:71], v[70:71], 0, v[130:131]
	v_lshlrev_b64 v[72:73], 2, v[70:71]
	v_lshl_add_u64 v[70:71], s[0:1], 0, v[72:73]
	s_waitcnt vmcnt(0)
	v_mul_f32_e32 v50, 0x3fd744fd, v50
	v_fmac_f32_e32 v50, v34, v78
	global_store_dword v[68:69], v50, off offset:256
	global_load_dword v34, v[70:71], off
	s_waitcnt vmcnt(0)
	v_mul_f32_e32 v34, 0x3fd744fd, v34
	v_fmac_f32_e32 v34, v51, v32
	v_lshl_add_u64 v[50:51], s[48:49], 0, v[72:73]
	global_store_dword v[50:51], v34, off
	global_load_dword v34, v[70:71], off offset:256
	s_waitcnt vmcnt(0)
	v_mul_f32_e32 v34, 0x3fd744fd, v34
	v_fmac_f32_e32 v34, v35, v78
	global_store_dword v[50:51], v34, off offset:256
	v_or_b32_e32 v34, 34, v132
	v_ashrrev_i32_e32 v35, 31, v34
	v_lshlrev_b64 v[34:35], 10, v[34:35]
	v_lshl_add_u64 v[34:35], v[34:35], 0, v[130:131]
	v_lshlrev_b64 v[72:73], 2, v[34:35]
	v_lshl_add_u64 v[34:35], s[0:1], 0, v[72:73]
	global_load_dword v74, v[34:35], off
	v_lshl_add_u64 v[72:73], s[48:49], 0, v[72:73]
	s_waitcnt vmcnt(0)
	v_mul_f32_e32 v74, 0x3fd744fd, v74
	v_fmac_f32_e32 v74, v52, v32
	global_store_dword v[72:73], v74, off
	global_load_dword v52, v[34:35], off offset:256
	v_or_b32_e32 v74, 35, v132
	v_ashrrev_i32_e32 v75, 31, v74
	v_lshlrev_b64 v[74:75], 10, v[74:75]
	v_lshl_add_u64 v[74:75], v[74:75], 0, v[130:131]
	v_lshlrev_b64 v[76:77], 2, v[74:75]
	v_lshl_add_u64 v[74:75], s[0:1], 0, v[76:77]
	s_waitcnt vmcnt(0)
	v_mul_f32_e32 v52, 0x3fd744fd, v52
	v_fmac_f32_e32 v52, v36, v78
	global_store_dword v[72:73], v52, off offset:256
	global_load_dword v36, v[74:75], off
	s_waitcnt vmcnt(0)
	v_mul_f32_e32 v36, 0x3fd744fd, v36
	v_fmac_f32_e32 v36, v53, v32
	v_lshl_add_u64 v[52:53], s[48:49], 0, v[76:77]
	global_store_dword v[52:53], v36, off
	global_load_dword v32, v[74:75], off offset:256
	v_or_b32_e32 v36, 40, v132
	s_waitcnt vmcnt(0)
	v_mul_f32_e32 v32, 0x3fd744fd, v32
	v_fmac_f32_e32 v32, v37, v78
	v_ashrrev_i32_e32 v37, 31, v36
	v_lshlrev_b64 v[36:37], 10, v[36:37]
	v_lshl_add_u64 v[36:37], v[36:37], 0, v[130:131]
	v_lshlrev_b64 v[76:77], 2, v[36:37]
	global_store_dword v[52:53], v32, off offset:256
	v_lshl_add_u64 v[36:37], s[0:1], 0, v[76:77]
	global_load_dword v32, v[134:135], off
	global_load_dword v86, v[134:135], off offset:256
	global_load_dword v78, v[36:37], off
	v_lshl_add_u64 v[76:77], s[48:49], 0, v[76:77]
	s_waitcnt vmcnt(0)
	v_mul_f32_e32 v78, 0x3fd744fd, v78
	v_fmac_f32_e32 v78, v54, v32
	global_store_dword v[76:77], v78, off
	global_load_dword v54, v[36:37], off offset:256
	v_or_b32_e32 v78, 41, v132
	v_ashrrev_i32_e32 v79, 31, v78
	v_lshlrev_b64 v[78:79], 10, v[78:79]
	v_lshl_add_u64 v[78:79], v[78:79], 0, v[130:131]
	v_lshlrev_b64 v[80:81], 2, v[78:79]
	v_lshl_add_u64 v[78:79], s[0:1], 0, v[80:81]
	s_waitcnt vmcnt(0)
	v_mul_f32_e32 v54, 0x3fd744fd, v54
	v_fmac_f32_e32 v54, v38, v86
	global_store_dword v[76:77], v54, off offset:256
	global_load_dword v38, v[78:79], off
	s_waitcnt vmcnt(0)
	v_mul_f32_e32 v38, 0x3fd744fd, v38
	v_fmac_f32_e32 v38, v55, v32
	v_lshl_add_u64 v[54:55], s[48:49], 0, v[80:81]
	global_store_dword v[54:55], v38, off
	global_load_dword v38, v[78:79], off offset:256
	s_waitcnt vmcnt(0)
	v_mul_f32_e32 v38, 0x3fd744fd, v38
	v_fmac_f32_e32 v38, v39, v86
	global_store_dword v[54:55], v38, off offset:256
	v_or_b32_e32 v38, 42, v132
	v_ashrrev_i32_e32 v39, 31, v38
	v_lshlrev_b64 v[38:39], 10, v[38:39]
	v_lshl_add_u64 v[38:39], v[38:39], 0, v[130:131]
	v_lshlrev_b64 v[80:81], 2, v[38:39]
	v_lshl_add_u64 v[38:39], s[0:1], 0, v[80:81]
	global_load_dword v82, v[38:39], off
	v_lshl_add_u64 v[80:81], s[48:49], 0, v[80:81]
	s_waitcnt vmcnt(0)
	v_mul_f32_e32 v82, 0x3fd744fd, v82
	v_fmac_f32_e32 v82, v56, v32
	global_store_dword v[80:81], v82, off
	global_load_dword v56, v[38:39], off offset:256
	v_or_b32_e32 v82, 43, v132
	v_ashrrev_i32_e32 v83, 31, v82
	v_lshlrev_b64 v[82:83], 10, v[82:83]
	v_lshl_add_u64 v[82:83], v[82:83], 0, v[130:131]
	v_lshlrev_b64 v[84:85], 2, v[82:83]
	v_lshl_add_u64 v[82:83], s[0:1], 0, v[84:85]
	s_waitcnt vmcnt(0)
	v_mul_f32_e32 v56, 0x3fd744fd, v56
	v_fmac_f32_e32 v56, v40, v86
	global_store_dword v[80:81], v56, off offset:256
	global_load_dword v40, v[82:83], off
	s_waitcnt vmcnt(0)
	v_mul_f32_e32 v40, 0x3fd744fd, v40
	v_fmac_f32_e32 v40, v57, v32
	v_lshl_add_u64 v[56:57], s[48:49], 0, v[84:85]
	global_store_dword v[56:57], v40, off
	global_load_dword v32, v[82:83], off offset:256
	v_or_b32_e32 v40, 48, v132
	s_waitcnt vmcnt(0)
	v_mul_f32_e32 v32, 0x3fd744fd, v32
	v_fmac_f32_e32 v32, v41, v86
	v_ashrrev_i32_e32 v41, 31, v40
	v_lshlrev_b64 v[40:41], 10, v[40:41]
	v_lshl_add_u64 v[40:41], v[40:41], 0, v[130:131]
	v_lshlrev_b64 v[84:85], 2, v[40:41]
	global_store_dword v[56:57], v32, off offset:256
	v_lshl_add_u64 v[40:41], s[0:1], 0, v[84:85]
	global_load_dword v32, v[134:135], off
	global_load_dword v94, v[134:135], off offset:256
	global_load_dword v86, v[40:41], off
	v_lshl_add_u64 v[84:85], s[48:49], 0, v[84:85]
	s_waitcnt vmcnt(0)
	v_mul_f32_e32 v86, 0x3fd744fd, v86
	v_fmac_f32_e32 v86, v58, v32
	global_store_dword v[84:85], v86, off
	global_load_dword v58, v[40:41], off offset:256
	v_or_b32_e32 v86, 49, v132
	v_ashrrev_i32_e32 v87, 31, v86
	v_lshlrev_b64 v[86:87], 10, v[86:87]
	v_lshl_add_u64 v[86:87], v[86:87], 0, v[130:131]
	v_lshlrev_b64 v[88:89], 2, v[86:87]
	v_lshl_add_u64 v[86:87], s[0:1], 0, v[88:89]
	s_waitcnt vmcnt(0)
	v_mul_f32_e32 v58, 0x3fd744fd, v58
	v_fmac_f32_e32 v58, v42, v94
	global_store_dword v[84:85], v58, off offset:256
	global_load_dword v42, v[86:87], off
	s_waitcnt vmcnt(0)
	v_mul_f32_e32 v42, 0x3fd744fd, v42
	v_fmac_f32_e32 v42, v59, v32
	v_lshl_add_u64 v[58:59], s[48:49], 0, v[88:89]
	global_store_dword v[58:59], v42, off
	global_load_dword v42, v[86:87], off offset:256
	s_waitcnt vmcnt(0)
	v_mul_f32_e32 v42, 0x3fd744fd, v42
	v_fmac_f32_e32 v42, v43, v94
	global_store_dword v[58:59], v42, off offset:256
	v_or_b32_e32 v42, 50, v132
	v_ashrrev_i32_e32 v43, 31, v42
	v_lshlrev_b64 v[42:43], 10, v[42:43]
	v_lshl_add_u64 v[42:43], v[42:43], 0, v[130:131]
	v_lshlrev_b64 v[88:89], 2, v[42:43]
	v_lshl_add_u64 v[42:43], s[0:1], 0, v[88:89]
	global_load_dword v90, v[42:43], off
	v_lshl_add_u64 v[88:89], s[48:49], 0, v[88:89]
	s_waitcnt vmcnt(0)
	v_mul_f32_e32 v90, 0x3fd744fd, v90
	v_fmac_f32_e32 v90, v60, v32
	global_store_dword v[88:89], v90, off
	global_load_dword v60, v[42:43], off offset:256
	v_or_b32_e32 v90, 51, v132
	v_ashrrev_i32_e32 v91, 31, v90
	v_lshlrev_b64 v[90:91], 10, v[90:91]
	v_lshl_add_u64 v[90:91], v[90:91], 0, v[130:131]
	v_lshlrev_b64 v[92:93], 2, v[90:91]
	v_lshl_add_u64 v[90:91], s[0:1], 0, v[92:93]
	s_waitcnt vmcnt(0)
	v_mul_f32_e32 v60, 0x3fd744fd, v60
	v_fmac_f32_e32 v60, v44, v94
	global_store_dword v[88:89], v60, off offset:256
	global_load_dword v44, v[90:91], off
	s_waitcnt vmcnt(0)
	v_mul_f32_e32 v44, 0x3fd744fd, v44
	v_fmac_f32_e32 v44, v61, v32
	v_lshl_add_u64 v[60:61], s[48:49], 0, v[92:93]
	global_store_dword v[60:61], v44, off
	global_load_dword v32, v[90:91], off offset:256
	v_or_b32_e32 v44, 56, v132
	s_waitcnt vmcnt(0)
	v_mul_f32_e32 v32, 0x3fd744fd, v32
	v_fmac_f32_e32 v32, v45, v94
	v_ashrrev_i32_e32 v45, 31, v44
	v_lshlrev_b64 v[44:45], 10, v[44:45]
	v_lshl_add_u64 v[44:45], v[44:45], 0, v[130:131]
	v_lshlrev_b64 v[92:93], 2, v[44:45]
	global_store_dword v[60:61], v32, off offset:256
	v_lshl_add_u64 v[44:45], s[0:1], 0, v[92:93]
	global_load_dword v32, v[134:135], off
	global_load_dword v104, v[134:135], off offset:256
	global_load_dword v94, v[44:45], off
	v_lshl_add_u64 v[92:93], s[48:49], 0, v[92:93]
	s_waitcnt vmcnt(0)
	v_mul_f32_e32 v94, 0x3fd744fd, v94
	v_fmac_f32_e32 v94, v62, v32
	global_store_dword v[92:93], v94, off
	global_load_dword v62, v[44:45], off offset:256
	v_or_b32_e32 v94, 57, v132
	v_ashrrev_i32_e32 v95, 31, v94
	v_lshlrev_b64 v[94:95], 10, v[94:95]
	v_lshl_add_u64 v[94:95], v[94:95], 0, v[130:131]
	v_lshlrev_b64 v[96:97], 2, v[94:95]
	v_lshl_add_u64 v[94:95], s[0:1], 0, v[96:97]
	s_waitcnt vmcnt(0)
	v_mul_f32_e32 v62, 0x3fd744fd, v62
	v_fmac_f32_e32 v62, v46, v104
	global_store_dword v[92:93], v62, off offset:256
	global_load_dword v46, v[94:95], off
	s_waitcnt vmcnt(0)
	v_mul_f32_e32 v46, 0x3fd744fd, v46
	v_fmac_f32_e32 v46, v63, v32
	v_lshl_add_u64 v[62:63], s[48:49], 0, v[96:97]
	global_store_dword v[62:63], v46, off
	global_load_dword v46, v[94:95], off offset:256
	s_waitcnt vmcnt(0)
	v_mul_f32_e32 v46, 0x3fd744fd, v46
	v_fmac_f32_e32 v46, v47, v104
	global_store_dword v[62:63], v46, off offset:256
	v_or_b32_e32 v46, 58, v132
	v_ashrrev_i32_e32 v47, 31, v46
	v_lshlrev_b64 v[46:47], 10, v[46:47]
	v_lshl_add_u64 v[46:47], v[46:47], 0, v[130:131]
	v_lshlrev_b64 v[96:97], 2, v[46:47]
	v_lshl_add_u64 v[46:47], s[0:1], 0, v[96:97]
	global_load_dword v100, v[46:47], off
	v_lshl_add_u64 v[96:97], s[48:49], 0, v[96:97]
	s_waitcnt vmcnt(0)
	v_mul_f32_e32 v100, 0x3fd744fd, v100
	v_fmac_f32_e32 v100, v64, v32
	global_store_dword v[96:97], v100, off
	global_load_dword v64, v[46:47], off offset:256
	v_or_b32_e32 v100, 59, v132
	v_ashrrev_i32_e32 v101, 31, v100
	v_lshlrev_b64 v[100:101], 10, v[100:101]
	v_lshl_add_u64 v[100:101], v[100:101], 0, v[130:131]
	v_lshlrev_b64 v[100:101], 2, v[100:101]
	v_lshl_add_u64 v[102:103], s[0:1], 0, v[100:101]
	s_waitcnt vmcnt(0)
	v_mul_f32_e32 v64, 0x3fd744fd, v64
	v_fmac_f32_e32 v64, v48, v104
	global_store_dword v[96:97], v64, off offset:256
	global_load_dword v48, v[102:103], off
	s_waitcnt vmcnt(0)
	v_mul_f32_e32 v48, 0x3fd744fd, v48
	v_fmac_f32_e32 v48, v65, v32
	v_lshl_add_u64 v[64:65], s[48:49], 0, v[100:101]
	global_store_dword v[64:65], v48, off
	global_load_dword v32, v[102:103], off offset:256
	s_waitcnt vmcnt(0)
	v_mul_f32_e32 v32, 0x3fd744fd, v32
	v_fmac_f32_e32 v32, v49, v104
	global_store_dword v[64:65], v32, off offset:256
	global_load_dword v32, v[98:99], off
	s_nop 0
	global_load_dword v48, v[98:99], off offset:256
	global_load_dword v49, v[66:67], off offset:128
	s_waitcnt vmcnt(0)
	v_mul_f32_e32 v49, 0x3fd744fd, v49
	v_fmac_f32_e32 v49, v16, v32
	global_store_dword v[68:69], v49, off offset:128
	global_load_dword v16, v[66:67], off offset:384
	s_waitcnt vmcnt(0)
	v_mul_f32_e32 v16, 0x3fd744fd, v16
	v_fmac_f32_e32 v16, v0, v48
	global_store_dword v[68:69], v16, off offset:384
	global_load_dword v0, v[70:71], off offset:128
	s_waitcnt vmcnt(0)
	v_mul_f32_e32 v0, 0x3fd744fd, v0
	v_fmac_f32_e32 v0, v17, v32
	global_store_dword v[50:51], v0, off offset:128
	global_load_dword v0, v[70:71], off offset:384
	s_waitcnt vmcnt(0)
	v_mul_f32_e32 v0, 0x3fd744fd, v0
	v_fmac_f32_e32 v0, v1, v48
	global_store_dword v[50:51], v0, off offset:384
	global_load_dword v0, v[34:35], off offset:128
	s_waitcnt vmcnt(0)
	v_mul_f32_e32 v0, 0x3fd744fd, v0
	v_fmac_f32_e32 v0, v18, v32
	global_store_dword v[72:73], v0, off offset:128
	global_load_dword v0, v[34:35], off offset:384
	s_waitcnt vmcnt(0)
	v_mul_f32_e32 v0, 0x3fd744fd, v0
	v_fmac_f32_e32 v0, v2, v48
	global_store_dword v[72:73], v0, off offset:384
	global_load_dword v0, v[74:75], off offset:128
	s_waitcnt vmcnt(0)
	v_mul_f32_e32 v0, 0x3fd744fd, v0
	v_fmac_f32_e32 v0, v19, v32
	global_store_dword v[52:53], v0, off offset:128
	global_load_dword v0, v[74:75], off offset:384
	s_waitcnt vmcnt(0)
	v_mul_f32_e32 v0, 0x3fd744fd, v0
	v_fmac_f32_e32 v0, v3, v48
	global_store_dword v[52:53], v0, off offset:384
	global_load_dword v0, v[98:99], off
	s_nop 0
	global_load_dword v1, v[98:99], off offset:256
	global_load_dword v2, v[36:37], off offset:128
	s_waitcnt vmcnt(0)
	v_mul_f32_e32 v2, 0x3fd744fd, v2
	v_fmac_f32_e32 v2, v20, v0
	global_store_dword v[76:77], v2, off offset:128
	global_load_dword v2, v[36:37], off offset:384
	s_waitcnt vmcnt(0)
	v_mul_f32_e32 v2, 0x3fd744fd, v2
	v_fmac_f32_e32 v2, v4, v1
	global_store_dword v[76:77], v2, off offset:384
	global_load_dword v2, v[78:79], off offset:128
	s_waitcnt vmcnt(0)
	v_mul_f32_e32 v2, 0x3fd744fd, v2
	v_fmac_f32_e32 v2, v21, v0
	global_store_dword v[54:55], v2, off offset:128
	global_load_dword v2, v[78:79], off offset:384
	s_waitcnt vmcnt(0)
	v_mul_f32_e32 v2, 0x3fd744fd, v2
	v_fmac_f32_e32 v2, v5, v1
	global_store_dword v[54:55], v2, off offset:384
	global_load_dword v2, v[38:39], off offset:128
	s_waitcnt vmcnt(0)
	v_mul_f32_e32 v2, 0x3fd744fd, v2
	v_fmac_f32_e32 v2, v22, v0
	global_store_dword v[80:81], v2, off offset:128
	global_load_dword v2, v[38:39], off offset:384
	s_waitcnt vmcnt(0)
	v_mul_f32_e32 v2, 0x3fd744fd, v2
	v_fmac_f32_e32 v2, v6, v1
	global_store_dword v[80:81], v2, off offset:384
	global_load_dword v2, v[82:83], off offset:128
	s_waitcnt vmcnt(0)
	v_mul_f32_e32 v2, 0x3fd744fd, v2
	v_fmac_f32_e32 v2, v23, v0
	global_store_dword v[56:57], v2, off offset:128
	global_load_dword v0, v[82:83], off offset:384
	s_waitcnt vmcnt(0)
	v_mul_f32_e32 v0, 0x3fd744fd, v0
	v_fmac_f32_e32 v0, v7, v1
	global_store_dword v[56:57], v0, off offset:384
	global_load_dword v0, v[98:99], off
	s_nop 0
	global_load_dword v1, v[98:99], off offset:256
	global_load_dword v2, v[40:41], off offset:128
	s_waitcnt vmcnt(0)
	v_mul_f32_e32 v2, 0x3fd744fd, v2
	v_fmac_f32_e32 v2, v24, v0
	global_store_dword v[84:85], v2, off offset:128
	global_load_dword v2, v[40:41], off offset:384
	s_waitcnt vmcnt(0)
	v_mul_f32_e32 v2, 0x3fd744fd, v2
	v_fmac_f32_e32 v2, v8, v1
	global_store_dword v[84:85], v2, off offset:384
	global_load_dword v2, v[86:87], off offset:128
	s_waitcnt vmcnt(0)
	v_mul_f32_e32 v2, 0x3fd744fd, v2
	v_fmac_f32_e32 v2, v25, v0
	global_store_dword v[58:59], v2, off offset:128
	global_load_dword v2, v[86:87], off offset:384
	s_waitcnt vmcnt(0)
	v_mul_f32_e32 v2, 0x3fd744fd, v2
	v_fmac_f32_e32 v2, v9, v1
	global_store_dword v[58:59], v2, off offset:384
	global_load_dword v2, v[42:43], off offset:128
	s_waitcnt vmcnt(0)
	v_mul_f32_e32 v2, 0x3fd744fd, v2
	v_fmac_f32_e32 v2, v26, v0
	global_store_dword v[88:89], v2, off offset:128
	global_load_dword v2, v[42:43], off offset:384
	s_waitcnt vmcnt(0)
	v_mul_f32_e32 v2, 0x3fd744fd, v2
	v_fmac_f32_e32 v2, v10, v1
	global_store_dword v[88:89], v2, off offset:384
	global_load_dword v2, v[90:91], off offset:128
	s_waitcnt vmcnt(0)
	v_mul_f32_e32 v2, 0x3fd744fd, v2
	v_fmac_f32_e32 v2, v27, v0
	global_store_dword v[60:61], v2, off offset:128
	global_load_dword v0, v[90:91], off offset:384
	s_waitcnt vmcnt(0)
	v_mul_f32_e32 v0, 0x3fd744fd, v0
	v_fmac_f32_e32 v0, v11, v1
	global_store_dword v[60:61], v0, off offset:384
	global_load_dword v0, v[98:99], off
	s_nop 0
	global_load_dword v1, v[98:99], off offset:256
	global_load_dword v2, v[44:45], off offset:128
	s_waitcnt vmcnt(0)
	v_mul_f32_e32 v2, 0x3fd744fd, v2
	v_fmac_f32_e32 v2, v28, v0
	global_store_dword v[92:93], v2, off offset:128
	global_load_dword v2, v[44:45], off offset:384
	s_waitcnt vmcnt(0)
	v_mul_f32_e32 v2, 0x3fd744fd, v2
	v_fmac_f32_e32 v2, v12, v1
	global_store_dword v[92:93], v2, off offset:384
	global_load_dword v2, v[94:95], off offset:128
	s_waitcnt vmcnt(0)
	v_mul_f32_e32 v2, 0x3fd744fd, v2
	v_fmac_f32_e32 v2, v29, v0
	global_store_dword v[62:63], v2, off offset:128
	global_load_dword v2, v[94:95], off offset:384
	s_waitcnt vmcnt(0)
	v_mul_f32_e32 v2, 0x3fd744fd, v2
	v_fmac_f32_e32 v2, v13, v1
	global_store_dword v[62:63], v2, off offset:384
	global_load_dword v2, v[46:47], off offset:128
	s_waitcnt vmcnt(0)
	v_mul_f32_e32 v2, 0x3fd744fd, v2
	v_fmac_f32_e32 v2, v30, v0
	global_store_dword v[96:97], v2, off offset:128
	global_load_dword v2, v[46:47], off offset:384
	s_waitcnt vmcnt(0)
	v_mul_f32_e32 v2, 0x3fd744fd, v2
	v_fmac_f32_e32 v2, v14, v1
	global_store_dword v[96:97], v2, off offset:384
	global_load_dword v2, v[102:103], off offset:128
	s_waitcnt vmcnt(0)
	v_mul_f32_e32 v2, 0x3fd744fd, v2
	v_fmac_f32_e32 v2, v31, v0
	global_store_dword v[64:65], v2, off offset:128
	global_load_dword v0, v[102:103], off offset:384
	s_waitcnt vmcnt(0)
	v_mul_f32_e32 v0, 0x3fd744fd, v0
	v_fmac_f32_e32 v0, v15, v1
	global_store_dword v[64:65], v0, off offset:384
	s_cbranch_scc1 .LBB0_1692
